# K-loops: delete the back-to-back s_setprio 0 / s_setprio 1 pair between the two 16-MFMA halves of every 32-MFMA block (2 SALU issue slots inside the MFMA stream, 32 sites)
# baseline (speedup 1.0000x reference)
; #define PG8_STAGE(bufoff, gbase, voff) do { _Pragma("unroll") for (int _i = 0; _i < 2; ++_i) \
;         __builtin_amdgcn_global_load_lds((const unsigned*)((const char*)(gbase) + (voff)[_i]), (LAS unsigned*)(lds + (bufoff) + ldsw + _i * 8192), 16, 0, 0); } while (0)
; #define PG8_LDA(dst, b, h) do { _Pragma("unroll") for (int m = 0; m < 4; ++m) _Pragma("unroll") for (int k = 0; k < 2; ++k) dst[m][k] = *(const LAS bf16x8*)(lds + PG8_SA(b, h) + aoff + m * 2048 + k * 1024); } while (0)
; #define PG8_LDB(dst, b, h) do { _Pragma("unroll") for (int n = 0; n < 2; ++n) _Pragma("unroll") for (int k = 0; k < 2; ++k) dst[n][k] = *(const LAS bf16x8*)(lds + PG8_SB(b, h) + boff + n * 2048 + k * 1024); } while (0)
; #define PG8_MMA(ai, bj, At, Bt) do { __builtin_amdgcn_s_setprio(1); _Pragma("unroll") for (int m = 0; m < 4; ++m) _Pragma("unroll") for (int n = 0; n < 2; ++n) _Pragma("unroll") for (int k = 0; k < 2; ++k) \
;         acc[ai][bj][m][n] = __builtin_amdgcn_mfma_f32_16x16x32_bf16(Bt[n][k], At[m][k], acc[ai][bj][m][n], 0, 0, 0); __builtin_amdgcn_s_setprio(0); } while (0)
; #define PG8_WAIT_V(n) asm volatile("s_waitcnt vmcnt(" #n ")" ::: "memory")
; #define PG8_WAIT_L(n) asm volatile("s_waitcnt lgkmcnt(" #n ")" ::: "memory")
; #define PG8_BAR __builtin_amdgcn_s_barrier()
; #define PG8_SCHED __builtin_amdgcn_sched_barrier(0)
; template <class Epi>
; __device__ __forceinline__ void gemm_phase(LAS unsigned char* lds, const GemmD g, const Epi& E, int G, int c) {
;     ...
;         for (int t = 0; t < nt; t += 2) {
;             const bool last = (t == nt - 2);
;             const char* a1 = cA + (size_t)(t + 1) * kstep;
;             const char* a2 = last ? nA : cA + (size_t)(t + 2) * kstep; const char* b2 = last ? nB : cB + (size_t)(t + 2) * kstep;
;             const char* a3 = a2 + kstep; const char* b3 = b2 + kstep;
;             PG8_LDB(B0, 0, 0); PG8_LDB(B1, 0, 1); PG8_SCHED; PG8_LDA(At, 0, 0); PG8_STAGE(PG8_SA(1, 1), a1 + hstepA, voffA);
;             PG8_WAIT_V(8); PG8_WAIT_L(0); PG8_BAR; PG8_MMA(0, 0, At, B0); PG8_MMA(0, 1, At, B1); PG8_BAR; PG8_SCHED;
;             PG8_LDA(At, 0, 1); PG8_STAGE(PG8_SB(0, 0), b2, voffB); PG8_STAGE(PG8_SB(0, 1), b2 + hstepB, voffB); PG8_STAGE(PG8_SA(0, 0), a2, voffA);
;             PG8_WAIT_V(8); PG8_WAIT_L(0); PG8_BAR; PG8_MMA(1, 0, At, B0); PG8_MMA(1, 1, At, B1); PG8_BAR; PG8_SCHED;
.LBB0_106:
	s_add_u32 s88, s46, 0x100
	s_addc_u32 s89, s47, 0
	s_add_i32 s31, 0, 0x10000
	s_cmpk_eq_i32 s30, 0x54
	s_cselect_b32 s5, s85, s89
	s_cselect_b32 s4, s84, s88
	v_add_u32_e32 v153, s31, v149
	s_cselect_b32 s91, s87, s29
	s_cselect_b32 s90, s86, s28
	s_add_i32 s33, 0, 0x14000
	ds_read_b128 v[140:143], v153
	ds_read_b128 v[144:147], v153 offset:1024
	ds_read_b128 v[154:157], v153 offset:2048
	ds_read_b128 v[158:161], v153 offset:3072
	v_add_u32_e32 v153, s33, v149
	ds_read_b128 v[162:165], v153
	ds_read_b128 v[166:169], v153 offset:1024
	ds_read_b128 v[170:173], v153 offset:2048
	ds_read_b128 v[180:183], v153 offset:3072
	v_lshl_add_u64 v[174:175], s[46:47], 0, v[136:137]
	s_add_i32 m0, s6, 0xc000
	ds_read_b128 v[184:187], v151
	ds_read_b128 v[188:191], v151 offset:1024
	ds_read_b128 v[192:195], v151 offset:2048
	ds_read_b128 v[210:213], v151 offset:3072
	ds_read_b128 v[214:217], v151 offset:4096
	ds_read_b128 v[218:221], v151 offset:5120
	ds_read_b128 v[222:225], v151 offset:6144
	ds_read_b128 v[226:229], v151 offset:7168
	global_load_lds_dwordx4 v[174:175], off
	v_lshl_add_u64 v[174:175], s[46:47], 0, v[138:139]
	s_add_i32 m0, s6, 0xe000
	s_nop 0
	global_load_lds_dwordx4 v[174:175], off
	s_waitcnt vmcnt(8)
	s_waitcnt lgkmcnt(0)
	s_barrier
	s_setprio 1
	s_waitcnt lgkmcnt(0)
	v_mfma_f32_16x16x32_bf16 v[124:127], v[140:143], v[184:187], v[124:127]
	v_mfma_f32_16x16x32_bf16 v[116:119], v[154:157], v[184:187], v[116:119]
	v_mfma_f32_16x16x32_bf16 v[104:107], v[140:143], v[192:195], v[104:107]
	v_mfma_f32_16x16x32_bf16 v[96:99], v[154:157], v[192:195], v[96:99]
	v_mfma_f32_16x16x32_bf16 v[88:91], v[140:143], v[214:217], v[88:91]
	v_mfma_f32_16x16x32_bf16 v[80:83], v[154:157], v[214:217], v[80:83]
	v_mfma_f32_16x16x32_bf16 v[72:75], v[140:143], v[222:225], v[72:75]
	v_mfma_f32_16x16x32_bf16 v[64:67], v[154:157], v[222:225], v[64:67]
	v_mfma_f32_16x16x32_bf16 v[124:127], v[144:147], v[188:191], v[124:127]
	v_mfma_f32_16x16x32_bf16 v[116:119], v[158:161], v[188:191], v[116:119]
	v_mfma_f32_16x16x32_bf16 v[104:107], v[144:147], v[210:213], v[104:107]
	v_mfma_f32_16x16x32_bf16 v[96:99], v[158:161], v[210:213], v[96:99]
	v_mfma_f32_16x16x32_bf16 v[88:91], v[144:147], v[218:221], v[88:91]
	v_mfma_f32_16x16x32_bf16 v[80:83], v[158:161], v[218:221], v[80:83]
	v_mfma_f32_16x16x32_bf16 v[72:75], v[144:147], v[226:229], v[72:75]
	v_mfma_f32_16x16x32_bf16 v[64:67], v[158:161], v[226:229], v[64:67]
	v_mfma_f32_16x16x32_bf16 v[120:123], v[162:165], v[184:187], v[120:123]
	v_mfma_f32_16x16x32_bf16 v[112:115], v[170:173], v[184:187], v[112:115]
	v_mfma_f32_16x16x32_bf16 v[108:111], v[162:165], v[192:195], v[108:111]
	v_mfma_f32_16x16x32_bf16 v[100:103], v[170:173], v[192:195], v[100:103]
	v_mfma_f32_16x16x32_bf16 v[92:95], v[162:165], v[214:217], v[92:95]
	v_mfma_f32_16x16x32_bf16 v[84:87], v[170:173], v[214:217], v[84:87]
	v_mfma_f32_16x16x32_bf16 v[76:79], v[162:165], v[222:225], v[76:79]
	v_mfma_f32_16x16x32_bf16 v[68:71], v[170:173], v[222:225], v[68:71]
	v_mfma_f32_16x16x32_bf16 v[120:123], v[166:169], v[188:191], v[120:123]
	v_mfma_f32_16x16x32_bf16 v[112:115], v[180:183], v[188:191], v[112:115]
	v_mfma_f32_16x16x32_bf16 v[108:111], v[166:169], v[210:213], v[108:111]
	v_mfma_f32_16x16x32_bf16 v[100:103], v[180:183], v[210:213], v[100:103]
	v_mfma_f32_16x16x32_bf16 v[92:95], v[166:169], v[218:221], v[92:95]
	v_mfma_f32_16x16x32_bf16 v[84:87], v[180:183], v[218:221], v[84:87]
	v_mfma_f32_16x16x32_bf16 v[76:79], v[166:169], v[226:229], v[76:79]
	v_mfma_f32_16x16x32_bf16 v[68:71], v[180:183], v[226:229], v[68:71]
	s_setprio 0
	s_barrier
	s_add_i32 s31, s31, s2
	v_lshl_add_u64 v[174:175], s[90:91], 0, v[178:179]
	s_mov_b32 m0, s31
	ds_read_b128 v[184:187], v151 offset:16384
	ds_read_b128 v[188:191], v151 offset:17408
	ds_read_b128 v[192:195], v151 offset:18432
	ds_read_b128 v[210:213], v151 offset:19456
	ds_read_b128 v[214:217], v151 offset:20480
	ds_read_b128 v[218:221], v151 offset:21504
	ds_read_b128 v[222:225], v151 offset:22528
	ds_read_b128 v[226:229], v151 offset:23552
	global_load_lds_dwordx4 v[174:175], off
	s_add_i32 m0, s31, 0x2000
	s_add_u32 s38, s90, 0x160000
	v_lshl_add_u64 v[198:199], s[90:91], 0, v[128:129]
	s_addc_u32 s39, s91, 0
	s_add_i32 s31, s33, s2
	global_load_lds_dwordx4 v[198:199], off
	v_lshl_add_u64 v[230:231], s[38:39], 0, v[178:179]
	s_mov_b32 m0, s31
	v_lshl_add_u64 v[232:233], s[4:5], 0, v[130:131]
	global_load_lds_dwordx4 v[230:231], off
	v_lshl_add_u64 v[230:231], s[38:39], 0, v[128:129]
	s_add_i32 m0, s31, 0x2000
	s_nop 0
	global_load_lds_dwordx4 v[230:231], off
	v_lshl_add_u64 v[230:231], s[4:5], 0, v[132:133]
	s_mov_b32 m0, s6
	s_nop 0
	global_load_lds_dwordx4 v[230:231], off
	s_mov_b32 m0, s9
	s_nop 0
	global_load_lds_dwordx4 v[232:233], off
	s_waitcnt vmcnt(8)
	s_waitcnt lgkmcnt(0)
	s_barrier
; #define PG8_STAGE(bufoff, gbase, voff) do { _Pragma("unroll") for (int _i = 0; _i < 2; ++_i) \
;         __builtin_amdgcn_global_load_lds((const unsigned*)((const char*)(gbase) + (voff)[_i]), (LAS unsigned*)(lds + (bufoff) + ldsw + _i * 8192), 16, 0, 0); } while (0)
; #define PG8_LDA(dst, b, h) do { _Pragma("unroll") for (int m = 0; m < 4; ++m) _Pragma("unroll") for (int k = 0; k < 2; ++k) dst[m][k] = *(const LAS bf16x8*)(lds + PG8_SA(b, h) + aoff + m * 2048 + k * 1024); } while (0)
; #define PG8_LDB(dst, b, h) do { _Pragma("unroll") for (int n = 0; n < 2; ++n) _Pragma("unroll") for (int k = 0; k < 2; ++k) dst[n][k] = *(const LAS bf16x8*)(lds + PG8_SB(b, h) + boff + n * 2048 + k * 1024); } while (0)
; #define PG8_MMA(ai, bj, At, Bt) do { __builtin_amdgcn_s_setprio(1); _Pragma("unroll") for (int m = 0; m < 4; ++m) _Pragma("unroll") for (int n = 0; n < 2; ++n) _Pragma("unroll") for (int k = 0; k < 2; ++k) \
;         acc[ai][bj][m][n] = __builtin_amdgcn_mfma_f32_16x16x32_bf16(Bt[n][k], At[m][k], acc[ai][bj][m][n], 0, 0, 0); __builtin_amdgcn_s_setprio(0); } while (0)
; #define PG8_WAIT_V(n) asm volatile("s_waitcnt vmcnt(" #n ")" ::: "memory")
; #define PG8_WAIT_L(n) asm volatile("s_waitcnt lgkmcnt(" #n ")" ::: "memory")
; #define PG8_BAR __builtin_amdgcn_s_barrier()
; #define PG8_SCHED __builtin_amdgcn_sched_barrier(0)
; template <class Epi>
; __device__ __forceinline__ void gemm_phase(LAS unsigned char* lds, const GemmD g, const Epi& E, int G, int c) {
;     ...
;             PG8_WAIT_V(8); PG8_WAIT_L(0); PG8_BAR; PG8_MMA(1, 0, At, B0); PG8_MMA(1, 1, At, B1); PG8_BAR; PG8_SCHED;
;             PG8_LDB(B0, 1, 0); PG8_LDB(B1, 1, 1); PG8_SCHED; PG8_LDA(At, 1, 0); PG8_STAGE(PG8_SA(0, 1), a2 + hstepA, voffA);
;             PG8_WAIT_V(8); PG8_WAIT_L(0); PG8_BAR; PG8_MMA(0, 0, At, B0); PG8_MMA(0, 1, At, B1); PG8_BAR; PG8_SCHED;
	s_setprio 1
	s_waitcnt lgkmcnt(0)
	v_mfma_f32_16x16x32_bf16 v[52:55], v[140:143], v[184:187], v[52:55]
	v_mfma_f32_16x16x32_bf16 v[56:59], v[154:157], v[184:187], v[56:59]
	v_mfma_f32_16x16x32_bf16 v[40:43], v[140:143], v[192:195], v[40:43]
	v_mfma_f32_16x16x32_bf16 v[32:35], v[154:157], v[192:195], v[32:35]
	v_mfma_f32_16x16x32_bf16 v[20:23], v[140:143], v[214:217], v[20:23]
	v_mfma_f32_16x16x32_bf16 v[16:19], v[154:157], v[214:217], v[16:19]
	v_mfma_f32_16x16x32_bf16 v[4:7], v[140:143], v[222:225], v[4:7]
	v_mfma_f32_16x16x32_bf16 v[0:3], v[154:157], v[222:225], v[0:3]
	v_mfma_f32_16x16x32_bf16 v[52:55], v[144:147], v[188:191], v[52:55]
	v_mfma_f32_16x16x32_bf16 v[56:59], v[158:161], v[188:191], v[56:59]
	v_mfma_f32_16x16x32_bf16 v[40:43], v[144:147], v[210:213], v[40:43]
	v_mfma_f32_16x16x32_bf16 v[32:35], v[158:161], v[210:213], v[32:35]
	v_mfma_f32_16x16x32_bf16 v[20:23], v[144:147], v[218:221], v[20:23]
	v_mfma_f32_16x16x32_bf16 v[16:19], v[158:161], v[218:221], v[16:19]
	v_mfma_f32_16x16x32_bf16 v[4:7], v[144:147], v[226:229], v[4:7]
	v_mfma_f32_16x16x32_bf16 v[0:3], v[158:161], v[226:229], v[0:3]
	v_mfma_f32_16x16x32_bf16 v[60:63], v[162:165], v[184:187], v[60:63]
	v_mfma_f32_16x16x32_bf16 v[48:51], v[170:173], v[184:187], v[48:51]
	v_mfma_f32_16x16x32_bf16 v[44:47], v[162:165], v[192:195], v[44:47]
	v_mfma_f32_16x16x32_bf16 v[36:39], v[170:173], v[192:195], v[36:39]
	v_mfma_f32_16x16x32_bf16 v[28:31], v[162:165], v[214:217], v[28:31]
	v_mfma_f32_16x16x32_bf16 v[24:27], v[170:173], v[214:217], v[24:27]
	v_mfma_f32_16x16x32_bf16 v[12:15], v[162:165], v[222:225], v[12:15]
	v_mfma_f32_16x16x32_bf16 v[8:11], v[170:173], v[222:225], v[8:11]
	v_mfma_f32_16x16x32_bf16 v[60:63], v[166:169], v[188:191], v[60:63]
	v_mfma_f32_16x16x32_bf16 v[48:51], v[180:183], v[188:191], v[48:51]
	v_mfma_f32_16x16x32_bf16 v[44:47], v[166:169], v[210:213], v[44:47]
	v_mfma_f32_16x16x32_bf16 v[36:39], v[180:183], v[210:213], v[36:39]
	v_mfma_f32_16x16x32_bf16 v[28:31], v[166:169], v[218:221], v[28:31]
	v_mfma_f32_16x16x32_bf16 v[24:27], v[180:183], v[218:221], v[24:27]
	v_mfma_f32_16x16x32_bf16 v[12:15], v[166:169], v[226:229], v[12:15]
	v_mfma_f32_16x16x32_bf16 v[8:11], v[180:183], v[226:229], v[8:11]
	s_setprio 0
	s_barrier
	s_add_i32 s31, 0, 0x18000
	v_add_u32_e32 v153, s31, v149
	s_add_i32 s33, 0, 0x1c000
	ds_read_b128 v[140:143], v153
	ds_read_b128 v[144:147], v153 offset:1024
	ds_read_b128 v[154:157], v153 offset:2048
	ds_read_b128 v[158:161], v153 offset:3072
	v_add_u32_e32 v153, s33, v149
	ds_read_b128 v[162:165], v153
	ds_read_b128 v[166:169], v153 offset:1024
	ds_read_b128 v[170:173], v153 offset:2048
	ds_read_b128 v[180:183], v153 offset:3072
	s_add_u32 s4, s4, 0x160000
	s_addc_u32 s5, s5, 0
	s_mov_b32 m0, s10
	v_lshl_add_u64 v[234:235], s[4:5], 0, v[132:133]
	ds_read_b128 v[184:187], v151 offset:32768
	ds_read_b128 v[188:191], v151 offset:33792
	ds_read_b128 v[192:195], v151 offset:34816
	ds_read_b128 v[210:213], v151 offset:35840
	ds_read_b128 v[214:217], v151 offset:36864
	ds_read_b128 v[218:221], v151 offset:37888
	ds_read_b128 v[222:225], v151 offset:38912
	ds_read_b128 v[226:229], v151 offset:39936
	global_load_lds_dwordx4 v[234:235], off
	v_lshl_add_u64 v[234:235], s[4:5], 0, v[130:131]
	s_mov_b32 m0, s11
	s_nop 0
	global_load_lds_dwordx4 v[234:235], off
	s_waitcnt vmcnt(8)
	s_waitcnt lgkmcnt(0)
	s_barrier
	s_setprio 1
	s_waitcnt lgkmcnt(0)
	v_mfma_f32_16x16x32_bf16 v[124:127], v[140:143], v[184:187], v[124:127]
	v_mfma_f32_16x16x32_bf16 v[116:119], v[154:157], v[184:187], v[116:119]
	v_mfma_f32_16x16x32_bf16 v[104:107], v[140:143], v[192:195], v[104:107]
	v_mfma_f32_16x16x32_bf16 v[96:99], v[154:157], v[192:195], v[96:99]
	v_mfma_f32_16x16x32_bf16 v[88:91], v[140:143], v[214:217], v[88:91]
	v_mfma_f32_16x16x32_bf16 v[80:83], v[154:157], v[214:217], v[80:83]
	v_mfma_f32_16x16x32_bf16 v[72:75], v[140:143], v[222:225], v[72:75]
	v_mfma_f32_16x16x32_bf16 v[64:67], v[154:157], v[222:225], v[64:67]
	v_mfma_f32_16x16x32_bf16 v[124:127], v[144:147], v[188:191], v[124:127]
	v_mfma_f32_16x16x32_bf16 v[116:119], v[158:161], v[188:191], v[116:119]
	v_mfma_f32_16x16x32_bf16 v[104:107], v[144:147], v[210:213], v[104:107]
	v_mfma_f32_16x16x32_bf16 v[96:99], v[158:161], v[210:213], v[96:99]
	v_mfma_f32_16x16x32_bf16 v[88:91], v[144:147], v[218:221], v[88:91]
	v_mfma_f32_16x16x32_bf16 v[80:83], v[158:161], v[218:221], v[80:83]
	v_mfma_f32_16x16x32_bf16 v[72:75], v[144:147], v[226:229], v[72:75]
	v_mfma_f32_16x16x32_bf16 v[64:67], v[158:161], v[226:229], v[64:67]
	v_mfma_f32_16x16x32_bf16 v[120:123], v[162:165], v[184:187], v[120:123]
	v_mfma_f32_16x16x32_bf16 v[112:115], v[170:173], v[184:187], v[112:115]
	v_mfma_f32_16x16x32_bf16 v[108:111], v[162:165], v[192:195], v[108:111]
	v_mfma_f32_16x16x32_bf16 v[100:103], v[170:173], v[192:195], v[100:103]
	v_mfma_f32_16x16x32_bf16 v[92:95], v[162:165], v[214:217], v[92:95]
	v_mfma_f32_16x16x32_bf16 v[84:87], v[170:173], v[214:217], v[84:87]
	v_mfma_f32_16x16x32_bf16 v[76:79], v[162:165], v[222:225], v[76:79]
	v_mfma_f32_16x16x32_bf16 v[68:71], v[170:173], v[222:225], v[68:71]
	v_mfma_f32_16x16x32_bf16 v[120:123], v[166:169], v[188:191], v[120:123]
	v_mfma_f32_16x16x32_bf16 v[112:115], v[180:183], v[188:191], v[112:115]
	v_mfma_f32_16x16x32_bf16 v[108:111], v[166:169], v[210:213], v[108:111]
	v_mfma_f32_16x16x32_bf16 v[100:103], v[180:183], v[210:213], v[100:103]
	v_mfma_f32_16x16x32_bf16 v[92:95], v[166:169], v[218:221], v[92:95]
	v_mfma_f32_16x16x32_bf16 v[84:87], v[180:183], v[218:221], v[84:87]
	v_mfma_f32_16x16x32_bf16 v[76:79], v[166:169], v[226:229], v[76:79]
	v_mfma_f32_16x16x32_bf16 v[68:71], v[180:183], v[226:229], v[68:71]
	s_setprio 0
	s_barrier
; #define PG8_STAGE(bufoff, gbase, voff) do { _Pragma("unroll") for (int _i = 0; _i < 2; ++_i) \
;         __builtin_amdgcn_global_load_lds((const unsigned*)((const char*)(gbase) + (voff)[_i]), (LAS unsigned*)(lds + (bufoff) + ldsw + _i * 8192), 16, 0, 0); } while (0)
; #define PG8_LDA(dst, b, h) do { _Pragma("unroll") for (int m = 0; m < 4; ++m) _Pragma("unroll") for (int k = 0; k < 2; ++k) dst[m][k] = *(const LAS bf16x8*)(lds + PG8_SA(b, h) + aoff + m * 2048 + k * 1024); } while (0)
; #define PG8_MMA(ai, bj, At, Bt) do { __builtin_amdgcn_s_setprio(1); _Pragma("unroll") for (int m = 0; m < 4; ++m) _Pragma("unroll") for (int n = 0; n < 2; ++n) _Pragma("unroll") for (int k = 0; k < 2; ++k) \
;         acc[ai][bj][m][n] = __builtin_amdgcn_mfma_f32_16x16x32_bf16(Bt[n][k], At[m][k], acc[ai][bj][m][n], 0, 0, 0); __builtin_amdgcn_s_setprio(0); } while (0)
; #define PG8_WAIT_V(n) asm volatile("s_waitcnt vmcnt(" #n ")" ::: "memory")
; #define PG8_WAIT_L(n) asm volatile("s_waitcnt lgkmcnt(" #n ")" ::: "memory")
; #define PG8_BAR __builtin_amdgcn_s_barrier()
; #define PG8_SCHED __builtin_amdgcn_sched_barrier(0)
; template <class Epi>
; __device__ __forceinline__ void gemm_phase(LAS unsigned char* lds, const GemmD g, const Epi& E, int G, int c) {
;     ...
;             PG8_LDA(At, 1, 1); PG8_STAGE(PG8_SB(1, 0), b3, voffB); PG8_STAGE(PG8_SB(1, 1), b3 + hstepB, voffB); PG8_STAGE(PG8_SA(1, 0), a3, voffA);
;             PG8_WAIT_V(8); PG8_WAIT_L(0); PG8_BAR; PG8_MMA(1, 0, At, B0); PG8_MMA(1, 1, At, B1); PG8_BAR; PG8_SCHED;
;         }
;         if (wr == 0) PG8_BAR;
	s_add_i32 s4, s31, s2
	v_lshl_add_u64 v[174:175], v[174:175], 0, s[48:49]
	s_mov_b32 m0, s4
	ds_read_b128 v[184:187], v151 offset:49152
	ds_read_b128 v[188:191], v151 offset:50176
	ds_read_b128 v[192:195], v151 offset:51200
	ds_read_b128 v[210:213], v151 offset:52224
	ds_read_b128 v[214:217], v151 offset:53248
	ds_read_b128 v[218:221], v151 offset:54272
	ds_read_b128 v[222:225], v151 offset:55296
	ds_read_b128 v[226:229], v151 offset:56320
	global_load_lds_dwordx4 v[174:175], off
	s_add_i32 m0, s4, 0x2000
	s_add_u32 s4, s90, 0x160080
	v_lshl_add_u64 v[174:175], v[198:199], 0, s[48:49]
	s_addc_u32 s5, s91, 0
	s_add_i32 s31, s33, s2
	global_load_lds_dwordx4 v[174:175], off
	v_lshl_add_u64 v[174:175], s[4:5], 0, v[178:179]
	s_mov_b32 m0, s31
	s_nop 0
	global_load_lds_dwordx4 v[174:175], off
	v_lshl_add_u64 v[174:175], s[4:5], 0, v[128:129]
	s_add_i32 m0, s31, 0x2000
	s_nop 0
	global_load_lds_dwordx4 v[174:175], off
	v_lshl_add_u64 v[174:175], v[230:231], 0, s[48:49]
	s_mov_b32 m0, s16
	s_nop 0
	global_load_lds_dwordx4 v[174:175], off
	v_lshl_add_u64 v[174:175], v[232:233], 0, s[48:49]
	s_mov_b32 m0, s17
	s_nop 0
	global_load_lds_dwordx4 v[174:175], off
	s_waitcnt vmcnt(8)
	s_waitcnt lgkmcnt(0)
	s_barrier
	s_setprio 1
	s_waitcnt lgkmcnt(0)
	v_mfma_f32_16x16x32_bf16 v[52:55], v[140:143], v[184:187], v[52:55]
	v_mfma_f32_16x16x32_bf16 v[56:59], v[154:157], v[184:187], v[56:59]
	v_mfma_f32_16x16x32_bf16 v[40:43], v[140:143], v[192:195], v[40:43]
	v_mfma_f32_16x16x32_bf16 v[32:35], v[154:157], v[192:195], v[32:35]
	v_mfma_f32_16x16x32_bf16 v[20:23], v[140:143], v[214:217], v[20:23]
	v_mfma_f32_16x16x32_bf16 v[16:19], v[154:157], v[214:217], v[16:19]
	v_mfma_f32_16x16x32_bf16 v[4:7], v[140:143], v[222:225], v[4:7]
	v_mfma_f32_16x16x32_bf16 v[0:3], v[154:157], v[222:225], v[0:3]
	v_mfma_f32_16x16x32_bf16 v[52:55], v[144:147], v[188:191], v[52:55]
	v_mfma_f32_16x16x32_bf16 v[56:59], v[158:161], v[188:191], v[56:59]
	v_mfma_f32_16x16x32_bf16 v[40:43], v[144:147], v[210:213], v[40:43]
	v_mfma_f32_16x16x32_bf16 v[32:35], v[158:161], v[210:213], v[32:35]
	v_mfma_f32_16x16x32_bf16 v[20:23], v[144:147], v[218:221], v[20:23]
	v_mfma_f32_16x16x32_bf16 v[16:19], v[158:161], v[218:221], v[16:19]
	v_mfma_f32_16x16x32_bf16 v[4:7], v[144:147], v[226:229], v[4:7]
	v_mfma_f32_16x16x32_bf16 v[0:3], v[158:161], v[226:229], v[0:3]
	v_mfma_f32_16x16x32_bf16 v[60:63], v[162:165], v[184:187], v[60:63]
	v_mfma_f32_16x16x32_bf16 v[48:51], v[170:173], v[184:187], v[48:51]
	v_mfma_f32_16x16x32_bf16 v[44:47], v[162:165], v[192:195], v[44:47]
	v_mfma_f32_16x16x32_bf16 v[36:39], v[170:173], v[192:195], v[36:39]
	v_mfma_f32_16x16x32_bf16 v[28:31], v[162:165], v[214:217], v[28:31]
	v_mfma_f32_16x16x32_bf16 v[24:27], v[170:173], v[214:217], v[24:27]
	v_mfma_f32_16x16x32_bf16 v[12:15], v[162:165], v[222:225], v[12:15]
	v_mfma_f32_16x16x32_bf16 v[8:11], v[170:173], v[222:225], v[8:11]
	v_mfma_f32_16x16x32_bf16 v[60:63], v[166:169], v[188:191], v[60:63]
	v_mfma_f32_16x16x32_bf16 v[48:51], v[180:183], v[188:191], v[48:51]
	v_mfma_f32_16x16x32_bf16 v[44:47], v[166:169], v[210:213], v[44:47]
	v_mfma_f32_16x16x32_bf16 v[36:39], v[180:183], v[210:213], v[36:39]
	v_mfma_f32_16x16x32_bf16 v[28:31], v[166:169], v[218:221], v[28:31]
	v_mfma_f32_16x16x32_bf16 v[24:27], v[180:183], v[218:221], v[24:27]
	v_mfma_f32_16x16x32_bf16 v[12:15], v[166:169], v[226:229], v[12:15]
	v_mfma_f32_16x16x32_bf16 v[8:11], v[180:183], v[226:229], v[8:11]
	s_setprio 0
	s_barrier
	s_add_i32 s30, s30, 2
	s_add_u32 s28, s28, 0x100
	s_addc_u32 s29, s29, 0
	s_cmpk_gt_u32 s30, 0x55
	s_mov_b64 s[46:47], s[88:89]
	s_cbranch_scc0 .LBB0_106
	s_and_b64 vcc, exec, s[80:81]
	s_cbranch_vccz .LBB0_109
	s_barrier

; #define PG8_STAGE(bufoff, gbase, voff) do { _Pragma("unroll") for (int _i = 0; _i < 2; ++_i) \
;         __builtin_amdgcn_global_load_lds((const unsigned*)((const char*)(gbase) + (voff)[_i]), (LAS unsigned*)(lds + (bufoff) + ldsw + _i * 8192), 16, 0, 0); } while (0)
; #define PG8_LDA(dst, b, h) do { _Pragma("unroll") for (int m = 0; m < 4; ++m) _Pragma("unroll") for (int k = 0; k < 2; ++k) dst[m][k] = *(const LAS bf16x8*)(lds + PG8_SA(b, h) + aoff + m * 2048 + k * 1024); } while (0)
; #define PG8_MMA(ai, bj, At, Bt) do { __builtin_amdgcn_s_setprio(1); _Pragma("unroll") for (int m = 0; m < 4; ++m) _Pragma("unroll") for (int n = 0; n < 2; ++n) _Pragma("unroll") for (int k = 0; k < 2; ++k) \
;         acc[ai][bj][m][n] = __builtin_amdgcn_mfma_f32_16x16x32_bf16(Bt[n][k], At[m][k], acc[ai][bj][m][n], 0, 0, 0); __builtin_amdgcn_s_setprio(0); } while (0)
; #define PG8_WAIT_V(n) asm volatile("s_waitcnt vmcnt(" #n ")" ::: "memory")
; #define PG8_WAIT_L(n) asm volatile("s_waitcnt lgkmcnt(" #n ")" ::: "memory")
; #define PG8_BAR __builtin_amdgcn_s_barrier()
; #define PG8_SCHED __builtin_amdgcn_sched_barrier(0)
; template <class Epi>
; __device__ __forceinline__ void gemm_phase(LAS unsigned char* lds, const GemmD g, const Epi& E, int G, int c) {
;     ...
;             PG8_WAIT_V(8); PG8_WAIT_L(0); PG8_BAR; PG8_MMA(0, 0, At, B0); PG8_MMA(0, 1, At, B1); PG8_BAR; PG8_SCHED;
;             PG8_LDA(At, 0, 1); PG8_STAGE(PG8_SB(0, 0), b2, voffB); PG8_STAGE(PG8_SB(0, 1), b2 + hstepB, voffB); PG8_STAGE(PG8_SA(0, 0), a2, voffA);
;             PG8_WAIT_V(8); PG8_WAIT_L(0); PG8_BAR; PG8_MMA(1, 0, At, B0); PG8_MMA(1, 1, At, B1); PG8_BAR; PG8_SCHED;
.Lrw_FfnUp_0_d:
	s_waitcnt lgkmcnt(0)
	s_barrier
	s_setprio 1
	s_waitcnt lgkmcnt(0)
	v_mfma_f32_16x16x32_bf16 v[124:127], v[138:141], v[184:187], v[124:127]
	v_mfma_f32_16x16x32_bf16 v[116:119], v[156:159], v[184:187], v[116:119]
	v_mfma_f32_16x16x32_bf16 v[108:111], v[138:141], v[192:195], v[108:111]
	v_mfma_f32_16x16x32_bf16 v[100:103], v[156:159], v[192:195], v[100:103]
	v_mfma_f32_16x16x32_bf16 v[92:95], v[138:141], v[214:217], v[92:95]
	v_mfma_f32_16x16x32_bf16 v[84:87], v[156:159], v[214:217], v[84:87]
	v_mfma_f32_16x16x32_bf16 v[76:79], v[138:141], v[222:225], v[76:79]
	v_mfma_f32_16x16x32_bf16 v[68:71], v[156:159], v[222:225], v[68:71]
	v_mfma_f32_16x16x32_bf16 v[124:127], v[152:155], v[188:191], v[124:127]
	v_mfma_f32_16x16x32_bf16 v[116:119], v[160:163], v[188:191], v[116:119]
	v_mfma_f32_16x16x32_bf16 v[108:111], v[152:155], v[210:213], v[108:111]
	v_mfma_f32_16x16x32_bf16 v[100:103], v[160:163], v[210:213], v[100:103]
	v_mfma_f32_16x16x32_bf16 v[92:95], v[152:155], v[218:221], v[92:95]
	v_mfma_f32_16x16x32_bf16 v[84:87], v[160:163], v[218:221], v[84:87]
	v_mfma_f32_16x16x32_bf16 v[76:79], v[152:155], v[226:229], v[76:79]
	v_mfma_f32_16x16x32_bf16 v[68:71], v[160:163], v[226:229], v[68:71]
	v_mfma_f32_16x16x32_bf16 v[120:123], v[164:167], v[184:187], v[120:123]
	v_mfma_f32_16x16x32_bf16 v[112:115], v[172:175], v[184:187], v[112:115]
	v_mfma_f32_16x16x32_bf16 v[104:107], v[164:167], v[192:195], v[104:107]
	v_mfma_f32_16x16x32_bf16 v[96:99], v[172:175], v[192:195], v[96:99]
	v_mfma_f32_16x16x32_bf16 v[88:91], v[164:167], v[214:217], v[88:91]
	v_mfma_f32_16x16x32_bf16 v[80:83], v[172:175], v[214:217], v[80:83]
	v_mfma_f32_16x16x32_bf16 v[72:75], v[164:167], v[222:225], v[72:75]
	v_mfma_f32_16x16x32_bf16 v[64:67], v[172:175], v[222:225], v[64:67]
	v_mfma_f32_16x16x32_bf16 v[120:123], v[168:171], v[188:191], v[120:123]
	v_mfma_f32_16x16x32_bf16 v[112:115], v[180:183], v[188:191], v[112:115]
	v_mfma_f32_16x16x32_bf16 v[104:107], v[168:171], v[210:213], v[104:107]
	v_mfma_f32_16x16x32_bf16 v[96:99], v[180:183], v[210:213], v[96:99]
	v_mfma_f32_16x16x32_bf16 v[88:91], v[168:171], v[218:221], v[88:91]
	v_mfma_f32_16x16x32_bf16 v[80:83], v[180:183], v[218:221], v[80:83]
	v_mfma_f32_16x16x32_bf16 v[72:75], v[168:171], v[226:229], v[72:75]
	v_mfma_f32_16x16x32_bf16 v[64:67], v[180:183], v[226:229], v[64:67]
	s_setprio 0
	s_barrier
	s_add_i32 s35, s35, s2
	v_lshl_add_u64 v[146:147], s[86:87], 0, v[178:179]
	s_mov_b32 m0, s35
	ds_read_b128 v[184:187], v151 offset:16384
	ds_read_b128 v[188:191], v151 offset:17408
	ds_read_b128 v[192:195], v151 offset:18432
	ds_read_b128 v[210:213], v151 offset:19456
	ds_read_b128 v[214:217], v151 offset:20480
	ds_read_b128 v[218:221], v151 offset:21504
	ds_read_b128 v[222:225], v151 offset:22528
	ds_read_b128 v[226:229], v151 offset:23552
	global_load_lds_dwordx4 v[146:147], off
	s_add_i32 m0, s35, 0x2000
	s_add_u32 s38, s86, 0x80000
	v_lshl_add_u64 v[198:199], s[86:87], 0, v[128:129]
	s_addc_u32 s39, s87, 0
	s_add_i32 s35, s36, s2
	global_load_lds_dwordx4 v[198:199], off
	v_lshl_add_u64 v[230:231], s[38:39], 0, v[178:179]
	s_mov_b32 m0, s35
	v_lshl_add_u64 v[232:233], s[4:5], 0, v[130:131]
	global_load_lds_dwordx4 v[230:231], off
	v_lshl_add_u64 v[230:231], s[38:39], 0, v[128:129]
	s_add_i32 m0, s35, 0x2000
	s_nop 0
	global_load_lds_dwordx4 v[230:231], off
	v_lshl_add_u64 v[230:231], s[4:5], 0, v[132:133]
	s_mov_b32 m0, s6
	s_nop 0
	global_load_lds_dwordx4 v[230:231], off
	s_mov_b32 m0, s9
	s_nop 0
	global_load_lds_dwordx4 v[232:233], off
	s_cmp_lg_u32 s99, 0
	s_cbranch_scc1 .Lrw_FfnUp_1_r
	s_waitcnt vmcnt(8)
	s_branch .Lrw_FfnUp_1_d

; #define PG8_STAGE(bufoff, gbase, voff) do { _Pragma("unroll") for (int _i = 0; _i < 2; ++_i) \
;         __builtin_amdgcn_global_load_lds((const unsigned*)((const char*)(gbase) + (voff)[_i]), (LAS unsigned*)(lds + (bufoff) + ldsw + _i * 8192), 16, 0, 0); } while (0)
; #define PG8_LDA(dst, b, h) do { _Pragma("unroll") for (int m = 0; m < 4; ++m) _Pragma("unroll") for (int k = 0; k < 2; ++k) dst[m][k] = *(const LAS bf16x8*)(lds + PG8_SA(b, h) + aoff + m * 2048 + k * 1024); } while (0)
; #define PG8_LDB(dst, b, h) do { _Pragma("unroll") for (int n = 0; n < 2; ++n) _Pragma("unroll") for (int k = 0; k < 2; ++k) dst[n][k] = *(const LAS bf16x8*)(lds + PG8_SB(b, h) + boff + n * 2048 + k * 1024); } while (0)
; #define PG8_MMA(ai, bj, At, Bt) do { __builtin_amdgcn_s_setprio(1); _Pragma("unroll") for (int m = 0; m < 4; ++m) _Pragma("unroll") for (int n = 0; n < 2; ++n) _Pragma("unroll") for (int k = 0; k < 2; ++k) \
;         acc[ai][bj][m][n] = __builtin_amdgcn_mfma_f32_16x16x32_bf16(Bt[n][k], At[m][k], acc[ai][bj][m][n], 0, 0, 0); __builtin_amdgcn_s_setprio(0); } while (0)
; #define PG8_WAIT_V(n) asm volatile("s_waitcnt vmcnt(" #n ")" ::: "memory")
; #define PG8_WAIT_L(n) asm volatile("s_waitcnt lgkmcnt(" #n ")" ::: "memory")
; #define PG8_BAR __builtin_amdgcn_s_barrier()
; #define PG8_SCHED __builtin_amdgcn_sched_barrier(0)
; template <class Epi>
; __device__ __forceinline__ void gemm_phase(LAS unsigned char* lds, const GemmD g, const Epi& E, int G, int c) {
;     ...
;             PG8_WAIT_V(8); PG8_WAIT_L(0); PG8_BAR; PG8_MMA(1, 0, At, B0); PG8_MMA(1, 1, At, B1); PG8_BAR; PG8_SCHED;
;             PG8_LDB(B0, 1, 0); PG8_LDB(B1, 1, 1); PG8_SCHED; PG8_LDA(At, 1, 0); PG8_STAGE(PG8_SA(0, 1), a2 + hstepA, voffA);
;             PG8_WAIT_V(8); PG8_WAIT_L(0); PG8_BAR; PG8_MMA(0, 0, At, B0); PG8_MMA(0, 1, At, B1); PG8_BAR; PG8_SCHED;
.Lrw_FfnUp_1_d:
	s_waitcnt lgkmcnt(0)
	s_barrier
	s_setprio 1
	s_waitcnt lgkmcnt(0)
	v_mfma_f32_16x16x32_bf16 v[60:63], v[138:141], v[184:187], v[60:63]
	v_mfma_f32_16x16x32_bf16 v[52:55], v[156:159], v[184:187], v[52:55]
	v_mfma_f32_16x16x32_bf16 v[44:47], v[138:141], v[192:195], v[44:47]
	v_mfma_f32_16x16x32_bf16 v[36:39], v[156:159], v[192:195], v[36:39]
	v_mfma_f32_16x16x32_bf16 v[28:31], v[138:141], v[214:217], v[28:31]
	v_mfma_f32_16x16x32_bf16 v[20:23], v[156:159], v[214:217], v[20:23]
	v_mfma_f32_16x16x32_bf16 v[12:15], v[138:141], v[222:225], v[12:15]
	v_mfma_f32_16x16x32_bf16 v[4:7], v[156:159], v[222:225], v[4:7]
	v_mfma_f32_16x16x32_bf16 v[60:63], v[152:155], v[188:191], v[60:63]
	v_mfma_f32_16x16x32_bf16 v[52:55], v[160:163], v[188:191], v[52:55]
	v_mfma_f32_16x16x32_bf16 v[44:47], v[152:155], v[210:213], v[44:47]
	v_mfma_f32_16x16x32_bf16 v[36:39], v[160:163], v[210:213], v[36:39]
	v_mfma_f32_16x16x32_bf16 v[28:31], v[152:155], v[218:221], v[28:31]
	v_mfma_f32_16x16x32_bf16 v[20:23], v[160:163], v[218:221], v[20:23]
	v_mfma_f32_16x16x32_bf16 v[12:15], v[152:155], v[226:229], v[12:15]
	v_mfma_f32_16x16x32_bf16 v[4:7], v[160:163], v[226:229], v[4:7]
	v_mfma_f32_16x16x32_bf16 v[56:59], v[164:167], v[184:187], v[56:59]
	v_mfma_f32_16x16x32_bf16 v[48:51], v[172:175], v[184:187], v[48:51]
	v_mfma_f32_16x16x32_bf16 v[40:43], v[164:167], v[192:195], v[40:43]
	v_mfma_f32_16x16x32_bf16 v[32:35], v[172:175], v[192:195], v[32:35]
	v_mfma_f32_16x16x32_bf16 v[24:27], v[164:167], v[214:217], v[24:27]
	v_mfma_f32_16x16x32_bf16 v[16:19], v[172:175], v[214:217], v[16:19]
	v_mfma_f32_16x16x32_bf16 v[8:11], v[164:167], v[222:225], v[8:11]
	v_mfma_f32_16x16x32_bf16 v[0:3], v[172:175], v[222:225], v[0:3]
	v_mfma_f32_16x16x32_bf16 v[56:59], v[168:171], v[188:191], v[56:59]
	v_mfma_f32_16x16x32_bf16 v[48:51], v[180:183], v[188:191], v[48:51]
	v_mfma_f32_16x16x32_bf16 v[40:43], v[168:171], v[210:213], v[40:43]
	v_mfma_f32_16x16x32_bf16 v[32:35], v[180:183], v[210:213], v[32:35]
	v_mfma_f32_16x16x32_bf16 v[24:27], v[168:171], v[218:221], v[24:27]
	v_mfma_f32_16x16x32_bf16 v[16:19], v[180:183], v[218:221], v[16:19]
	v_mfma_f32_16x16x32_bf16 v[8:11], v[168:171], v[226:229], v[8:11]
	v_mfma_f32_16x16x32_bf16 v[0:3], v[180:183], v[226:229], v[0:3]
	s_setprio 0
	s_barrier
	s_add_i32 s35, 0, 0x18000
	v_add_u32_e32 v142, s35, v145
	s_add_i32 s36, 0, 0x1c000
	ds_read_b128 v[138:141], v142
	ds_read_b128 v[152:155], v142 offset:1024
	ds_read_b128 v[156:159], v142 offset:2048
	ds_read_b128 v[160:163], v142 offset:3072
	v_add_u32_e32 v142, s36, v145
	ds_read_b128 v[164:167], v142
	ds_read_b128 v[168:171], v142 offset:1024
	ds_read_b128 v[172:175], v142 offset:2048
	ds_read_b128 v[180:183], v142 offset:3072
	s_add_u32 s4, s4, 0x80000
	s_addc_u32 s5, s5, 0
	s_mov_b32 m0, s10
	v_lshl_add_u64 v[234:235], s[4:5], 0, v[132:133]
	ds_read_b128 v[184:187], v151 offset:32768
	ds_read_b128 v[188:191], v151 offset:33792
	ds_read_b128 v[192:195], v151 offset:34816
	ds_read_b128 v[210:213], v151 offset:35840
	ds_read_b128 v[214:217], v151 offset:36864
	ds_read_b128 v[218:221], v151 offset:37888
	ds_read_b128 v[222:225], v151 offset:38912
	ds_read_b128 v[226:229], v151 offset:39936
	global_load_lds_dwordx4 v[234:235], off
	v_lshl_add_u64 v[234:235], s[4:5], 0, v[130:131]
	s_mov_b32 m0, s11
	s_nop 0
	global_load_lds_dwordx4 v[234:235], off
	s_waitcnt vmcnt(8)
	s_waitcnt lgkmcnt(0)
	s_barrier
	s_setprio 1
	s_waitcnt lgkmcnt(0)
	v_mfma_f32_16x16x32_bf16 v[124:127], v[138:141], v[184:187], v[124:127]
	v_mfma_f32_16x16x32_bf16 v[116:119], v[156:159], v[184:187], v[116:119]
	v_mfma_f32_16x16x32_bf16 v[108:111], v[138:141], v[192:195], v[108:111]
	v_mfma_f32_16x16x32_bf16 v[100:103], v[156:159], v[192:195], v[100:103]
	v_mfma_f32_16x16x32_bf16 v[92:95], v[138:141], v[214:217], v[92:95]
	v_mfma_f32_16x16x32_bf16 v[84:87], v[156:159], v[214:217], v[84:87]
	v_mfma_f32_16x16x32_bf16 v[76:79], v[138:141], v[222:225], v[76:79]
	v_mfma_f32_16x16x32_bf16 v[68:71], v[156:159], v[222:225], v[68:71]
	v_mfma_f32_16x16x32_bf16 v[124:127], v[152:155], v[188:191], v[124:127]
	v_mfma_f32_16x16x32_bf16 v[116:119], v[160:163], v[188:191], v[116:119]
	v_mfma_f32_16x16x32_bf16 v[108:111], v[152:155], v[210:213], v[108:111]
	v_mfma_f32_16x16x32_bf16 v[100:103], v[160:163], v[210:213], v[100:103]
	v_mfma_f32_16x16x32_bf16 v[92:95], v[152:155], v[218:221], v[92:95]
	v_mfma_f32_16x16x32_bf16 v[84:87], v[160:163], v[218:221], v[84:87]
	v_mfma_f32_16x16x32_bf16 v[76:79], v[152:155], v[226:229], v[76:79]
	v_mfma_f32_16x16x32_bf16 v[68:71], v[160:163], v[226:229], v[68:71]
	v_mfma_f32_16x16x32_bf16 v[120:123], v[164:167], v[184:187], v[120:123]
	v_mfma_f32_16x16x32_bf16 v[112:115], v[172:175], v[184:187], v[112:115]
	v_mfma_f32_16x16x32_bf16 v[104:107], v[164:167], v[192:195], v[104:107]
	v_mfma_f32_16x16x32_bf16 v[96:99], v[172:175], v[192:195], v[96:99]
	v_mfma_f32_16x16x32_bf16 v[88:91], v[164:167], v[214:217], v[88:91]
	v_mfma_f32_16x16x32_bf16 v[80:83], v[172:175], v[214:217], v[80:83]
	v_mfma_f32_16x16x32_bf16 v[72:75], v[164:167], v[222:225], v[72:75]
	v_mfma_f32_16x16x32_bf16 v[64:67], v[172:175], v[222:225], v[64:67]
	v_mfma_f32_16x16x32_bf16 v[120:123], v[168:171], v[188:191], v[120:123]
	v_mfma_f32_16x16x32_bf16 v[112:115], v[180:183], v[188:191], v[112:115]
	v_mfma_f32_16x16x32_bf16 v[104:107], v[168:171], v[210:213], v[104:107]
	v_mfma_f32_16x16x32_bf16 v[96:99], v[180:183], v[210:213], v[96:99]
	v_mfma_f32_16x16x32_bf16 v[88:91], v[168:171], v[218:221], v[88:91]
	v_mfma_f32_16x16x32_bf16 v[80:83], v[180:183], v[218:221], v[80:83]
	v_mfma_f32_16x16x32_bf16 v[72:75], v[168:171], v[226:229], v[72:75]
	v_mfma_f32_16x16x32_bf16 v[64:67], v[180:183], v[226:229], v[64:67]
	s_setprio 0
	s_barrier
; #define PG8_STAGE(bufoff, gbase, voff) do { _Pragma("unroll") for (int _i = 0; _i < 2; ++_i) \
;         __builtin_amdgcn_global_load_lds((const unsigned*)((const char*)(gbase) + (voff)[_i]), (LAS unsigned*)(lds + (bufoff) + ldsw + _i * 8192), 16, 0, 0); } while (0)
; #define PG8_LDA(dst, b, h) do { _Pragma("unroll") for (int m = 0; m < 4; ++m) _Pragma("unroll") for (int k = 0; k < 2; ++k) dst[m][k] = *(const LAS bf16x8*)(lds + PG8_SA(b, h) + aoff + m * 2048 + k * 1024); } while (0)
; #define PG8_MMA(ai, bj, At, Bt) do { __builtin_amdgcn_s_setprio(1); _Pragma("unroll") for (int m = 0; m < 4; ++m) _Pragma("unroll") for (int n = 0; n < 2; ++n) _Pragma("unroll") for (int k = 0; k < 2; ++k) \
;         acc[ai][bj][m][n] = __builtin_amdgcn_mfma_f32_16x16x32_bf16(Bt[n][k], At[m][k], acc[ai][bj][m][n], 0, 0, 0); __builtin_amdgcn_s_setprio(0); } while (0)
; #define PG8_WAIT_V(n) asm volatile("s_waitcnt vmcnt(" #n ")" ::: "memory")
; #define PG8_WAIT_L(n) asm volatile("s_waitcnt lgkmcnt(" #n ")" ::: "memory")
; #define PG8_BAR __builtin_amdgcn_s_barrier()
; #define PG8_SCHED __builtin_amdgcn_sched_barrier(0)
; template <class Epi>
; __device__ __forceinline__ void gemm_phase(LAS unsigned char* lds, const GemmD g, const Epi& E, int G, int c) {
;     ...
;             PG8_LDA(At, 1, 1); PG8_STAGE(PG8_SB(1, 0), b3, voffB); PG8_STAGE(PG8_SB(1, 1), b3 + hstepB, voffB); PG8_STAGE(PG8_SA(1, 0), a3, voffA);
;             PG8_WAIT_V(8); PG8_WAIT_L(0); PG8_BAR; PG8_MMA(1, 0, At, B0); PG8_MMA(1, 1, At, B1); PG8_BAR; PG8_SCHED;
;         }
;         if (wr == 0) PG8_BAR;
	s_add_i32 s4, s35, s2
	v_lshl_add_u64 v[146:147], v[146:147], 0, s[48:49]
	s_mov_b32 m0, s4
	ds_read_b128 v[184:187], v151 offset:49152
	ds_read_b128 v[188:191], v151 offset:50176
	ds_read_b128 v[192:195], v151 offset:51200
	ds_read_b128 v[210:213], v151 offset:52224
	ds_read_b128 v[214:217], v151 offset:53248
	ds_read_b128 v[218:221], v151 offset:54272
	ds_read_b128 v[222:225], v151 offset:55296
	ds_read_b128 v[226:229], v151 offset:56320
	global_load_lds_dwordx4 v[146:147], off
	s_add_i32 m0, s4, 0x2000
	s_add_u32 s4, s86, 0x80080
	v_lshl_add_u64 v[146:147], v[198:199], 0, s[48:49]
	s_addc_u32 s5, s87, 0
	s_add_i32 s35, s36, s2
	global_load_lds_dwordx4 v[146:147], off
	v_lshl_add_u64 v[146:147], s[4:5], 0, v[178:179]
	s_mov_b32 m0, s35
	s_nop 0
	global_load_lds_dwordx4 v[146:147], off
	v_lshl_add_u64 v[146:147], s[4:5], 0, v[128:129]
	s_add_i32 m0, s35, 0x2000
	s_nop 0
	global_load_lds_dwordx4 v[146:147], off
	v_lshl_add_u64 v[146:147], v[230:231], 0, s[48:49]
	s_mov_b32 m0, s16
	s_nop 0
	global_load_lds_dwordx4 v[146:147], off
	v_lshl_add_u64 v[146:147], v[232:233], 0, s[48:49]
	s_mov_b32 m0, s17
	s_nop 0
	global_load_lds_dwordx4 v[146:147], off
	s_waitcnt vmcnt(8)
	s_waitcnt lgkmcnt(0)
	s_barrier
	s_setprio 1
	s_waitcnt lgkmcnt(0)
	v_mfma_f32_16x16x32_bf16 v[60:63], v[138:141], v[184:187], v[60:63]
	v_mfma_f32_16x16x32_bf16 v[52:55], v[156:159], v[184:187], v[52:55]
	v_mfma_f32_16x16x32_bf16 v[44:47], v[138:141], v[192:195], v[44:47]
	v_mfma_f32_16x16x32_bf16 v[36:39], v[156:159], v[192:195], v[36:39]
	v_mfma_f32_16x16x32_bf16 v[28:31], v[138:141], v[214:217], v[28:31]
	v_mfma_f32_16x16x32_bf16 v[20:23], v[156:159], v[214:217], v[20:23]
	v_mfma_f32_16x16x32_bf16 v[12:15], v[138:141], v[222:225], v[12:15]
	v_mfma_f32_16x16x32_bf16 v[4:7], v[156:159], v[222:225], v[4:7]
	v_mfma_f32_16x16x32_bf16 v[60:63], v[152:155], v[188:191], v[60:63]
	v_mfma_f32_16x16x32_bf16 v[52:55], v[160:163], v[188:191], v[52:55]
	v_mfma_f32_16x16x32_bf16 v[44:47], v[152:155], v[210:213], v[44:47]
	v_mfma_f32_16x16x32_bf16 v[36:39], v[160:163], v[210:213], v[36:39]
	v_mfma_f32_16x16x32_bf16 v[28:31], v[152:155], v[218:221], v[28:31]
	v_mfma_f32_16x16x32_bf16 v[20:23], v[160:163], v[218:221], v[20:23]
	v_mfma_f32_16x16x32_bf16 v[12:15], v[152:155], v[226:229], v[12:15]
	v_mfma_f32_16x16x32_bf16 v[4:7], v[160:163], v[226:229], v[4:7]
	v_mfma_f32_16x16x32_bf16 v[56:59], v[164:167], v[184:187], v[56:59]
	v_mfma_f32_16x16x32_bf16 v[48:51], v[172:175], v[184:187], v[48:51]
	v_mfma_f32_16x16x32_bf16 v[40:43], v[164:167], v[192:195], v[40:43]
	v_mfma_f32_16x16x32_bf16 v[32:35], v[172:175], v[192:195], v[32:35]
	v_mfma_f32_16x16x32_bf16 v[24:27], v[164:167], v[214:217], v[24:27]
	v_mfma_f32_16x16x32_bf16 v[16:19], v[172:175], v[214:217], v[16:19]
	v_mfma_f32_16x16x32_bf16 v[8:11], v[164:167], v[222:225], v[8:11]
	v_mfma_f32_16x16x32_bf16 v[0:3], v[172:175], v[222:225], v[0:3]
	v_mfma_f32_16x16x32_bf16 v[56:59], v[168:171], v[188:191], v[56:59]
	v_mfma_f32_16x16x32_bf16 v[48:51], v[180:183], v[188:191], v[48:51]
	v_mfma_f32_16x16x32_bf16 v[40:43], v[168:171], v[210:213], v[40:43]
	v_mfma_f32_16x16x32_bf16 v[32:35], v[180:183], v[210:213], v[32:35]
	v_mfma_f32_16x16x32_bf16 v[24:27], v[168:171], v[218:221], v[24:27]
	v_mfma_f32_16x16x32_bf16 v[16:19], v[180:183], v[218:221], v[16:19]
	v_mfma_f32_16x16x32_bf16 v[8:11], v[168:171], v[226:229], v[8:11]
	v_mfma_f32_16x16x32_bf16 v[0:3], v[180:183], v[226:229], v[0:3]
	s_setprio 0
	s_barrier
	s_add_i32 s33, s33, 2
	s_add_u32 s42, s42, 0x100
	s_addc_u32 s43, s43, 0
	s_add_u32 s30, s30, 0x100
	s_addc_u32 s31, s31, 0
	s_cmp_gt_u32 s33, 29
	s_cbranch_scc0 .LBB0_202
	s_and_b64 vcc, exec, s[46:47]
	s_cbranch_vccz .LBB0_205
	s_barrier

; #define PG8_STAGE(bufoff, gbase, voff) do { _Pragma("unroll") for (int _i = 0; _i < 2; ++_i) \
;         __builtin_amdgcn_global_load_lds((const unsigned*)((const char*)(gbase) + (voff)[_i]), (LAS unsigned*)(lds + (bufoff) + ldsw + _i * 8192), 16, 0, 0); } while (0)
; #define PG8_LDA(dst, b, h) do { _Pragma("unroll") for (int m = 0; m < 4; ++m) _Pragma("unroll") for (int k = 0; k < 2; ++k) dst[m][k] = *(const LAS bf16x8*)(lds + PG8_SA(b, h) + aoff + m * 2048 + k * 1024); } while (0)
; #define PG8_LDB(dst, b, h) do { _Pragma("unroll") for (int n = 0; n < 2; ++n) _Pragma("unroll") for (int k = 0; k < 2; ++k) dst[n][k] = *(const LAS bf16x8*)(lds + PG8_SB(b, h) + boff + n * 2048 + k * 1024); } while (0)
; #define PG8_MMA(ai, bj, At, Bt) do { __builtin_amdgcn_s_setprio(1); _Pragma("unroll") for (int m = 0; m < 4; ++m) _Pragma("unroll") for (int n = 0; n < 2; ++n) _Pragma("unroll") for (int k = 0; k < 2; ++k) \
;         acc[ai][bj][m][n] = __builtin_amdgcn_mfma_f32_16x16x32_bf16(Bt[n][k], At[m][k], acc[ai][bj][m][n], 0, 0, 0); __builtin_amdgcn_s_setprio(0); } while (0)
; #define PG8_WAIT_V(n) asm volatile("s_waitcnt vmcnt(" #n ")" ::: "memory")
; #define PG8_WAIT_L(n) asm volatile("s_waitcnt lgkmcnt(" #n ")" ::: "memory")
; #define PG8_BAR __builtin_amdgcn_s_barrier()
; #define PG8_SCHED __builtin_amdgcn_sched_barrier(0)
; template <class Epi>
; __device__ __forceinline__ void gemm_phase(LAS unsigned char* lds, const GemmD g, const Epi& E, int G, int c) {
;     ...
;         for (int t = 0; t < nt; t += 2) {
;             const bool last = (t == nt - 2);
;             const char* a1 = cA + (size_t)(t + 1) * kstep;
;             const char* a2 = last ? nA : cA + (size_t)(t + 2) * kstep; const char* b2 = last ? nB : cB + (size_t)(t + 2) * kstep;
;             const char* a3 = a2 + kstep; const char* b3 = b2 + kstep;
;             PG8_LDB(B0, 0, 0); PG8_LDB(B1, 0, 1); PG8_SCHED; PG8_LDA(At, 0, 0); PG8_STAGE(PG8_SA(1, 1), a1 + hstepA, voffA);
;             PG8_WAIT_V(8); PG8_WAIT_L(0); PG8_BAR; PG8_MMA(0, 0, At, B0); PG8_MMA(0, 1, At, B1); PG8_BAR; PG8_SCHED;
;             PG8_LDA(At, 0, 1); PG8_STAGE(PG8_SB(0, 0), b2, voffB); PG8_STAGE(PG8_SB(0, 1), b2 + hstepB, voffB); PG8_STAGE(PG8_SA(0, 0), a2, voffA);
;             PG8_WAIT_V(8); PG8_WAIT_L(0); PG8_BAR; PG8_MMA(1, 0, At, B0); PG8_MMA(1, 1, At, B1); PG8_BAR; PG8_SCHED;
.LBB0_224:
	s_add_u32 s4, s86, 0xfff80080
	s_addc_u32 s5, s87, -1
	s_add_i32 s35, 0, 0x10000
	s_cmp_eq_u32 s33, 28
	s_cselect_b32 s5, s26, s5
	s_cselect_b32 s4, s27, s4
	v_add_u32_e32 v140, s35, v143
	s_cselect_b32 s85, s28, s31
	s_cselect_b32 s84, s29, s30
	s_add_i32 s36, 0, 0x14000
	ds_read_b128 v[148:151], v140
	ds_read_b128 v[152:155], v140 offset:1024
	ds_read_b128 v[156:159], v140 offset:2048
	ds_read_b128 v[160:163], v140 offset:3072
	v_add_u32_e32 v140, s36, v143
	ds_read_b128 v[164:167], v140
	ds_read_b128 v[168:171], v140 offset:1024
	ds_read_b128 v[172:175], v140 offset:2048
	ds_read_b128 v[180:183], v140 offset:3072
	v_lshl_add_u64 v[140:141], s[86:87], 0, v[136:137]
	s_add_i32 m0, s6, 0xc000
	ds_read_b128 v[184:187], v145
	ds_read_b128 v[188:191], v145 offset:1024
	ds_read_b128 v[192:195], v145 offset:2048
	ds_read_b128 v[210:213], v145 offset:3072
	ds_read_b128 v[214:217], v145 offset:4096
	ds_read_b128 v[218:221], v145 offset:5120
	ds_read_b128 v[222:225], v145 offset:6144
	ds_read_b128 v[226:229], v145 offset:7168
	global_load_lds_dwordx4 v[140:141], off
	v_lshl_add_u64 v[140:141], s[86:87], 0, v[138:139]
	s_add_i32 m0, s6, 0xe000
	s_nop 0
	global_load_lds_dwordx4 v[140:141], off
	s_waitcnt vmcnt(8)
	s_waitcnt lgkmcnt(0)
	s_barrier
	s_setprio 1
	s_waitcnt lgkmcnt(0)
	v_mfma_f32_16x16x32_bf16 v[124:127], v[148:151], v[184:187], v[124:127]
	v_mfma_f32_16x16x32_bf16 v[120:123], v[156:159], v[184:187], v[120:123]
	v_mfma_f32_16x16x32_bf16 v[108:111], v[148:151], v[192:195], v[108:111]
	v_mfma_f32_16x16x32_bf16 v[104:107], v[156:159], v[192:195], v[104:107]
	v_mfma_f32_16x16x32_bf16 v[92:95], v[148:151], v[214:217], v[92:95]
	v_mfma_f32_16x16x32_bf16 v[88:91], v[156:159], v[214:217], v[88:91]
	v_mfma_f32_16x16x32_bf16 v[76:79], v[148:151], v[222:225], v[76:79]
	v_mfma_f32_16x16x32_bf16 v[72:75], v[156:159], v[222:225], v[72:75]
	v_mfma_f32_16x16x32_bf16 v[124:127], v[152:155], v[188:191], v[124:127]
	v_mfma_f32_16x16x32_bf16 v[120:123], v[160:163], v[188:191], v[120:123]
	v_mfma_f32_16x16x32_bf16 v[108:111], v[152:155], v[210:213], v[108:111]
	v_mfma_f32_16x16x32_bf16 v[104:107], v[160:163], v[210:213], v[104:107]
	v_mfma_f32_16x16x32_bf16 v[92:95], v[152:155], v[218:221], v[92:95]
	v_mfma_f32_16x16x32_bf16 v[88:91], v[160:163], v[218:221], v[88:91]
	v_mfma_f32_16x16x32_bf16 v[76:79], v[152:155], v[226:229], v[76:79]
	v_mfma_f32_16x16x32_bf16 v[72:75], v[160:163], v[226:229], v[72:75]
	v_mfma_f32_16x16x32_bf16 v[116:119], v[164:167], v[184:187], v[116:119]
	v_mfma_f32_16x16x32_bf16 v[112:115], v[172:175], v[184:187], v[112:115]
	v_mfma_f32_16x16x32_bf16 v[100:103], v[164:167], v[192:195], v[100:103]
	v_mfma_f32_16x16x32_bf16 v[96:99], v[172:175], v[192:195], v[96:99]
	v_mfma_f32_16x16x32_bf16 v[84:87], v[164:167], v[214:217], v[84:87]
	v_mfma_f32_16x16x32_bf16 v[80:83], v[172:175], v[214:217], v[80:83]
	v_mfma_f32_16x16x32_bf16 v[68:71], v[164:167], v[222:225], v[68:71]
	v_mfma_f32_16x16x32_bf16 v[64:67], v[172:175], v[222:225], v[64:67]
	v_mfma_f32_16x16x32_bf16 v[116:119], v[168:171], v[188:191], v[116:119]
	v_mfma_f32_16x16x32_bf16 v[112:115], v[180:183], v[188:191], v[112:115]
	v_mfma_f32_16x16x32_bf16 v[100:103], v[168:171], v[210:213], v[100:103]
	v_mfma_f32_16x16x32_bf16 v[96:99], v[180:183], v[210:213], v[96:99]
	v_mfma_f32_16x16x32_bf16 v[84:87], v[168:171], v[218:221], v[84:87]
	v_mfma_f32_16x16x32_bf16 v[80:83], v[180:183], v[218:221], v[80:83]
	v_mfma_f32_16x16x32_bf16 v[68:71], v[168:171], v[226:229], v[68:71]
	v_mfma_f32_16x16x32_bf16 v[64:67], v[180:183], v[226:229], v[64:67]
	s_setprio 0
	s_barrier
	s_add_i32 s35, s35, s2
	v_lshl_add_u64 v[140:141], s[84:85], 0, v[178:179]
	s_mov_b32 m0, s35
	ds_read_b128 v[184:187], v145 offset:16384
	ds_read_b128 v[188:191], v145 offset:17408
	ds_read_b128 v[192:195], v145 offset:18432
	ds_read_b128 v[210:213], v145 offset:19456
	ds_read_b128 v[214:217], v145 offset:20480
	ds_read_b128 v[218:221], v145 offset:21504
	ds_read_b128 v[222:225], v145 offset:22528
	ds_read_b128 v[226:229], v145 offset:23552
	global_load_lds_dwordx4 v[140:141], off
	s_add_i32 m0, s35, 0x2000
	s_add_u32 s38, s84, 0x80000
	v_lshl_add_u64 v[198:199], s[84:85], 0, v[128:129]
	s_addc_u32 s39, s85, 0
	s_add_i32 s35, s36, s2
	global_load_lds_dwordx4 v[198:199], off
	v_lshl_add_u64 v[230:231], s[38:39], 0, v[178:179]
	s_mov_b32 m0, s35
	v_lshl_add_u64 v[232:233], s[4:5], 0, v[130:131]
	global_load_lds_dwordx4 v[230:231], off
	v_lshl_add_u64 v[230:231], s[38:39], 0, v[128:129]
	s_add_i32 m0, s35, 0x2000
	s_nop 0
	global_load_lds_dwordx4 v[230:231], off
	v_lshl_add_u64 v[230:231], s[4:5], 0, v[132:133]
	s_mov_b32 m0, s6
	s_nop 0
	global_load_lds_dwordx4 v[230:231], off
	s_mov_b32 m0, s9
	s_nop 0
	global_load_lds_dwordx4 v[232:233], off
	s_waitcnt vmcnt(8)
	s_waitcnt lgkmcnt(0)
	s_barrier
; #define PG8_STAGE(bufoff, gbase, voff) do { _Pragma("unroll") for (int _i = 0; _i < 2; ++_i) \
;         __builtin_amdgcn_global_load_lds((const unsigned*)((const char*)(gbase) + (voff)[_i]), (LAS unsigned*)(lds + (bufoff) + ldsw + _i * 8192), 16, 0, 0); } while (0)
; #define PG8_LDA(dst, b, h) do { _Pragma("unroll") for (int m = 0; m < 4; ++m) _Pragma("unroll") for (int k = 0; k < 2; ++k) dst[m][k] = *(const LAS bf16x8*)(lds + PG8_SA(b, h) + aoff + m * 2048 + k * 1024); } while (0)
; #define PG8_LDB(dst, b, h) do { _Pragma("unroll") for (int n = 0; n < 2; ++n) _Pragma("unroll") for (int k = 0; k < 2; ++k) dst[n][k] = *(const LAS bf16x8*)(lds + PG8_SB(b, h) + boff + n * 2048 + k * 1024); } while (0)
; #define PG8_MMA(ai, bj, At, Bt) do { __builtin_amdgcn_s_setprio(1); _Pragma("unroll") for (int m = 0; m < 4; ++m) _Pragma("unroll") for (int n = 0; n < 2; ++n) _Pragma("unroll") for (int k = 0; k < 2; ++k) \
;         acc[ai][bj][m][n] = __builtin_amdgcn_mfma_f32_16x16x32_bf16(Bt[n][k], At[m][k], acc[ai][bj][m][n], 0, 0, 0); __builtin_amdgcn_s_setprio(0); } while (0)
; #define PG8_WAIT_V(n) asm volatile("s_waitcnt vmcnt(" #n ")" ::: "memory")
; #define PG8_WAIT_L(n) asm volatile("s_waitcnt lgkmcnt(" #n ")" ::: "memory")
; #define PG8_BAR __builtin_amdgcn_s_barrier()
; #define PG8_SCHED __builtin_amdgcn_sched_barrier(0)
; template <class Epi>
; __device__ __forceinline__ void gemm_phase(LAS unsigned char* lds, const GemmD g, const Epi& E, int G, int c) {
;     ...
;             PG8_WAIT_V(8); PG8_WAIT_L(0); PG8_BAR; PG8_MMA(1, 0, At, B0); PG8_MMA(1, 1, At, B1); PG8_BAR; PG8_SCHED;
;             PG8_LDB(B0, 1, 0); PG8_LDB(B1, 1, 1); PG8_SCHED; PG8_LDA(At, 1, 0); PG8_STAGE(PG8_SA(0, 1), a2 + hstepA, voffA);
;             PG8_WAIT_V(8); PG8_WAIT_L(0); PG8_BAR; PG8_MMA(0, 0, At, B0); PG8_MMA(0, 1, At, B1); PG8_BAR; PG8_SCHED;
	s_setprio 1
	s_waitcnt lgkmcnt(0)
	v_mfma_f32_16x16x32_bf16 v[56:59], v[148:151], v[184:187], v[56:59]
	v_mfma_f32_16x16x32_bf16 v[60:63], v[156:159], v[184:187], v[60:63]
	v_mfma_f32_16x16x32_bf16 v[40:43], v[148:151], v[192:195], v[40:43]
	v_mfma_f32_16x16x32_bf16 v[36:39], v[156:159], v[192:195], v[36:39]
	v_mfma_f32_16x16x32_bf16 v[28:31], v[148:151], v[214:217], v[28:31]
	v_mfma_f32_16x16x32_bf16 v[24:27], v[156:159], v[214:217], v[24:27]
	v_mfma_f32_16x16x32_bf16 v[12:15], v[148:151], v[222:225], v[12:15]
	v_mfma_f32_16x16x32_bf16 v[8:11], v[156:159], v[222:225], v[8:11]
	v_mfma_f32_16x16x32_bf16 v[56:59], v[152:155], v[188:191], v[56:59]
	v_mfma_f32_16x16x32_bf16 v[60:63], v[160:163], v[188:191], v[60:63]
	v_mfma_f32_16x16x32_bf16 v[40:43], v[152:155], v[210:213], v[40:43]
	v_mfma_f32_16x16x32_bf16 v[36:39], v[160:163], v[210:213], v[36:39]
	v_mfma_f32_16x16x32_bf16 v[28:31], v[152:155], v[218:221], v[28:31]
	v_mfma_f32_16x16x32_bf16 v[24:27], v[160:163], v[218:221], v[24:27]
	v_mfma_f32_16x16x32_bf16 v[12:15], v[152:155], v[226:229], v[12:15]
	v_mfma_f32_16x16x32_bf16 v[8:11], v[160:163], v[226:229], v[8:11]
	v_mfma_f32_16x16x32_bf16 v[52:55], v[164:167], v[184:187], v[52:55]
	v_mfma_f32_16x16x32_bf16 v[48:51], v[172:175], v[184:187], v[48:51]
	v_mfma_f32_16x16x32_bf16 v[44:47], v[164:167], v[192:195], v[44:47]
	v_mfma_f32_16x16x32_bf16 v[32:35], v[172:175], v[192:195], v[32:35]
	v_mfma_f32_16x16x32_bf16 v[20:23], v[164:167], v[214:217], v[20:23]
	v_mfma_f32_16x16x32_bf16 v[16:19], v[172:175], v[214:217], v[16:19]
	v_mfma_f32_16x16x32_bf16 v[4:7], v[164:167], v[222:225], v[4:7]
	v_mfma_f32_16x16x32_bf16 v[0:3], v[172:175], v[222:225], v[0:3]
	v_mfma_f32_16x16x32_bf16 v[52:55], v[168:171], v[188:191], v[52:55]
	v_mfma_f32_16x16x32_bf16 v[48:51], v[180:183], v[188:191], v[48:51]
	v_mfma_f32_16x16x32_bf16 v[44:47], v[168:171], v[210:213], v[44:47]
	v_mfma_f32_16x16x32_bf16 v[32:35], v[180:183], v[210:213], v[32:35]
	v_mfma_f32_16x16x32_bf16 v[20:23], v[168:171], v[218:221], v[20:23]
	v_mfma_f32_16x16x32_bf16 v[16:19], v[180:183], v[218:221], v[16:19]
	v_mfma_f32_16x16x32_bf16 v[4:7], v[168:171], v[226:229], v[4:7]
	v_mfma_f32_16x16x32_bf16 v[0:3], v[180:183], v[226:229], v[0:3]
	s_setprio 0
	s_barrier
	s_add_i32 s35, 0, 0x18000
	v_add_u32_e32 v147, s35, v143
	s_add_i32 s36, 0, 0x1c000
	ds_read_b128 v[148:151], v147
	ds_read_b128 v[152:155], v147 offset:1024
	ds_read_b128 v[156:159], v147 offset:2048
	ds_read_b128 v[160:163], v147 offset:3072
	v_add_u32_e32 v147, s36, v143
	ds_read_b128 v[164:167], v147
	ds_read_b128 v[168:171], v147 offset:1024
	ds_read_b128 v[172:175], v147 offset:2048
	ds_read_b128 v[180:183], v147 offset:3072
	s_add_u32 s4, s4, 0x80000
	s_addc_u32 s5, s5, 0
	s_mov_b32 m0, s10
	v_lshl_add_u64 v[234:235], s[4:5], 0, v[132:133]
	ds_read_b128 v[184:187], v145 offset:32768
	ds_read_b128 v[188:191], v145 offset:33792
	ds_read_b128 v[192:195], v145 offset:34816
	ds_read_b128 v[210:213], v145 offset:35840
	ds_read_b128 v[214:217], v145 offset:36864
	ds_read_b128 v[218:221], v145 offset:37888
	ds_read_b128 v[222:225], v145 offset:38912
	ds_read_b128 v[226:229], v145 offset:39936
	global_load_lds_dwordx4 v[234:235], off
	v_lshl_add_u64 v[234:235], s[4:5], 0, v[130:131]
	s_mov_b32 m0, s11
	s_nop 0
	global_load_lds_dwordx4 v[234:235], off
	s_waitcnt vmcnt(8)
	s_waitcnt lgkmcnt(0)
	s_barrier
	s_setprio 1
	s_waitcnt lgkmcnt(0)
	v_mfma_f32_16x16x32_bf16 v[124:127], v[148:151], v[184:187], v[124:127]
	v_mfma_f32_16x16x32_bf16 v[120:123], v[156:159], v[184:187], v[120:123]
	v_mfma_f32_16x16x32_bf16 v[108:111], v[148:151], v[192:195], v[108:111]
	v_mfma_f32_16x16x32_bf16 v[104:107], v[156:159], v[192:195], v[104:107]
	v_mfma_f32_16x16x32_bf16 v[92:95], v[148:151], v[214:217], v[92:95]
	v_mfma_f32_16x16x32_bf16 v[88:91], v[156:159], v[214:217], v[88:91]
	v_mfma_f32_16x16x32_bf16 v[76:79], v[148:151], v[222:225], v[76:79]
	v_mfma_f32_16x16x32_bf16 v[72:75], v[156:159], v[222:225], v[72:75]
	v_mfma_f32_16x16x32_bf16 v[124:127], v[152:155], v[188:191], v[124:127]
	v_mfma_f32_16x16x32_bf16 v[120:123], v[160:163], v[188:191], v[120:123]
	v_mfma_f32_16x16x32_bf16 v[108:111], v[152:155], v[210:213], v[108:111]
	v_mfma_f32_16x16x32_bf16 v[104:107], v[160:163], v[210:213], v[104:107]
	v_mfma_f32_16x16x32_bf16 v[92:95], v[152:155], v[218:221], v[92:95]
	v_mfma_f32_16x16x32_bf16 v[88:91], v[160:163], v[218:221], v[88:91]
	v_mfma_f32_16x16x32_bf16 v[76:79], v[152:155], v[226:229], v[76:79]
	v_mfma_f32_16x16x32_bf16 v[72:75], v[160:163], v[226:229], v[72:75]
	v_mfma_f32_16x16x32_bf16 v[116:119], v[164:167], v[184:187], v[116:119]
	v_mfma_f32_16x16x32_bf16 v[112:115], v[172:175], v[184:187], v[112:115]
	v_mfma_f32_16x16x32_bf16 v[100:103], v[164:167], v[192:195], v[100:103]
	v_mfma_f32_16x16x32_bf16 v[96:99], v[172:175], v[192:195], v[96:99]
	v_mfma_f32_16x16x32_bf16 v[84:87], v[164:167], v[214:217], v[84:87]
	v_mfma_f32_16x16x32_bf16 v[80:83], v[172:175], v[214:217], v[80:83]
	v_mfma_f32_16x16x32_bf16 v[68:71], v[164:167], v[222:225], v[68:71]
	v_mfma_f32_16x16x32_bf16 v[64:67], v[172:175], v[222:225], v[64:67]
	v_mfma_f32_16x16x32_bf16 v[116:119], v[168:171], v[188:191], v[116:119]
	v_mfma_f32_16x16x32_bf16 v[112:115], v[180:183], v[188:191], v[112:115]
	v_mfma_f32_16x16x32_bf16 v[100:103], v[168:171], v[210:213], v[100:103]
	v_mfma_f32_16x16x32_bf16 v[96:99], v[180:183], v[210:213], v[96:99]
	v_mfma_f32_16x16x32_bf16 v[84:87], v[168:171], v[218:221], v[84:87]
	v_mfma_f32_16x16x32_bf16 v[80:83], v[180:183], v[218:221], v[80:83]
	v_mfma_f32_16x16x32_bf16 v[68:71], v[168:171], v[226:229], v[68:71]
	v_mfma_f32_16x16x32_bf16 v[64:67], v[180:183], v[226:229], v[64:67]
	s_setprio 0
	s_barrier
; #define PG8_STAGE(bufoff, gbase, voff) do { _Pragma("unroll") for (int _i = 0; _i < 2; ++_i) \
;         __builtin_amdgcn_global_load_lds((const unsigned*)((const char*)(gbase) + (voff)[_i]), (LAS unsigned*)(lds + (bufoff) + ldsw + _i * 8192), 16, 0, 0); } while (0)
; #define PG8_LDA(dst, b, h) do { _Pragma("unroll") for (int m = 0; m < 4; ++m) _Pragma("unroll") for (int k = 0; k < 2; ++k) dst[m][k] = *(const LAS bf16x8*)(lds + PG8_SA(b, h) + aoff + m * 2048 + k * 1024); } while (0)
; #define PG8_MMA(ai, bj, At, Bt) do { __builtin_amdgcn_s_setprio(1); _Pragma("unroll") for (int m = 0; m < 4; ++m) _Pragma("unroll") for (int n = 0; n < 2; ++n) _Pragma("unroll") for (int k = 0; k < 2; ++k) \
;         acc[ai][bj][m][n] = __builtin_amdgcn_mfma_f32_16x16x32_bf16(Bt[n][k], At[m][k], acc[ai][bj][m][n], 0, 0, 0); __builtin_amdgcn_s_setprio(0); } while (0)
; #define PG8_WAIT_V(n) asm volatile("s_waitcnt vmcnt(" #n ")" ::: "memory")
; #define PG8_WAIT_L(n) asm volatile("s_waitcnt lgkmcnt(" #n ")" ::: "memory")
; #define PG8_BAR __builtin_amdgcn_s_barrier()
; #define PG8_SCHED __builtin_amdgcn_sched_barrier(0)
; template <class Epi>
; __device__ __forceinline__ void gemm_phase(LAS unsigned char* lds, const GemmD g, const Epi& E, int G, int c) {
;     ...
;             PG8_LDA(At, 1, 1); PG8_STAGE(PG8_SB(1, 0), b3, voffB); PG8_STAGE(PG8_SB(1, 1), b3 + hstepB, voffB); PG8_STAGE(PG8_SA(1, 0), a3, voffA);
;             PG8_WAIT_V(8); PG8_WAIT_L(0); PG8_BAR; PG8_MMA(1, 0, At, B0); PG8_MMA(1, 1, At, B1); PG8_BAR; PG8_SCHED;
;         }
;         if (wr == 0) PG8_BAR;
	s_add_i32 s4, s35, s2
	v_lshl_add_u64 v[140:141], v[140:141], 0, s[48:49]
	s_mov_b32 m0, s4
	ds_read_b128 v[184:187], v145 offset:49152
	ds_read_b128 v[188:191], v145 offset:50176
	ds_read_b128 v[192:195], v145 offset:51200
	ds_read_b128 v[210:213], v145 offset:52224
	ds_read_b128 v[214:217], v145 offset:53248
	ds_read_b128 v[218:221], v145 offset:54272
	ds_read_b128 v[222:225], v145 offset:55296
	ds_read_b128 v[226:229], v145 offset:56320
	global_load_lds_dwordx4 v[140:141], off
	s_add_i32 m0, s4, 0x2000
	s_add_u32 s4, s84, 0x80080
	v_lshl_add_u64 v[140:141], v[198:199], 0, s[48:49]
	s_addc_u32 s5, s85, 0
	s_add_i32 s35, s36, s2
	global_load_lds_dwordx4 v[140:141], off
	v_lshl_add_u64 v[140:141], s[4:5], 0, v[178:179]
	s_mov_b32 m0, s35
	s_nop 0
	global_load_lds_dwordx4 v[140:141], off
	v_lshl_add_u64 v[140:141], s[4:5], 0, v[128:129]
	s_add_i32 m0, s35, 0x2000
	s_nop 0
	global_load_lds_dwordx4 v[140:141], off
	v_lshl_add_u64 v[140:141], v[230:231], 0, s[48:49]
	s_mov_b32 m0, s16
	s_nop 0
	global_load_lds_dwordx4 v[140:141], off
	v_lshl_add_u64 v[140:141], v[232:233], 0, s[48:49]
	s_mov_b32 m0, s17
	s_nop 0
	global_load_lds_dwordx4 v[140:141], off
	s_waitcnt vmcnt(8)
	s_waitcnt lgkmcnt(0)
	s_barrier
	s_setprio 1
	s_waitcnt lgkmcnt(0)
	v_mfma_f32_16x16x32_bf16 v[56:59], v[148:151], v[184:187], v[56:59]
	v_mfma_f32_16x16x32_bf16 v[60:63], v[156:159], v[184:187], v[60:63]
	v_mfma_f32_16x16x32_bf16 v[40:43], v[148:151], v[192:195], v[40:43]
	v_mfma_f32_16x16x32_bf16 v[36:39], v[156:159], v[192:195], v[36:39]
	v_mfma_f32_16x16x32_bf16 v[28:31], v[148:151], v[214:217], v[28:31]
	v_mfma_f32_16x16x32_bf16 v[24:27], v[156:159], v[214:217], v[24:27]
	v_mfma_f32_16x16x32_bf16 v[12:15], v[148:151], v[222:225], v[12:15]
	v_mfma_f32_16x16x32_bf16 v[8:11], v[156:159], v[222:225], v[8:11]
	v_mfma_f32_16x16x32_bf16 v[56:59], v[152:155], v[188:191], v[56:59]
	v_mfma_f32_16x16x32_bf16 v[60:63], v[160:163], v[188:191], v[60:63]
	v_mfma_f32_16x16x32_bf16 v[40:43], v[152:155], v[210:213], v[40:43]
	v_mfma_f32_16x16x32_bf16 v[36:39], v[160:163], v[210:213], v[36:39]
	v_mfma_f32_16x16x32_bf16 v[28:31], v[152:155], v[218:221], v[28:31]
	v_mfma_f32_16x16x32_bf16 v[24:27], v[160:163], v[218:221], v[24:27]
	v_mfma_f32_16x16x32_bf16 v[12:15], v[152:155], v[226:229], v[12:15]
	v_mfma_f32_16x16x32_bf16 v[8:11], v[160:163], v[226:229], v[8:11]
	v_mfma_f32_16x16x32_bf16 v[52:55], v[164:167], v[184:187], v[52:55]
	v_mfma_f32_16x16x32_bf16 v[48:51], v[172:175], v[184:187], v[48:51]
	v_mfma_f32_16x16x32_bf16 v[44:47], v[164:167], v[192:195], v[44:47]
	v_mfma_f32_16x16x32_bf16 v[32:35], v[172:175], v[192:195], v[32:35]
	v_mfma_f32_16x16x32_bf16 v[20:23], v[164:167], v[214:217], v[20:23]
	v_mfma_f32_16x16x32_bf16 v[16:19], v[172:175], v[214:217], v[16:19]
	v_mfma_f32_16x16x32_bf16 v[4:7], v[164:167], v[222:225], v[4:7]
	v_mfma_f32_16x16x32_bf16 v[0:3], v[172:175], v[222:225], v[0:3]
	v_mfma_f32_16x16x32_bf16 v[52:55], v[168:171], v[188:191], v[52:55]
	v_mfma_f32_16x16x32_bf16 v[48:51], v[180:183], v[188:191], v[48:51]
	v_mfma_f32_16x16x32_bf16 v[44:47], v[168:171], v[210:213], v[44:47]
	v_mfma_f32_16x16x32_bf16 v[32:35], v[180:183], v[210:213], v[32:35]
	v_mfma_f32_16x16x32_bf16 v[20:23], v[168:171], v[218:221], v[20:23]
	v_mfma_f32_16x16x32_bf16 v[16:19], v[180:183], v[218:221], v[16:19]
	v_mfma_f32_16x16x32_bf16 v[4:7], v[168:171], v[226:229], v[4:7]
	v_mfma_f32_16x16x32_bf16 v[0:3], v[180:183], v[226:229], v[0:3]
	s_setprio 0
	s_barrier
	s_add_i32 s33, s33, 2
	s_add_u32 s86, s86, 0x100
	s_addc_u32 s87, s87, 0
	s_add_u32 s30, s30, 0x100
	s_addc_u32 s31, s31, 0
	s_cmp_gt_u32 s33, 29
	s_cbranch_scc0 .LBB0_224
	s_and_b64 vcc, exec, s[46:47]
	s_cbranch_vccz .LBB0_227
	s_barrier

; #define PG8_STAGE(bufoff, gbase, voff) do { _Pragma("unroll") for (int _i = 0; _i < 2; ++_i) \
;         __builtin_amdgcn_global_load_lds((const unsigned*)((const char*)(gbase) + (voff)[_i]), (LAS unsigned*)(lds + (bufoff) + ldsw + _i * 8192), 16, 0, 0); } while (0)
; #define PG8_LDA(dst, b, h) do { _Pragma("unroll") for (int m = 0; m < 4; ++m) _Pragma("unroll") for (int k = 0; k < 2; ++k) dst[m][k] = *(const LAS bf16x8*)(lds + PG8_SA(b, h) + aoff + m * 2048 + k * 1024); } while (0)
; #define PG8_MMA(ai, bj, At, Bt) do { __builtin_amdgcn_s_setprio(1); _Pragma("unroll") for (int m = 0; m < 4; ++m) _Pragma("unroll") for (int n = 0; n < 2; ++n) _Pragma("unroll") for (int k = 0; k < 2; ++k) \
;         acc[ai][bj][m][n] = __builtin_amdgcn_mfma_f32_16x16x32_bf16(Bt[n][k], At[m][k], acc[ai][bj][m][n], 0, 0, 0); __builtin_amdgcn_s_setprio(0); } while (0)
; #define PG8_WAIT_V(n) asm volatile("s_waitcnt vmcnt(" #n ")" ::: "memory")
; #define PG8_WAIT_L(n) asm volatile("s_waitcnt lgkmcnt(" #n ")" ::: "memory")
; #define PG8_BAR __builtin_amdgcn_s_barrier()
; #define PG8_SCHED __builtin_amdgcn_sched_barrier(0)
; template <class Epi>
; __device__ __forceinline__ void gemm_phase(LAS unsigned char* lds, const GemmD g, const Epi& E, int G, int c) {
;     ...
;             PG8_WAIT_V(8); PG8_WAIT_L(0); PG8_BAR; PG8_MMA(0, 0, At, B0); PG8_MMA(0, 1, At, B1); PG8_BAR; PG8_SCHED;
;             PG8_LDA(At, 0, 1); PG8_STAGE(PG8_SB(0, 0), b2, voffB); PG8_STAGE(PG8_SB(0, 1), b2 + hstepB, voffB); PG8_STAGE(PG8_SA(0, 0), a2, voffA);
;             PG8_WAIT_V(8); PG8_WAIT_L(0); PG8_BAR; PG8_MMA(1, 0, At, B0); PG8_MMA(1, 1, At, B1); PG8_BAR; PG8_SCHED;
.Lrw_Glu_0_d:
	s_waitcnt lgkmcnt(0)
	s_barrier
	s_setprio 1
	s_waitcnt lgkmcnt(0)
	v_mfma_f32_16x16x32_bf16 v[140:143], v[24:27], v[160:163], v[140:143]
	v_mfma_f32_16x16x32_bf16 v[136:139], v[36:39], v[160:163], v[136:139]
	v_mfma_f32_16x16x32_bf16 v[124:127], v[24:27], v[168:171], v[124:127]
	v_mfma_f32_16x16x32_bf16 v[120:123], v[36:39], v[168:171], v[120:123]
	v_mfma_f32_16x16x32_bf16 v[108:111], v[24:27], v[190:193], v[108:111]
	v_mfma_f32_16x16x32_bf16 v[104:107], v[36:39], v[190:193], v[104:107]
	v_mfma_f32_16x16x32_bf16 v[92:95], v[24:27], v[218:221], v[92:95]
	v_mfma_f32_16x16x32_bf16 v[88:91], v[36:39], v[218:221], v[88:91]
	v_mfma_f32_16x16x32_bf16 v[140:143], v[28:31], v[164:167], v[140:143]
	v_mfma_f32_16x16x32_bf16 v[136:139], v[44:47], v[164:167], v[136:139]
	v_mfma_f32_16x16x32_bf16 v[124:127], v[28:31], v[172:175], v[124:127]
	v_mfma_f32_16x16x32_bf16 v[120:123], v[44:47], v[172:175], v[120:123]
	v_mfma_f32_16x16x32_bf16 v[108:111], v[28:31], v[214:217], v[108:111]
	v_mfma_f32_16x16x32_bf16 v[104:107], v[44:47], v[214:217], v[104:107]
	v_mfma_f32_16x16x32_bf16 v[92:95], v[28:31], v[222:225], v[92:95]
	v_mfma_f32_16x16x32_bf16 v[88:91], v[44:47], v[222:225], v[88:91]
	v_mfma_f32_16x16x32_bf16 v[132:135], v[144:147], v[160:163], v[132:135]
	v_mfma_f32_16x16x32_bf16 v[128:131], v[152:155], v[160:163], v[128:131]
	v_mfma_f32_16x16x32_bf16 v[116:119], v[144:147], v[168:171], v[116:119]
	v_mfma_f32_16x16x32_bf16 v[112:115], v[152:155], v[168:171], v[112:115]
	v_mfma_f32_16x16x32_bf16 v[100:103], v[144:147], v[190:193], v[100:103]
	v_mfma_f32_16x16x32_bf16 v[96:99], v[152:155], v[190:193], v[96:99]
	v_mfma_f32_16x16x32_bf16 v[84:87], v[144:147], v[218:221], v[84:87]
	v_mfma_f32_16x16x32_bf16 v[80:83], v[152:155], v[218:221], v[80:83]
	v_mfma_f32_16x16x32_bf16 v[132:135], v[148:151], v[164:167], v[132:135]
	v_mfma_f32_16x16x32_bf16 v[128:131], v[156:159], v[164:167], v[128:131]
	v_mfma_f32_16x16x32_bf16 v[116:119], v[148:151], v[172:175], v[116:119]
	v_mfma_f32_16x16x32_bf16 v[112:115], v[156:159], v[172:175], v[112:115]
	v_mfma_f32_16x16x32_bf16 v[100:103], v[148:151], v[214:217], v[100:103]
	v_mfma_f32_16x16x32_bf16 v[96:99], v[156:159], v[214:217], v[96:99]
	v_mfma_f32_16x16x32_bf16 v[84:87], v[148:151], v[222:225], v[84:87]
	v_mfma_f32_16x16x32_bf16 v[80:83], v[156:159], v[222:225], v[80:83]
	s_setprio 0
	s_barrier
	s_add_i32 s28, s28, s16
	v_lshl_add_u64 v[194:195], s[88:89], 0, v[178:179]
	s_mov_b32 m0, s28
	ds_read_b128 v[160:163], v212 offset:16384
	ds_read_b128 v[164:167], v212 offset:17408
	ds_read_b128 v[168:171], v212 offset:18432
	ds_read_b128 v[172:175], v212 offset:19456
	ds_read_b128 v[190:193], v212 offset:20480
	ds_read_b128 v[214:217], v212 offset:21504
	ds_read_b128 v[218:221], v212 offset:22528
	ds_read_b128 v[222:225], v212 offset:23552
	global_load_lds_dwordx4 v[194:195], off
	s_add_i32 m0, s28, 0x2000
	s_add_u32 s28, s88, 0x80000
	v_lshl_add_u64 v[198:199], s[88:89], 0, v[180:181]
	s_addc_u32 s29, s89, 0
	s_add_i32 s31, s31, s16
	global_load_lds_dwordx4 v[198:199], off
	v_lshl_add_u64 v[226:227], s[28:29], 0, v[178:179]
	s_mov_b32 m0, s31
	v_lshl_add_u64 v[228:229], s[4:5], 0, v[182:183]
	global_load_lds_dwordx4 v[226:227], off
	v_lshl_add_u64 v[226:227], s[28:29], 0, v[180:181]
	s_add_i32 m0, s31, 0x2000
	s_nop 0
	global_load_lds_dwordx4 v[226:227], off
	v_lshl_add_u64 v[226:227], s[4:5], 0, v[184:185]
	s_mov_b32 m0, s23
	s_nop 0
	global_load_lds_dwordx4 v[226:227], off
	s_mov_b32 m0, s26
	s_nop 0
	global_load_lds_dwordx4 v[228:229], off
	s_cmp_lg_u32 s99, 0
	s_cbranch_scc1 .Lrw_Glu_1_r
	s_waitcnt vmcnt(8)
	s_branch .Lrw_Glu_1_d

; #define PG8_STAGE(bufoff, gbase, voff) do { _Pragma("unroll") for (int _i = 0; _i < 2; ++_i) \
;         __builtin_amdgcn_global_load_lds((const unsigned*)((const char*)(gbase) + (voff)[_i]), (LAS unsigned*)(lds + (bufoff) + ldsw + _i * 8192), 16, 0, 0); } while (0)
; #define PG8_LDA(dst, b, h) do { _Pragma("unroll") for (int m = 0; m < 4; ++m) _Pragma("unroll") for (int k = 0; k < 2; ++k) dst[m][k] = *(const LAS bf16x8*)(lds + PG8_SA(b, h) + aoff + m * 2048 + k * 1024); } while (0)
; #define PG8_LDB(dst, b, h) do { _Pragma("unroll") for (int n = 0; n < 2; ++n) _Pragma("unroll") for (int k = 0; k < 2; ++k) dst[n][k] = *(const LAS bf16x8*)(lds + PG8_SB(b, h) + boff + n * 2048 + k * 1024); } while (0)
; #define PG8_MMA(ai, bj, At, Bt) do { __builtin_amdgcn_s_setprio(1); _Pragma("unroll") for (int m = 0; m < 4; ++m) _Pragma("unroll") for (int n = 0; n < 2; ++n) _Pragma("unroll") for (int k = 0; k < 2; ++k) \
;         acc[ai][bj][m][n] = __builtin_amdgcn_mfma_f32_16x16x32_bf16(Bt[n][k], At[m][k], acc[ai][bj][m][n], 0, 0, 0); __builtin_amdgcn_s_setprio(0); } while (0)
; #define PG8_WAIT_V(n) asm volatile("s_waitcnt vmcnt(" #n ")" ::: "memory")
; #define PG8_WAIT_L(n) asm volatile("s_waitcnt lgkmcnt(" #n ")" ::: "memory")
; #define PG8_BAR __builtin_amdgcn_s_barrier()
; #define PG8_SCHED __builtin_amdgcn_sched_barrier(0)
; template <class Epi>
; __device__ __forceinline__ void gemm_phase(LAS unsigned char* lds, const GemmD g, const Epi& E, int G, int c) {
;     ...
;             PG8_WAIT_V(8); PG8_WAIT_L(0); PG8_BAR; PG8_MMA(1, 0, At, B0); PG8_MMA(1, 1, At, B1); PG8_BAR; PG8_SCHED;
;             PG8_LDB(B0, 1, 0); PG8_LDB(B1, 1, 1); PG8_SCHED; PG8_LDA(At, 1, 0); PG8_STAGE(PG8_SA(0, 1), a2 + hstepA, voffA);
;             PG8_WAIT_V(8); PG8_WAIT_L(0); PG8_BAR; PG8_MMA(0, 0, At, B0); PG8_MMA(0, 1, At, B1); PG8_BAR; PG8_SCHED;
.Lrw_Glu_1_d:
	s_waitcnt lgkmcnt(0)
	s_barrier
	s_setprio 1
	s_waitcnt lgkmcnt(0)
	v_mfma_f32_16x16x32_bf16 v[76:79], v[24:27], v[160:163], v[76:79]
	v_mfma_f32_16x16x32_bf16 v[72:75], v[36:39], v[160:163], v[72:75]
	v_mfma_f32_16x16x32_bf16 v[60:63], v[24:27], v[168:171], v[60:63]
	v_mfma_f32_16x16x32_bf16 v[56:59], v[36:39], v[168:171], v[56:59]
	v_mfma_f32_16x16x32_bf16 v[40:43], v[24:27], v[190:193], v[40:43]
	v_mfma_f32_16x16x32_bf16 v[32:35], v[36:39], v[190:193], v[32:35]
	v_mfma_f32_16x16x32_bf16 v[12:15], v[24:27], v[218:221], v[12:15]
	v_mfma_f32_16x16x32_bf16 v[8:11], v[36:39], v[218:221], v[8:11]
	v_mfma_f32_16x16x32_bf16 v[76:79], v[28:31], v[164:167], v[76:79]
	v_mfma_f32_16x16x32_bf16 v[72:75], v[44:47], v[164:167], v[72:75]
	v_mfma_f32_16x16x32_bf16 v[60:63], v[28:31], v[172:175], v[60:63]
	v_mfma_f32_16x16x32_bf16 v[56:59], v[44:47], v[172:175], v[56:59]
	v_mfma_f32_16x16x32_bf16 v[40:43], v[28:31], v[214:217], v[40:43]
	v_mfma_f32_16x16x32_bf16 v[32:35], v[44:47], v[214:217], v[32:35]
	v_mfma_f32_16x16x32_bf16 v[12:15], v[28:31], v[222:225], v[12:15]
	v_mfma_f32_16x16x32_bf16 v[8:11], v[44:47], v[222:225], v[8:11]
	v_mfma_f32_16x16x32_bf16 v[20:23], v[144:147], v[190:193], v[20:23]
	v_mfma_f32_16x16x32_bf16 v[16:19], v[152:155], v[190:193], v[16:19]
	v_mfma_f32_16x16x32_bf16 v[4:7], v[144:147], v[218:221], v[4:7]
	v_mfma_f32_16x16x32_bf16 v[0:3], v[152:155], v[218:221], v[0:3]
	v_mfma_f32_16x16x32_bf16 v[24:27], v[144:147], v[160:163], v[68:71]
	v_mfma_f32_16x16x32_bf16 v[28:31], v[152:155], v[160:163], v[64:67]
	v_mfma_f32_16x16x32_bf16 v[36:39], v[144:147], v[168:171], v[52:55]
	v_mfma_f32_16x16x32_bf16 v[44:47], v[152:155], v[168:171], v[48:51]
	v_mfma_f32_16x16x32_bf16 v[20:23], v[148:151], v[214:217], v[20:23]
	v_mfma_f32_16x16x32_bf16 v[16:19], v[156:159], v[214:217], v[16:19]
	v_mfma_f32_16x16x32_bf16 v[4:7], v[148:151], v[222:225], v[4:7]
	v_mfma_f32_16x16x32_bf16 v[0:3], v[156:159], v[222:225], v[0:3]
	v_mfma_f32_16x16x32_bf16 v[24:27], v[148:151], v[164:167], v[24:27]
	v_mfma_f32_16x16x32_bf16 v[28:31], v[156:159], v[164:167], v[28:31]
	v_mfma_f32_16x16x32_bf16 v[36:39], v[148:151], v[172:175], v[36:39]
	v_mfma_f32_16x16x32_bf16 v[44:47], v[156:159], v[172:175], v[44:47]
	s_setprio 0
	s_barrier
	s_add_i32 s28, 0, 0x18000
	s_add_i32 s29, 0, 0x1c000
	v_add_u32_e32 v68, s28, v210
	v_add_u32_e32 v156, s29, v210
	ds_read_b128 v[48:51], v68
	ds_read_b128 v[52:55], v68 offset:1024
	ds_read_b128 v[64:67], v68 offset:2048
	ds_read_b128 v[68:71], v68 offset:3072
	ds_read_b128 v[144:147], v156
	ds_read_b128 v[148:151], v156 offset:1024
	ds_read_b128 v[152:155], v156 offset:2048
	ds_read_b128 v[156:159], v156 offset:3072
	s_add_u32 s4, s4, 0x80000
	s_addc_u32 s5, s5, 0
	s_mov_b32 m0, s30
	v_lshl_add_u64 v[230:231], s[4:5], 0, v[184:185]
	ds_read_b128 v[160:163], v212 offset:32768
	ds_read_b128 v[164:167], v212 offset:33792
	ds_read_b128 v[168:171], v212 offset:34816
	ds_read_b128 v[172:175], v212 offset:35840
	ds_read_b128 v[190:193], v212 offset:36864
	ds_read_b128 v[214:217], v212 offset:37888
	ds_read_b128 v[218:221], v212 offset:38912
	ds_read_b128 v[222:225], v212 offset:39936
	global_load_lds_dwordx4 v[230:231], off
	v_lshl_add_u64 v[230:231], s[4:5], 0, v[182:183]
	s_mov_b32 m0, s35
	s_nop 0
	global_load_lds_dwordx4 v[230:231], off
	s_waitcnt vmcnt(8)
	s_waitcnt lgkmcnt(0)
	s_barrier
	s_setprio 1
	s_waitcnt lgkmcnt(0)
	v_mfma_f32_16x16x32_bf16 v[140:143], v[48:51], v[160:163], v[140:143]
	v_mfma_f32_16x16x32_bf16 v[136:139], v[64:67], v[160:163], v[136:139]
	v_mfma_f32_16x16x32_bf16 v[124:127], v[48:51], v[168:171], v[124:127]
	v_mfma_f32_16x16x32_bf16 v[120:123], v[64:67], v[168:171], v[120:123]
	v_mfma_f32_16x16x32_bf16 v[108:111], v[48:51], v[190:193], v[108:111]
	v_mfma_f32_16x16x32_bf16 v[104:107], v[64:67], v[190:193], v[104:107]
	v_mfma_f32_16x16x32_bf16 v[92:95], v[48:51], v[218:221], v[92:95]
	v_mfma_f32_16x16x32_bf16 v[88:91], v[64:67], v[218:221], v[88:91]
	v_mfma_f32_16x16x32_bf16 v[140:143], v[52:55], v[164:167], v[140:143]
	v_mfma_f32_16x16x32_bf16 v[136:139], v[68:71], v[164:167], v[136:139]
	v_mfma_f32_16x16x32_bf16 v[124:127], v[52:55], v[172:175], v[124:127]
	v_mfma_f32_16x16x32_bf16 v[120:123], v[68:71], v[172:175], v[120:123]
	v_mfma_f32_16x16x32_bf16 v[108:111], v[52:55], v[214:217], v[108:111]
	v_mfma_f32_16x16x32_bf16 v[104:107], v[68:71], v[214:217], v[104:107]
	v_mfma_f32_16x16x32_bf16 v[92:95], v[52:55], v[222:225], v[92:95]
	v_mfma_f32_16x16x32_bf16 v[88:91], v[68:71], v[222:225], v[88:91]
	v_mfma_f32_16x16x32_bf16 v[132:135], v[144:147], v[160:163], v[132:135]
	v_mfma_f32_16x16x32_bf16 v[128:131], v[152:155], v[160:163], v[128:131]
	v_mfma_f32_16x16x32_bf16 v[116:119], v[144:147], v[168:171], v[116:119]
	v_mfma_f32_16x16x32_bf16 v[112:115], v[152:155], v[168:171], v[112:115]
	v_mfma_f32_16x16x32_bf16 v[100:103], v[144:147], v[190:193], v[100:103]
	v_mfma_f32_16x16x32_bf16 v[96:99], v[152:155], v[190:193], v[96:99]
	v_mfma_f32_16x16x32_bf16 v[84:87], v[144:147], v[218:221], v[84:87]
	v_mfma_f32_16x16x32_bf16 v[80:83], v[152:155], v[218:221], v[80:83]
	v_mfma_f32_16x16x32_bf16 v[132:135], v[148:151], v[164:167], v[132:135]
	v_mfma_f32_16x16x32_bf16 v[128:131], v[156:159], v[164:167], v[128:131]
	v_mfma_f32_16x16x32_bf16 v[116:119], v[148:151], v[172:175], v[116:119]
	v_mfma_f32_16x16x32_bf16 v[112:115], v[156:159], v[172:175], v[112:115]
	v_mfma_f32_16x16x32_bf16 v[100:103], v[148:151], v[214:217], v[100:103]
	v_mfma_f32_16x16x32_bf16 v[96:99], v[156:159], v[214:217], v[96:99]
	v_mfma_f32_16x16x32_bf16 v[84:87], v[148:151], v[222:225], v[84:87]
	v_mfma_f32_16x16x32_bf16 v[80:83], v[156:159], v[222:225], v[80:83]
	s_setprio 0
	s_barrier
; #define PG8_STAGE(bufoff, gbase, voff) do { _Pragma("unroll") for (int _i = 0; _i < 2; ++_i) \
;         __builtin_amdgcn_global_load_lds((const unsigned*)((const char*)(gbase) + (voff)[_i]), (LAS unsigned*)(lds + (bufoff) + ldsw + _i * 8192), 16, 0, 0); } while (0)
; #define PG8_LDA(dst, b, h) do { _Pragma("unroll") for (int m = 0; m < 4; ++m) _Pragma("unroll") for (int k = 0; k < 2; ++k) dst[m][k] = *(const LAS bf16x8*)(lds + PG8_SA(b, h) + aoff + m * 2048 + k * 1024); } while (0)
; #define PG8_MMA(ai, bj, At, Bt) do { __builtin_amdgcn_s_setprio(1); _Pragma("unroll") for (int m = 0; m < 4; ++m) _Pragma("unroll") for (int n = 0; n < 2; ++n) _Pragma("unroll") for (int k = 0; k < 2; ++k) \
;         acc[ai][bj][m][n] = __builtin_amdgcn_mfma_f32_16x16x32_bf16(Bt[n][k], At[m][k], acc[ai][bj][m][n], 0, 0, 0); __builtin_amdgcn_s_setprio(0); } while (0)
; #define PG8_WAIT_V(n) asm volatile("s_waitcnt vmcnt(" #n ")" ::: "memory")
; #define PG8_WAIT_L(n) asm volatile("s_waitcnt lgkmcnt(" #n ")" ::: "memory")
; #define PG8_BAR __builtin_amdgcn_s_barrier()
; #define PG8_SCHED __builtin_amdgcn_sched_barrier(0)
; template <class Epi>
; __device__ __forceinline__ void gemm_phase(LAS unsigned char* lds, const GemmD g, const Epi& E, int G, int c) {
;     ...
;             PG8_LDA(At, 1, 1); PG8_STAGE(PG8_SB(1, 0), b3, voffB); PG8_STAGE(PG8_SB(1, 1), b3 + hstepB, voffB); PG8_STAGE(PG8_SA(1, 0), a3, voffA);
;             PG8_WAIT_V(8); PG8_WAIT_L(0); PG8_BAR; PG8_MMA(1, 0, At, B0); PG8_MMA(1, 1, At, B1); PG8_BAR; PG8_SCHED;
;         }
;         if (wr == 0) PG8_BAR;
	s_add_i32 s4, s28, s16
	v_lshl_add_u64 v[194:195], v[194:195], 0, s[48:49]
	s_mov_b32 m0, s4
	ds_read_b128 v[160:163], v212 offset:49152
	ds_read_b128 v[164:167], v212 offset:50176
	ds_read_b128 v[168:171], v212 offset:51200
	ds_read_b128 v[172:175], v212 offset:52224
	ds_read_b128 v[190:193], v212 offset:53248
	ds_read_b128 v[214:217], v212 offset:54272
	ds_read_b128 v[218:221], v212 offset:55296
	ds_read_b128 v[222:225], v212 offset:56320
	global_load_lds_dwordx4 v[194:195], off
	s_add_i32 m0, s4, 0x2000
	s_add_u32 s4, s88, 0x80080
	v_lshl_add_u64 v[194:195], v[198:199], 0, s[48:49]
	s_addc_u32 s5, s89, 0
	s_add_i32 s28, s29, s16
	global_load_lds_dwordx4 v[194:195], off
	v_lshl_add_u64 v[194:195], s[4:5], 0, v[178:179]
	s_mov_b32 m0, s28
	s_nop 0
	global_load_lds_dwordx4 v[194:195], off
	v_lshl_add_u64 v[194:195], s[4:5], 0, v[180:181]
	s_add_i32 m0, s28, 0x2000
	s_nop 0
	global_load_lds_dwordx4 v[194:195], off
	v_lshl_add_u64 v[194:195], v[226:227], 0, s[48:49]
	s_mov_b32 m0, s36
	s_nop 0
	global_load_lds_dwordx4 v[194:195], off
	v_lshl_add_u64 v[194:195], v[228:229], 0, s[48:49]
	s_mov_b32 m0, s90
	s_nop 0
	global_load_lds_dwordx4 v[194:195], off
	s_waitcnt vmcnt(8)
	s_waitcnt lgkmcnt(0)
	s_barrier
	s_setprio 1
	s_waitcnt lgkmcnt(0)
	v_mfma_f32_16x16x32_bf16 v[76:79], v[48:51], v[160:163], v[76:79]
	v_mfma_f32_16x16x32_bf16 v[72:75], v[64:67], v[160:163], v[72:75]
	v_mfma_f32_16x16x32_bf16 v[60:63], v[48:51], v[168:171], v[60:63]
	v_mfma_f32_16x16x32_bf16 v[56:59], v[64:67], v[168:171], v[56:59]
	v_mfma_f32_16x16x32_bf16 v[40:43], v[48:51], v[190:193], v[40:43]
	v_mfma_f32_16x16x32_bf16 v[32:35], v[64:67], v[190:193], v[32:35]
	v_mfma_f32_16x16x32_bf16 v[12:15], v[48:51], v[218:221], v[12:15]
	v_mfma_f32_16x16x32_bf16 v[8:11], v[64:67], v[218:221], v[8:11]
	v_mfma_f32_16x16x32_bf16 v[76:79], v[52:55], v[164:167], v[76:79]
	v_mfma_f32_16x16x32_bf16 v[72:75], v[68:71], v[164:167], v[72:75]
	v_mfma_f32_16x16x32_bf16 v[60:63], v[52:55], v[172:175], v[60:63]
	v_mfma_f32_16x16x32_bf16 v[56:59], v[68:71], v[172:175], v[56:59]
	v_mfma_f32_16x16x32_bf16 v[40:43], v[52:55], v[214:217], v[40:43]
	v_mfma_f32_16x16x32_bf16 v[32:35], v[68:71], v[214:217], v[32:35]
	v_mfma_f32_16x16x32_bf16 v[12:15], v[52:55], v[222:225], v[12:15]
	v_mfma_f32_16x16x32_bf16 v[8:11], v[68:71], v[222:225], v[8:11]
	v_mfma_f32_16x16x32_bf16 v[24:27], v[144:147], v[160:163], v[24:27]
	v_mfma_f32_16x16x32_bf16 v[68:71], v[148:151], v[164:167], v[24:27]
	v_mfma_f32_16x16x32_bf16 v[24:27], v[152:155], v[160:163], v[28:31]
	v_mfma_f32_16x16x32_bf16 v[64:67], v[156:159], v[164:167], v[24:27]
	v_mfma_f32_16x16x32_bf16 v[24:27], v[144:147], v[168:171], v[36:39]
	v_mfma_f32_16x16x32_bf16 v[52:55], v[148:151], v[172:175], v[24:27]
	v_mfma_f32_16x16x32_bf16 v[24:27], v[152:155], v[168:171], v[44:47]
	v_mfma_f32_16x16x32_bf16 v[20:23], v[144:147], v[190:193], v[20:23]
	v_mfma_f32_16x16x32_bf16 v[16:19], v[152:155], v[190:193], v[16:19]
	v_mfma_f32_16x16x32_bf16 v[4:7], v[144:147], v[218:221], v[4:7]
	v_mfma_f32_16x16x32_bf16 v[0:3], v[152:155], v[218:221], v[0:3]
	v_mfma_f32_16x16x32_bf16 v[48:51], v[156:159], v[172:175], v[24:27]
	v_mfma_f32_16x16x32_bf16 v[20:23], v[148:151], v[214:217], v[20:23]
	v_mfma_f32_16x16x32_bf16 v[16:19], v[156:159], v[214:217], v[16:19]
	v_mfma_f32_16x16x32_bf16 v[4:7], v[148:151], v[222:225], v[4:7]
	v_mfma_f32_16x16x32_bf16 v[0:3], v[156:159], v[222:225], v[0:3]
	s_setprio 0
	s_barrier
	s_add_i32 s27, s27, 2
	s_add_u32 s42, s42, 0x100
	s_addc_u32 s43, s43, 0
	s_add_u32 s19, s19, 0x100
	s_addc_u32 s22, s22, 0
	s_cmp_gt_u32 s27, 29
	s_cbranch_scc0 .LBB0_271
	s_and_b64 vcc, exec, s[66:67]
	s_cbranch_vccz .LBB0_274
	s_barrier

; #define PG8_STAGE(bufoff, gbase, voff) do { _Pragma("unroll") for (int _i = 0; _i < 2; ++_i) \
;         __builtin_amdgcn_global_load_lds((const unsigned*)((const char*)(gbase) + (voff)[_i]), (LAS unsigned*)(lds + (bufoff) + ldsw + _i * 8192), 16, 0, 0); } while (0)
; #define PG8_LDA(dst, b, h) do { _Pragma("unroll") for (int m = 0; m < 4; ++m) _Pragma("unroll") for (int k = 0; k < 2; ++k) dst[m][k] = *(const LAS bf16x8*)(lds + PG8_SA(b, h) + aoff + m * 2048 + k * 1024); } while (0)
; #define PG8_MMA(ai, bj, At, Bt) do { __builtin_amdgcn_s_setprio(1); _Pragma("unroll") for (int m = 0; m < 4; ++m) _Pragma("unroll") for (int n = 0; n < 2; ++n) _Pragma("unroll") for (int k = 0; k < 2; ++k) \
;         acc[ai][bj][m][n] = __builtin_amdgcn_mfma_f32_16x16x32_bf16(Bt[n][k], At[m][k], acc[ai][bj][m][n], 0, 0, 0); __builtin_amdgcn_s_setprio(0); } while (0)
; #define PG8_WAIT_V(n) asm volatile("s_waitcnt vmcnt(" #n ")" ::: "memory")
; #define PG8_WAIT_L(n) asm volatile("s_waitcnt lgkmcnt(" #n ")" ::: "memory")
; #define PG8_BAR __builtin_amdgcn_s_barrier()
; #define PG8_SCHED __builtin_amdgcn_sched_barrier(0)
; template <class Epi>
; __device__ __forceinline__ void gemm_phase(LAS unsigned char* lds, const GemmD g, const Epi& E, int G, int c) {
;     ...
;             PG8_WAIT_V(8); PG8_WAIT_L(0); PG8_BAR; PG8_MMA(0, 0, At, B0); PG8_MMA(0, 1, At, B1); PG8_BAR; PG8_SCHED;
;             PG8_LDA(At, 0, 1); PG8_STAGE(PG8_SB(0, 0), b2, voffB); PG8_STAGE(PG8_SB(0, 1), b2 + hstepB, voffB); PG8_STAGE(PG8_SA(0, 0), a2, voffA);
;             PG8_WAIT_V(8); PG8_WAIT_L(0); PG8_BAR; PG8_MMA(1, 0, At, B0); PG8_MMA(1, 1, At, B1); PG8_BAR; PG8_SCHED;
.Lrw_PV_0_d:
	s_waitcnt lgkmcnt(0)
	s_barrier
	s_setprio 1
	s_waitcnt lgkmcnt(0)
	v_mfma_f32_16x16x32_bf16 v[124:127], v[146:149], v[184:187], v[124:127]
	v_mfma_f32_16x16x32_bf16 v[120:123], v[154:157], v[184:187], v[120:123]
	v_mfma_f32_16x16x32_bf16 v[112:115], v[146:149], v[192:195], v[112:115]
	v_mfma_f32_16x16x32_bf16 v[104:107], v[154:157], v[192:195], v[104:107]
	v_mfma_f32_16x16x32_bf16 v[96:99], v[146:149], v[214:217], v[96:99]
	v_mfma_f32_16x16x32_bf16 v[88:91], v[154:157], v[214:217], v[88:91]
	v_mfma_f32_16x16x32_bf16 v[80:83], v[146:149], v[222:225], v[80:83]
	v_mfma_f32_16x16x32_bf16 v[72:75], v[154:157], v[222:225], v[72:75]
	v_mfma_f32_16x16x32_bf16 v[124:127], v[150:153], v[188:191], v[124:127]
	v_mfma_f32_16x16x32_bf16 v[120:123], v[158:161], v[188:191], v[120:123]
	v_mfma_f32_16x16x32_bf16 v[112:115], v[150:153], v[210:213], v[112:115]
	v_mfma_f32_16x16x32_bf16 v[104:107], v[158:161], v[210:213], v[104:107]
	v_mfma_f32_16x16x32_bf16 v[96:99], v[150:153], v[218:221], v[96:99]
	v_mfma_f32_16x16x32_bf16 v[88:91], v[158:161], v[218:221], v[88:91]
	v_mfma_f32_16x16x32_bf16 v[80:83], v[150:153], v[226:229], v[80:83]
	v_mfma_f32_16x16x32_bf16 v[72:75], v[158:161], v[226:229], v[72:75]
	v_mfma_f32_16x16x32_bf16 v[116:119], v[162:165], v[184:187], v[116:119]
	v_mfma_f32_16x16x32_bf16 v[108:111], v[170:173], v[184:187], v[108:111]
	v_mfma_f32_16x16x32_bf16 v[100:103], v[162:165], v[192:195], v[100:103]
	v_mfma_f32_16x16x32_bf16 v[92:95], v[170:173], v[192:195], v[92:95]
	v_mfma_f32_16x16x32_bf16 v[84:87], v[162:165], v[214:217], v[84:87]
	v_mfma_f32_16x16x32_bf16 v[76:79], v[170:173], v[214:217], v[76:79]
	v_mfma_f32_16x16x32_bf16 v[68:71], v[162:165], v[222:225], v[68:71]
	v_mfma_f32_16x16x32_bf16 v[64:67], v[170:173], v[222:225], v[64:67]
	v_mfma_f32_16x16x32_bf16 v[116:119], v[166:169], v[188:191], v[116:119]
	v_mfma_f32_16x16x32_bf16 v[108:111], v[180:183], v[188:191], v[108:111]
	v_mfma_f32_16x16x32_bf16 v[100:103], v[166:169], v[210:213], v[100:103]
	v_mfma_f32_16x16x32_bf16 v[92:95], v[180:183], v[210:213], v[92:95]
	v_mfma_f32_16x16x32_bf16 v[84:87], v[166:169], v[218:221], v[84:87]
	v_mfma_f32_16x16x32_bf16 v[76:79], v[180:183], v[218:221], v[76:79]
	v_mfma_f32_16x16x32_bf16 v[68:71], v[166:169], v[226:229], v[68:71]
	v_mfma_f32_16x16x32_bf16 v[64:67], v[180:183], v[226:229], v[64:67]
	s_setprio 0
	s_barrier
	s_add_i32 s31, s31, s2
	v_lshl_add_u64 v[138:139], s[84:85], 0, v[178:179]
	s_mov_b32 m0, s31
	ds_read_b128 v[184:187], v143 offset:16384
	ds_read_b128 v[188:191], v143 offset:17408
	ds_read_b128 v[192:195], v143 offset:18432
	ds_read_b128 v[210:213], v143 offset:19456
	ds_read_b128 v[214:217], v143 offset:20480
	ds_read_b128 v[218:221], v143 offset:21504
	ds_read_b128 v[222:225], v143 offset:22528
	ds_read_b128 v[226:229], v143 offset:23552
	global_load_lds_dwordx4 v[138:139], off
	s_add_i32 m0, s31, 0x2000
	s_add_u32 s38, s84, 0x400000
	v_lshl_add_u64 v[174:175], s[84:85], 0, v[128:129]
	s_addc_u32 s39, s85, 0
	s_add_i32 s31, s33, s2
	global_load_lds_dwordx4 v[174:175], off
	v_lshl_add_u64 v[198:199], s[38:39], 0, v[178:179]
	s_mov_b32 m0, s31
	v_lshl_add_u64 v[230:231], s[4:5], 0, v[130:131]
	global_load_lds_dwordx4 v[198:199], off
	v_lshl_add_u64 v[198:199], s[38:39], 0, v[128:129]
	s_add_i32 m0, s31, 0x2000
	s_nop 0
	global_load_lds_dwordx4 v[198:199], off
	v_lshl_add_u64 v[198:199], s[4:5], 0, v[132:133]
	s_mov_b32 m0, s6
	s_nop 0
	global_load_lds_dwordx4 v[198:199], off
	s_mov_b32 m0, s9
	s_nop 0
	global_load_lds_dwordx4 v[230:231], off
	s_cmp_lg_u32 s99, 0
	s_cbranch_scc1 .Lrw_PV_1_r
	s_waitcnt vmcnt(8)
	s_branch .Lrw_PV_1_d

; #define PG8_STAGE(bufoff, gbase, voff) do { _Pragma("unroll") for (int _i = 0; _i < 2; ++_i) \
;         __builtin_amdgcn_global_load_lds((const unsigned*)((const char*)(gbase) + (voff)[_i]), (LAS unsigned*)(lds + (bufoff) + ldsw + _i * 8192), 16, 0, 0); } while (0)
; #define PG8_LDA(dst, b, h) do { _Pragma("unroll") for (int m = 0; m < 4; ++m) _Pragma("unroll") for (int k = 0; k < 2; ++k) dst[m][k] = *(const LAS bf16x8*)(lds + PG8_SA(b, h) + aoff + m * 2048 + k * 1024); } while (0)
; #define PG8_LDB(dst, b, h) do { _Pragma("unroll") for (int n = 0; n < 2; ++n) _Pragma("unroll") for (int k = 0; k < 2; ++k) dst[n][k] = *(const LAS bf16x8*)(lds + PG8_SB(b, h) + boff + n * 2048 + k * 1024); } while (0)
; #define PG8_MMA(ai, bj, At, Bt) do { __builtin_amdgcn_s_setprio(1); _Pragma("unroll") for (int m = 0; m < 4; ++m) _Pragma("unroll") for (int n = 0; n < 2; ++n) _Pragma("unroll") for (int k = 0; k < 2; ++k) \
;         acc[ai][bj][m][n] = __builtin_amdgcn_mfma_f32_16x16x32_bf16(Bt[n][k], At[m][k], acc[ai][bj][m][n], 0, 0, 0); __builtin_amdgcn_s_setprio(0); } while (0)
; #define PG8_WAIT_V(n) asm volatile("s_waitcnt vmcnt(" #n ")" ::: "memory")
; #define PG8_WAIT_L(n) asm volatile("s_waitcnt lgkmcnt(" #n ")" ::: "memory")
; #define PG8_BAR __builtin_amdgcn_s_barrier()
; #define PG8_SCHED __builtin_amdgcn_sched_barrier(0)
; template <class Epi>
; __device__ __forceinline__ void gemm_phase(LAS unsigned char* lds, const GemmD g, const Epi& E, int G, int c) {
;     ...
;             PG8_WAIT_V(8); PG8_WAIT_L(0); PG8_BAR; PG8_MMA(1, 0, At, B0); PG8_MMA(1, 1, At, B1); PG8_BAR; PG8_SCHED;
;             PG8_LDB(B0, 1, 0); PG8_LDB(B1, 1, 1); PG8_SCHED; PG8_LDA(At, 1, 0); PG8_STAGE(PG8_SA(0, 1), a2 + hstepA, voffA);
;             PG8_WAIT_V(8); PG8_WAIT_L(0); PG8_BAR; PG8_MMA(0, 0, At, B0); PG8_MMA(0, 1, At, B1); PG8_BAR; PG8_SCHED;
.Lrw_PV_1_d:
	s_waitcnt lgkmcnt(0)
	s_barrier
	s_setprio 1
	s_waitcnt lgkmcnt(0)
	v_mfma_f32_16x16x32_bf16 v[60:63], v[146:149], v[184:187], v[60:63]
	v_mfma_f32_16x16x32_bf16 v[56:59], v[154:157], v[184:187], v[56:59]
	v_mfma_f32_16x16x32_bf16 v[52:55], v[146:149], v[192:195], v[52:55]
	v_mfma_f32_16x16x32_bf16 v[44:47], v[154:157], v[192:195], v[44:47]
	v_mfma_f32_16x16x32_bf16 v[36:39], v[146:149], v[214:217], v[36:39]
	v_mfma_f32_16x16x32_bf16 v[28:31], v[154:157], v[214:217], v[28:31]
	v_mfma_f32_16x16x32_bf16 v[20:23], v[146:149], v[222:225], v[20:23]
	v_mfma_f32_16x16x32_bf16 v[12:15], v[154:157], v[222:225], v[12:15]
	v_mfma_f32_16x16x32_bf16 v[60:63], v[150:153], v[188:191], v[60:63]
	v_mfma_f32_16x16x32_bf16 v[56:59], v[158:161], v[188:191], v[56:59]
	v_mfma_f32_16x16x32_bf16 v[52:55], v[150:153], v[210:213], v[52:55]
	v_mfma_f32_16x16x32_bf16 v[44:47], v[158:161], v[210:213], v[44:47]
	v_mfma_f32_16x16x32_bf16 v[36:39], v[150:153], v[218:221], v[36:39]
	v_mfma_f32_16x16x32_bf16 v[28:31], v[158:161], v[218:221], v[28:31]
	v_mfma_f32_16x16x32_bf16 v[20:23], v[150:153], v[226:229], v[20:23]
	v_mfma_f32_16x16x32_bf16 v[12:15], v[158:161], v[226:229], v[12:15]
	v_mfma_f32_16x16x32_bf16 v[48:51], v[162:165], v[184:187], v[48:51]
	v_mfma_f32_16x16x32_bf16 v[40:43], v[170:173], v[184:187], v[40:43]
	v_mfma_f32_16x16x32_bf16 v[32:35], v[162:165], v[192:195], v[32:35]
	v_mfma_f32_16x16x32_bf16 v[24:27], v[170:173], v[192:195], v[24:27]
	v_mfma_f32_16x16x32_bf16 v[16:19], v[162:165], v[214:217], v[16:19]
	v_mfma_f32_16x16x32_bf16 v[8:11], v[170:173], v[214:217], v[8:11]
	v_mfma_f32_16x16x32_bf16 v[4:7], v[162:165], v[222:225], v[4:7]
	v_mfma_f32_16x16x32_bf16 v[0:3], v[170:173], v[222:225], v[0:3]
	v_mfma_f32_16x16x32_bf16 v[48:51], v[166:169], v[188:191], v[48:51]
	v_mfma_f32_16x16x32_bf16 v[40:43], v[180:183], v[188:191], v[40:43]
	v_mfma_f32_16x16x32_bf16 v[32:35], v[166:169], v[210:213], v[32:35]
	v_mfma_f32_16x16x32_bf16 v[24:27], v[180:183], v[210:213], v[24:27]
	v_mfma_f32_16x16x32_bf16 v[16:19], v[166:169], v[218:221], v[16:19]
	v_mfma_f32_16x16x32_bf16 v[8:11], v[180:183], v[218:221], v[8:11]
	v_mfma_f32_16x16x32_bf16 v[4:7], v[166:169], v[226:229], v[4:7]
	v_mfma_f32_16x16x32_bf16 v[0:3], v[180:183], v[226:229], v[0:3]
	s_setprio 0
	s_barrier
	s_add_i32 s31, 0, 0x18000
	v_add_u32_e32 v145, s31, v141
	s_add_i32 s33, 0, 0x1c000
	ds_read_b128 v[146:149], v145
	ds_read_b128 v[150:153], v145 offset:1024
	ds_read_b128 v[154:157], v145 offset:2048
	ds_read_b128 v[158:161], v145 offset:3072
	v_add_u32_e32 v145, s33, v141
	ds_read_b128 v[162:165], v145
	ds_read_b128 v[166:169], v145 offset:1024
	ds_read_b128 v[170:173], v145 offset:2048
	ds_read_b128 v[180:183], v145 offset:3072
	s_add_u32 s4, s4, 0x80000
	s_addc_u32 s5, s5, 0
	s_mov_b32 m0, s10
	v_lshl_add_u64 v[232:233], s[4:5], 0, v[132:133]
	ds_read_b128 v[184:187], v143 offset:32768
	ds_read_b128 v[188:191], v143 offset:33792
	ds_read_b128 v[192:195], v143 offset:34816
	ds_read_b128 v[210:213], v143 offset:35840
	ds_read_b128 v[214:217], v143 offset:36864
	ds_read_b128 v[218:221], v143 offset:37888
	ds_read_b128 v[222:225], v143 offset:38912
	ds_read_b128 v[226:229], v143 offset:39936
	global_load_lds_dwordx4 v[232:233], off
	v_lshl_add_u64 v[232:233], s[4:5], 0, v[130:131]
	s_mov_b32 m0, s11
	s_nop 0
	global_load_lds_dwordx4 v[232:233], off
	s_waitcnt vmcnt(8)
	s_waitcnt lgkmcnt(0)
	s_barrier
	s_setprio 1
	s_waitcnt lgkmcnt(0)
	v_mfma_f32_16x16x32_bf16 v[124:127], v[146:149], v[184:187], v[124:127]
	v_mfma_f32_16x16x32_bf16 v[120:123], v[154:157], v[184:187], v[120:123]
	v_mfma_f32_16x16x32_bf16 v[112:115], v[146:149], v[192:195], v[112:115]
	v_mfma_f32_16x16x32_bf16 v[104:107], v[154:157], v[192:195], v[104:107]
	v_mfma_f32_16x16x32_bf16 v[96:99], v[146:149], v[214:217], v[96:99]
	v_mfma_f32_16x16x32_bf16 v[88:91], v[154:157], v[214:217], v[88:91]
	v_mfma_f32_16x16x32_bf16 v[80:83], v[146:149], v[222:225], v[80:83]
	v_mfma_f32_16x16x32_bf16 v[72:75], v[154:157], v[222:225], v[72:75]
	v_mfma_f32_16x16x32_bf16 v[124:127], v[150:153], v[188:191], v[124:127]
	v_mfma_f32_16x16x32_bf16 v[120:123], v[158:161], v[188:191], v[120:123]
	v_mfma_f32_16x16x32_bf16 v[112:115], v[150:153], v[210:213], v[112:115]
	v_mfma_f32_16x16x32_bf16 v[104:107], v[158:161], v[210:213], v[104:107]
	v_mfma_f32_16x16x32_bf16 v[96:99], v[150:153], v[218:221], v[96:99]
	v_mfma_f32_16x16x32_bf16 v[88:91], v[158:161], v[218:221], v[88:91]
	v_mfma_f32_16x16x32_bf16 v[80:83], v[150:153], v[226:229], v[80:83]
	v_mfma_f32_16x16x32_bf16 v[72:75], v[158:161], v[226:229], v[72:75]
	v_mfma_f32_16x16x32_bf16 v[116:119], v[162:165], v[184:187], v[116:119]
	v_mfma_f32_16x16x32_bf16 v[108:111], v[170:173], v[184:187], v[108:111]
	v_mfma_f32_16x16x32_bf16 v[100:103], v[162:165], v[192:195], v[100:103]
	v_mfma_f32_16x16x32_bf16 v[92:95], v[170:173], v[192:195], v[92:95]
	v_mfma_f32_16x16x32_bf16 v[84:87], v[162:165], v[214:217], v[84:87]
	v_mfma_f32_16x16x32_bf16 v[76:79], v[170:173], v[214:217], v[76:79]
	v_mfma_f32_16x16x32_bf16 v[68:71], v[162:165], v[222:225], v[68:71]
	v_mfma_f32_16x16x32_bf16 v[64:67], v[170:173], v[222:225], v[64:67]
	v_mfma_f32_16x16x32_bf16 v[116:119], v[166:169], v[188:191], v[116:119]
	v_mfma_f32_16x16x32_bf16 v[108:111], v[180:183], v[188:191], v[108:111]
	v_mfma_f32_16x16x32_bf16 v[100:103], v[166:169], v[210:213], v[100:103]
	v_mfma_f32_16x16x32_bf16 v[92:95], v[180:183], v[210:213], v[92:95]
	v_mfma_f32_16x16x32_bf16 v[84:87], v[166:169], v[218:221], v[84:87]
	v_mfma_f32_16x16x32_bf16 v[76:79], v[180:183], v[218:221], v[76:79]
	v_mfma_f32_16x16x32_bf16 v[68:71], v[166:169], v[226:229], v[68:71]
	v_mfma_f32_16x16x32_bf16 v[64:67], v[180:183], v[226:229], v[64:67]
	s_setprio 0
	s_barrier
; #define PG8_STAGE(bufoff, gbase, voff) do { _Pragma("unroll") for (int _i = 0; _i < 2; ++_i) \
;         __builtin_amdgcn_global_load_lds((const unsigned*)((const char*)(gbase) + (voff)[_i]), (LAS unsigned*)(lds + (bufoff) + ldsw + _i * 8192), 16, 0, 0); } while (0)
; #define PG8_LDA(dst, b, h) do { _Pragma("unroll") for (int m = 0; m < 4; ++m) _Pragma("unroll") for (int k = 0; k < 2; ++k) dst[m][k] = *(const LAS bf16x8*)(lds + PG8_SA(b, h) + aoff + m * 2048 + k * 1024); } while (0)
; #define PG8_MMA(ai, bj, At, Bt) do { __builtin_amdgcn_s_setprio(1); _Pragma("unroll") for (int m = 0; m < 4; ++m) _Pragma("unroll") for (int n = 0; n < 2; ++n) _Pragma("unroll") for (int k = 0; k < 2; ++k) \
;         acc[ai][bj][m][n] = __builtin_amdgcn_mfma_f32_16x16x32_bf16(Bt[n][k], At[m][k], acc[ai][bj][m][n], 0, 0, 0); __builtin_amdgcn_s_setprio(0); } while (0)
; #define PG8_WAIT_V(n) asm volatile("s_waitcnt vmcnt(" #n ")" ::: "memory")
; #define PG8_WAIT_L(n) asm volatile("s_waitcnt lgkmcnt(" #n ")" ::: "memory")
; #define PG8_BAR __builtin_amdgcn_s_barrier()
; #define PG8_SCHED __builtin_amdgcn_sched_barrier(0)
; template <class Epi>
; __device__ __forceinline__ void gemm_phase(LAS unsigned char* lds, const GemmD g, const Epi& E, int G, int c) {
;     ...
;             PG8_LDA(At, 1, 1); PG8_STAGE(PG8_SB(1, 0), b3, voffB); PG8_STAGE(PG8_SB(1, 1), b3 + hstepB, voffB); PG8_STAGE(PG8_SA(1, 0), a3, voffA);
;             PG8_WAIT_V(8); PG8_WAIT_L(0); PG8_BAR; PG8_MMA(1, 0, At, B0); PG8_MMA(1, 1, At, B1); PG8_BAR; PG8_SCHED;
;         }
;         if (wr == 0) PG8_BAR;
	s_add_i32 s4, s31, s2
	v_lshl_add_u64 v[138:139], v[138:139], 0, s[48:49]
	s_mov_b32 m0, s4
	ds_read_b128 v[184:187], v143 offset:49152
	ds_read_b128 v[188:191], v143 offset:50176
	ds_read_b128 v[192:195], v143 offset:51200
	ds_read_b128 v[210:213], v143 offset:52224
	ds_read_b128 v[214:217], v143 offset:53248
	ds_read_b128 v[218:221], v143 offset:54272
	ds_read_b128 v[222:225], v143 offset:55296
	ds_read_b128 v[226:229], v143 offset:56320
	global_load_lds_dwordx4 v[138:139], off
	s_add_i32 m0, s4, 0x2000
	s_add_u32 s4, s84, 0x400080
	v_lshl_add_u64 v[138:139], v[174:175], 0, s[48:49]
	s_addc_u32 s5, s85, 0
	s_add_i32 s31, s33, s2
	global_load_lds_dwordx4 v[138:139], off
	v_lshl_add_u64 v[138:139], s[4:5], 0, v[178:179]
	s_mov_b32 m0, s31
	s_nop 0
	global_load_lds_dwordx4 v[138:139], off
	v_lshl_add_u64 v[138:139], s[4:5], 0, v[128:129]
	s_add_i32 m0, s31, 0x2000
	s_nop 0
	global_load_lds_dwordx4 v[138:139], off
	v_lshl_add_u64 v[138:139], v[198:199], 0, s[48:49]
	s_mov_b32 m0, s16
	s_nop 0
	global_load_lds_dwordx4 v[138:139], off
	v_lshl_add_u64 v[138:139], v[230:231], 0, s[48:49]
	s_mov_b32 m0, s17
	s_nop 0
	global_load_lds_dwordx4 v[138:139], off
	s_waitcnt vmcnt(8)
	s_waitcnt lgkmcnt(0)
	s_barrier
	s_setprio 1
	s_waitcnt lgkmcnt(0)
	v_mfma_f32_16x16x32_bf16 v[60:63], v[146:149], v[184:187], v[60:63]
	v_mfma_f32_16x16x32_bf16 v[56:59], v[154:157], v[184:187], v[56:59]
	v_mfma_f32_16x16x32_bf16 v[52:55], v[146:149], v[192:195], v[52:55]
	v_mfma_f32_16x16x32_bf16 v[44:47], v[154:157], v[192:195], v[44:47]
	v_mfma_f32_16x16x32_bf16 v[36:39], v[146:149], v[214:217], v[36:39]
	v_mfma_f32_16x16x32_bf16 v[28:31], v[154:157], v[214:217], v[28:31]
	v_mfma_f32_16x16x32_bf16 v[20:23], v[146:149], v[222:225], v[20:23]
	v_mfma_f32_16x16x32_bf16 v[12:15], v[154:157], v[222:225], v[12:15]
	v_mfma_f32_16x16x32_bf16 v[60:63], v[150:153], v[188:191], v[60:63]
	v_mfma_f32_16x16x32_bf16 v[56:59], v[158:161], v[188:191], v[56:59]
	v_mfma_f32_16x16x32_bf16 v[52:55], v[150:153], v[210:213], v[52:55]
	v_mfma_f32_16x16x32_bf16 v[44:47], v[158:161], v[210:213], v[44:47]
	v_mfma_f32_16x16x32_bf16 v[36:39], v[150:153], v[218:221], v[36:39]
	v_mfma_f32_16x16x32_bf16 v[28:31], v[158:161], v[218:221], v[28:31]
	v_mfma_f32_16x16x32_bf16 v[20:23], v[150:153], v[226:229], v[20:23]
	v_mfma_f32_16x16x32_bf16 v[12:15], v[158:161], v[226:229], v[12:15]
	v_mfma_f32_16x16x32_bf16 v[48:51], v[162:165], v[184:187], v[48:51]
	v_mfma_f32_16x16x32_bf16 v[40:43], v[170:173], v[184:187], v[40:43]
	v_mfma_f32_16x16x32_bf16 v[32:35], v[162:165], v[192:195], v[32:35]
	v_mfma_f32_16x16x32_bf16 v[24:27], v[170:173], v[192:195], v[24:27]
	v_mfma_f32_16x16x32_bf16 v[16:19], v[162:165], v[214:217], v[16:19]
	v_mfma_f32_16x16x32_bf16 v[8:11], v[170:173], v[214:217], v[8:11]
	v_mfma_f32_16x16x32_bf16 v[4:7], v[162:165], v[222:225], v[4:7]
	v_mfma_f32_16x16x32_bf16 v[0:3], v[170:173], v[222:225], v[0:3]
	v_mfma_f32_16x16x32_bf16 v[48:51], v[166:169], v[188:191], v[48:51]
	v_mfma_f32_16x16x32_bf16 v[40:43], v[180:183], v[188:191], v[40:43]
	v_mfma_f32_16x16x32_bf16 v[32:35], v[166:169], v[210:213], v[32:35]
	v_mfma_f32_16x16x32_bf16 v[24:27], v[180:183], v[210:213], v[24:27]
	v_mfma_f32_16x16x32_bf16 v[16:19], v[166:169], v[218:221], v[16:19]
	v_mfma_f32_16x16x32_bf16 v[8:11], v[180:183], v[218:221], v[8:11]
	v_mfma_f32_16x16x32_bf16 v[4:7], v[166:169], v[226:229], v[4:7]
	v_mfma_f32_16x16x32_bf16 v[0:3], v[180:183], v[226:229], v[0:3]
	s_setprio 0
	s_barrier
	s_add_i32 s30, s30, 2
	s_add_u32 s82, s82, 0x100
	s_addc_u32 s83, s83, 0
	s_add_u32 s28, s28, 0x100
	s_addc_u32 s29, s29, 0
	s_cmp_gt_u32 s30, 29
	s_cbranch_scc0 .LBB0_297
	s_and_b64 vcc, exec, s[60:61]
	s_cbranch_vccz .LBB0_300
	s_barrier

; #define PG8_STAGE(bufoff, gbase, voff) do { _Pragma("unroll") for (int _i = 0; _i < 2; ++_i) \
;         __builtin_amdgcn_global_load_lds((const unsigned*)((const char*)(gbase) + (voff)[_i]), (LAS unsigned*)(lds + (bufoff) + ldsw + _i * 8192), 16, 0, 0); } while (0)
; #define PG8_LDA(dst, b, h) do { _Pragma("unroll") for (int m = 0; m < 4; ++m) _Pragma("unroll") for (int k = 0; k < 2; ++k) dst[m][k] = *(const LAS bf16x8*)(lds + PG8_SA(b, h) + aoff + m * 2048 + k * 1024); } while (0)
; #define PG8_MMA(ai, bj, At, Bt) do { __builtin_amdgcn_s_setprio(1); _Pragma("unroll") for (int m = 0; m < 4; ++m) _Pragma("unroll") for (int n = 0; n < 2; ++n) _Pragma("unroll") for (int k = 0; k < 2; ++k) \
;         acc[ai][bj][m][n] = __builtin_amdgcn_mfma_f32_16x16x32_bf16(Bt[n][k], At[m][k], acc[ai][bj][m][n], 0, 0, 0); __builtin_amdgcn_s_setprio(0); } while (0)
; #define PG8_WAIT_V(n) asm volatile("s_waitcnt vmcnt(" #n ")" ::: "memory")
; #define PG8_WAIT_L(n) asm volatile("s_waitcnt lgkmcnt(" #n ")" ::: "memory")
; #define PG8_BAR __builtin_amdgcn_s_barrier()
; #define PG8_SCHED __builtin_amdgcn_sched_barrier(0)
; template <class Epi>
; __device__ __forceinline__ void gemm_phase(LAS unsigned char* lds, const GemmD g, const Epi& E, int G, int c) {
;     ...
;             PG8_WAIT_V(8); PG8_WAIT_L(0); PG8_BAR; PG8_MMA(0, 0, At, B0); PG8_MMA(0, 1, At, B1); PG8_BAR; PG8_SCHED;
;             PG8_LDA(At, 0, 1); PG8_STAGE(PG8_SB(0, 0), b2, voffB); PG8_STAGE(PG8_SB(0, 1), b2 + hstepB, voffB); PG8_STAGE(PG8_SA(0, 0), a2, voffA);
;             PG8_WAIT_V(8); PG8_WAIT_L(0); PG8_BAR; PG8_MMA(1, 0, At, B0); PG8_MMA(1, 1, At, B1); PG8_BAR; PG8_SCHED;
.Lrw_S_0_d:
	s_waitcnt lgkmcnt(0)
	s_barrier
	s_setprio 1
	s_waitcnt lgkmcnt(0)
	v_mfma_f32_16x16x32_bf16 v[124:127], v[128:131], v[166:169], v[124:127]
	v_mfma_f32_16x16x32_bf16 v[120:123], v[142:145], v[166:169], v[120:123]
	v_mfma_f32_16x16x32_bf16 v[108:111], v[128:131], v[184:187], v[108:111]
	v_mfma_f32_16x16x32_bf16 v[104:107], v[142:145], v[184:187], v[104:107]
	v_mfma_f32_16x16x32_bf16 v[92:95], v[128:131], v[192:195], v[92:95]
	v_mfma_f32_16x16x32_bf16 v[88:91], v[142:145], v[192:195], v[88:91]
	v_mfma_f32_16x16x32_bf16 v[76:79], v[128:131], v[214:217], v[76:79]
	v_mfma_f32_16x16x32_bf16 v[72:75], v[142:145], v[214:217], v[72:75]
	v_mfma_f32_16x16x32_bf16 v[124:127], v[138:141], v[180:183], v[124:127]
	v_mfma_f32_16x16x32_bf16 v[120:123], v[146:149], v[180:183], v[120:123]
	v_mfma_f32_16x16x32_bf16 v[108:111], v[138:141], v[188:191], v[108:111]
	v_mfma_f32_16x16x32_bf16 v[104:107], v[146:149], v[188:191], v[104:107]
	v_mfma_f32_16x16x32_bf16 v[92:95], v[138:141], v[210:213], v[92:95]
	v_mfma_f32_16x16x32_bf16 v[88:91], v[146:149], v[210:213], v[88:91]
	v_mfma_f32_16x16x32_bf16 v[76:79], v[138:141], v[218:221], v[76:79]
	v_mfma_f32_16x16x32_bf16 v[72:75], v[146:149], v[218:221], v[72:75]
	v_mfma_f32_16x16x32_bf16 v[116:119], v[150:153], v[166:169], v[116:119]
	v_mfma_f32_16x16x32_bf16 v[112:115], v[158:161], v[166:169], v[112:115]
	v_mfma_f32_16x16x32_bf16 v[100:103], v[150:153], v[184:187], v[100:103]
	v_mfma_f32_16x16x32_bf16 v[96:99], v[158:161], v[184:187], v[96:99]
	v_mfma_f32_16x16x32_bf16 v[84:87], v[150:153], v[192:195], v[84:87]
	v_mfma_f32_16x16x32_bf16 v[80:83], v[158:161], v[192:195], v[80:83]
	v_mfma_f32_16x16x32_bf16 v[68:71], v[150:153], v[214:217], v[68:71]
	v_mfma_f32_16x16x32_bf16 v[64:67], v[158:161], v[214:217], v[64:67]
	v_mfma_f32_16x16x32_bf16 v[116:119], v[154:157], v[180:183], v[116:119]
	v_mfma_f32_16x16x32_bf16 v[112:115], v[162:165], v[180:183], v[112:115]
	v_mfma_f32_16x16x32_bf16 v[100:103], v[154:157], v[188:191], v[100:103]
	v_mfma_f32_16x16x32_bf16 v[96:99], v[162:165], v[188:191], v[96:99]
	v_mfma_f32_16x16x32_bf16 v[84:87], v[154:157], v[210:213], v[84:87]
	v_mfma_f32_16x16x32_bf16 v[80:83], v[162:165], v[210:213], v[80:83]
	v_mfma_f32_16x16x32_bf16 v[68:71], v[154:157], v[218:221], v[68:71]
	v_mfma_f32_16x16x32_bf16 v[64:67], v[162:165], v[218:221], v[64:67]
	s_setprio 0
	s_barrier
	s_mov_b32 m0, s38
	v_lshl_add_u64 v[174:175], s[94:95], 0, v[178:179]
	ds_read_b128 v[166:169], v173 offset:16384
	ds_read_b128 v[180:183], v173 offset:17408
	ds_read_b128 v[184:187], v173 offset:18432
	ds_read_b128 v[188:191], v173 offset:19456
	ds_read_b128 v[192:195], v173 offset:20480
	ds_read_b128 v[210:213], v173 offset:21504
	ds_read_b128 v[214:217], v173 offset:22528
	ds_read_b128 v[218:221], v173 offset:23552
	global_load_lds_dwordx4 v[174:175], off
	v_lshl_add_u64 v[198:199], s[94:95], 0, v[132:133]
	s_mov_b32 m0, s29
	v_lshl_add_u64 v[222:223], s[96:97], 0, v[178:179]
	global_load_lds_dwordx4 v[198:199], off
	s_mov_b32 m0, s33
	v_lshl_add_u64 v[224:225], s[92:93], 0, v[134:135]
	global_load_lds_dwordx4 v[222:223], off
	v_lshl_add_u64 v[222:223], s[96:97], 0, v[132:133]
	s_mov_b32 m0, s31
	s_nop 0
	global_load_lds_dwordx4 v[222:223], off
	v_lshl_add_u64 v[222:223], s[92:93], 0, v[136:137]
	s_mov_b32 m0, s30
	s_nop 0
	global_load_lds_dwordx4 v[222:223], off
	s_mov_b32 m0, s35
	s_nop 0
	global_load_lds_dwordx4 v[224:225], off
	s_cmp_lg_u32 s99, 0
	s_cbranch_scc1 .Lrw_S_1_r
	s_waitcnt vmcnt(8)
	s_branch .Lrw_S_1_d

; #define PG8_STAGE(bufoff, gbase, voff) do { _Pragma("unroll") for (int _i = 0; _i < 2; ++_i) \
;         __builtin_amdgcn_global_load_lds((const unsigned*)((const char*)(gbase) + (voff)[_i]), (LAS unsigned*)(lds + (bufoff) + ldsw + _i * 8192), 16, 0, 0); } while (0)
; #define PG8_LDA(dst, b, h) do { _Pragma("unroll") for (int m = 0; m < 4; ++m) _Pragma("unroll") for (int k = 0; k < 2; ++k) dst[m][k] = *(const LAS bf16x8*)(lds + PG8_SA(b, h) + aoff + m * 2048 + k * 1024); } while (0)
; #define PG8_LDB(dst, b, h) do { _Pragma("unroll") for (int n = 0; n < 2; ++n) _Pragma("unroll") for (int k = 0; k < 2; ++k) dst[n][k] = *(const LAS bf16x8*)(lds + PG8_SB(b, h) + boff + n * 2048 + k * 1024); } while (0)
; #define PG8_MMA(ai, bj, At, Bt) do { __builtin_amdgcn_s_setprio(1); _Pragma("unroll") for (int m = 0; m < 4; ++m) _Pragma("unroll") for (int n = 0; n < 2; ++n) _Pragma("unroll") for (int k = 0; k < 2; ++k) \
;         acc[ai][bj][m][n] = __builtin_amdgcn_mfma_f32_16x16x32_bf16(Bt[n][k], At[m][k], acc[ai][bj][m][n], 0, 0, 0); __builtin_amdgcn_s_setprio(0); } while (0)
; #define PG8_WAIT_V(n) asm volatile("s_waitcnt vmcnt(" #n ")" ::: "memory")
; #define PG8_WAIT_L(n) asm volatile("s_waitcnt lgkmcnt(" #n ")" ::: "memory")
; #define PG8_BAR __builtin_amdgcn_s_barrier()
; #define PG8_SCHED __builtin_amdgcn_sched_barrier(0)
; template <class Epi>
; __device__ __forceinline__ void gemm_phase(LAS unsigned char* lds, const GemmD g, const Epi& E, int G, int c) {
;     ...
;             PG8_WAIT_V(8); PG8_WAIT_L(0); PG8_BAR; PG8_MMA(1, 0, At, B0); PG8_MMA(1, 1, At, B1); PG8_BAR; PG8_SCHED;
;             PG8_LDB(B0, 1, 0); PG8_LDB(B1, 1, 1); PG8_SCHED; PG8_LDA(At, 1, 0); PG8_STAGE(PG8_SA(0, 1), a2 + hstepA, voffA);
;             PG8_WAIT_V(8); PG8_WAIT_L(0); PG8_BAR; PG8_MMA(0, 0, At, B0); PG8_MMA(0, 1, At, B1); PG8_BAR; PG8_SCHED;
.Lrw_S_1_d:
	s_waitcnt lgkmcnt(0)
	s_barrier
	s_setprio 1
	s_waitcnt lgkmcnt(0)
	v_mfma_f32_16x16x32_bf16 v[60:63], v[128:131], v[166:169], v[60:63]
	v_mfma_f32_16x16x32_bf16 v[56:59], v[142:145], v[166:169], v[56:59]
	v_mfma_f32_16x16x32_bf16 v[44:47], v[128:131], v[184:187], v[44:47]
	v_mfma_f32_16x16x32_bf16 v[40:43], v[142:145], v[184:187], v[40:43]
	v_mfma_f32_16x16x32_bf16 v[28:31], v[128:131], v[192:195], v[28:31]
	v_mfma_f32_16x16x32_bf16 v[24:27], v[142:145], v[192:195], v[24:27]
	v_mfma_f32_16x16x32_bf16 v[12:15], v[128:131], v[214:217], v[12:15]
	v_mfma_f32_16x16x32_bf16 v[8:11], v[142:145], v[214:217], v[8:11]
	v_mfma_f32_16x16x32_bf16 v[60:63], v[138:141], v[180:183], v[60:63]
	v_mfma_f32_16x16x32_bf16 v[56:59], v[146:149], v[180:183], v[56:59]
	v_mfma_f32_16x16x32_bf16 v[44:47], v[138:141], v[188:191], v[44:47]
	v_mfma_f32_16x16x32_bf16 v[40:43], v[146:149], v[188:191], v[40:43]
	v_mfma_f32_16x16x32_bf16 v[28:31], v[138:141], v[210:213], v[28:31]
	v_mfma_f32_16x16x32_bf16 v[24:27], v[146:149], v[210:213], v[24:27]
	v_mfma_f32_16x16x32_bf16 v[12:15], v[138:141], v[218:221], v[12:15]
	v_mfma_f32_16x16x32_bf16 v[8:11], v[146:149], v[218:221], v[8:11]
	v_mfma_f32_16x16x32_bf16 v[52:55], v[150:153], v[166:169], v[52:55]
	v_mfma_f32_16x16x32_bf16 v[48:51], v[158:161], v[166:169], v[48:51]
	v_mfma_f32_16x16x32_bf16 v[36:39], v[150:153], v[184:187], v[36:39]
	v_mfma_f32_16x16x32_bf16 v[32:35], v[158:161], v[184:187], v[32:35]
	v_mfma_f32_16x16x32_bf16 v[20:23], v[150:153], v[192:195], v[20:23]
	v_mfma_f32_16x16x32_bf16 v[16:19], v[158:161], v[192:195], v[16:19]
	v_mfma_f32_16x16x32_bf16 v[4:7], v[150:153], v[214:217], v[4:7]
	v_mfma_f32_16x16x32_bf16 v[0:3], v[158:161], v[214:217], v[0:3]
	v_mfma_f32_16x16x32_bf16 v[52:55], v[154:157], v[180:183], v[52:55]
	v_mfma_f32_16x16x32_bf16 v[48:51], v[162:165], v[180:183], v[48:51]
	v_mfma_f32_16x16x32_bf16 v[36:39], v[154:157], v[188:191], v[36:39]
	v_mfma_f32_16x16x32_bf16 v[32:35], v[162:165], v[188:191], v[32:35]
	v_mfma_f32_16x16x32_bf16 v[20:23], v[154:157], v[210:213], v[20:23]
	v_mfma_f32_16x16x32_bf16 v[16:19], v[162:165], v[210:213], v[16:19]
	v_mfma_f32_16x16x32_bf16 v[4:7], v[154:157], v[218:221], v[4:7]
	v_mfma_f32_16x16x32_bf16 v[0:3], v[162:165], v[218:221], v[0:3]
	s_setprio 0
	s_barrier
	v_add_u32_e32 v146, s28, v171
	v_add_u32_e32 v162, s27, v171
	ds_read_b128 v[128:131], v146
	ds_read_b128 v[138:141], v146 offset:1024
	ds_read_b128 v[142:145], v146 offset:2048
	ds_read_b128 v[146:149], v146 offset:3072
	ds_read_b128 v[150:153], v162
	ds_read_b128 v[154:157], v162 offset:1024
	ds_read_b128 v[158:161], v162 offset:2048
	ds_read_b128 v[162:165], v162 offset:3072
	s_mov_b32 m0, s36
	v_lshl_add_u64 v[226:227], vcc, 0, v[136:137]
	ds_read_b128 v[166:169], v173 offset:32768
	ds_read_b128 v[180:183], v173 offset:33792
	ds_read_b128 v[184:187], v173 offset:34816
	ds_read_b128 v[188:191], v173 offset:35840
	ds_read_b128 v[192:195], v173 offset:36864
	ds_read_b128 v[210:213], v173 offset:37888
	ds_read_b128 v[214:217], v173 offset:38912
	ds_read_b128 v[218:221], v173 offset:39936
	global_load_lds_dwordx4 v[226:227], off
	v_lshl_add_u64 v[226:227], vcc, 0, v[134:135]
	s_mov_b32 m0, s9
	s_nop 0
	global_load_lds_dwordx4 v[226:227], off
	s_waitcnt vmcnt(8)
	s_waitcnt lgkmcnt(0)
	s_barrier
	s_setprio 1
	s_waitcnt lgkmcnt(0)
	v_mfma_f32_16x16x32_bf16 v[124:127], v[128:131], v[166:169], v[124:127]
	v_mfma_f32_16x16x32_bf16 v[120:123], v[142:145], v[166:169], v[120:123]
	v_mfma_f32_16x16x32_bf16 v[108:111], v[128:131], v[184:187], v[108:111]
	v_mfma_f32_16x16x32_bf16 v[104:107], v[142:145], v[184:187], v[104:107]
	v_mfma_f32_16x16x32_bf16 v[92:95], v[128:131], v[192:195], v[92:95]
	v_mfma_f32_16x16x32_bf16 v[88:91], v[142:145], v[192:195], v[88:91]
	v_mfma_f32_16x16x32_bf16 v[76:79], v[128:131], v[214:217], v[76:79]
	v_mfma_f32_16x16x32_bf16 v[72:75], v[142:145], v[214:217], v[72:75]
	v_mfma_f32_16x16x32_bf16 v[124:127], v[138:141], v[180:183], v[124:127]
	v_mfma_f32_16x16x32_bf16 v[120:123], v[146:149], v[180:183], v[120:123]
	v_mfma_f32_16x16x32_bf16 v[108:111], v[138:141], v[188:191], v[108:111]
	v_mfma_f32_16x16x32_bf16 v[104:107], v[146:149], v[188:191], v[104:107]
	v_mfma_f32_16x16x32_bf16 v[92:95], v[138:141], v[210:213], v[92:95]
	v_mfma_f32_16x16x32_bf16 v[88:91], v[146:149], v[210:213], v[88:91]
	v_mfma_f32_16x16x32_bf16 v[76:79], v[138:141], v[218:221], v[76:79]
	v_mfma_f32_16x16x32_bf16 v[72:75], v[146:149], v[218:221], v[72:75]
	v_mfma_f32_16x16x32_bf16 v[116:119], v[150:153], v[166:169], v[116:119]
	v_mfma_f32_16x16x32_bf16 v[112:115], v[158:161], v[166:169], v[112:115]
	v_mfma_f32_16x16x32_bf16 v[100:103], v[150:153], v[184:187], v[100:103]
	v_mfma_f32_16x16x32_bf16 v[96:99], v[158:161], v[184:187], v[96:99]
	v_mfma_f32_16x16x32_bf16 v[84:87], v[150:153], v[192:195], v[84:87]
	v_mfma_f32_16x16x32_bf16 v[80:83], v[158:161], v[192:195], v[80:83]
	v_mfma_f32_16x16x32_bf16 v[68:71], v[150:153], v[214:217], v[68:71]
	v_mfma_f32_16x16x32_bf16 v[64:67], v[158:161], v[214:217], v[64:67]
	v_mfma_f32_16x16x32_bf16 v[116:119], v[154:157], v[180:183], v[116:119]
	v_mfma_f32_16x16x32_bf16 v[112:115], v[162:165], v[180:183], v[112:115]
	v_mfma_f32_16x16x32_bf16 v[100:103], v[154:157], v[188:191], v[100:103]
	v_mfma_f32_16x16x32_bf16 v[96:99], v[162:165], v[188:191], v[96:99]
	v_mfma_f32_16x16x32_bf16 v[84:87], v[154:157], v[210:213], v[84:87]
	v_mfma_f32_16x16x32_bf16 v[80:83], v[162:165], v[210:213], v[80:83]
	v_mfma_f32_16x16x32_bf16 v[68:71], v[154:157], v[218:221], v[68:71]
	v_mfma_f32_16x16x32_bf16 v[64:67], v[162:165], v[218:221], v[64:67]
	s_setprio 0
	s_barrier
; #define PG8_STAGE(bufoff, gbase, voff) do { _Pragma("unroll") for (int _i = 0; _i < 2; ++_i) \
;         __builtin_amdgcn_global_load_lds((const unsigned*)((const char*)(gbase) + (voff)[_i]), (LAS unsigned*)(lds + (bufoff) + ldsw + _i * 8192), 16, 0, 0); } while (0)
; #define PG8_LDA(dst, b, h) do { _Pragma("unroll") for (int m = 0; m < 4; ++m) _Pragma("unroll") for (int k = 0; k < 2; ++k) dst[m][k] = *(const LAS bf16x8*)(lds + PG8_SA(b, h) + aoff + m * 2048 + k * 1024); } while (0)
; #define PG8_MMA(ai, bj, At, Bt) do { __builtin_amdgcn_s_setprio(1); _Pragma("unroll") for (int m = 0; m < 4; ++m) _Pragma("unroll") for (int n = 0; n < 2; ++n) _Pragma("unroll") for (int k = 0; k < 2; ++k) \
;         acc[ai][bj][m][n] = __builtin_amdgcn_mfma_f32_16x16x32_bf16(Bt[n][k], At[m][k], acc[ai][bj][m][n], 0, 0, 0); __builtin_amdgcn_s_setprio(0); } while (0)
; #define PG8_WAIT_V(n) asm volatile("s_waitcnt vmcnt(" #n ")" ::: "memory")
; #define PG8_WAIT_L(n) asm volatile("s_waitcnt lgkmcnt(" #n ")" ::: "memory")
; #define PG8_BAR __builtin_amdgcn_s_barrier()
; #define PG8_SCHED __builtin_amdgcn_sched_barrier(0)
; template <class Epi>
; __device__ __forceinline__ void gemm_phase(LAS unsigned char* lds, const GemmD g, const Epi& E, int G, int c) {
;     ...
;             PG8_LDA(At, 1, 1); PG8_STAGE(PG8_SB(1, 0), b3, voffB); PG8_STAGE(PG8_SB(1, 1), b3 + hstepB, voffB); PG8_STAGE(PG8_SA(1, 0), a3, voffA);
;             PG8_WAIT_V(8); PG8_WAIT_L(0); PG8_BAR; PG8_MMA(1, 0, At, B0); PG8_MMA(1, 1, At, B1); PG8_BAR; PG8_SCHED;
;         }
;         if (wr == 0) PG8_BAR;
	s_mov_b32 m0, s19
	v_lshl_add_u64 v[174:175], v[174:175], 0, s[48:49]
	ds_read_b128 v[166:169], v173 offset:49152
	ds_read_b128 v[180:183], v173 offset:50176
	ds_read_b128 v[184:187], v173 offset:51200
	ds_read_b128 v[188:191], v173 offset:52224
	ds_read_b128 v[192:195], v173 offset:53248
	ds_read_b128 v[210:213], v173 offset:54272
	ds_read_b128 v[214:217], v173 offset:55296
	ds_read_b128 v[218:221], v173 offset:56320
	global_load_lds_dwordx4 v[174:175], off
	v_lshl_add_u64 v[174:175], v[198:199], 0, s[48:49]
	s_mov_b32 m0, s17
	s_nop 0
	global_load_lds_dwordx4 v[174:175], off
	v_lshl_add_u64 v[174:175], s[90:91], 0, v[178:179]
	s_mov_b32 m0, s50
	s_nop 0
	global_load_lds_dwordx4 v[174:175], off
	v_lshl_add_u64 v[174:175], s[90:91], 0, v[132:133]
	s_mov_b32 m0, s39
	s_nop 0
	global_load_lds_dwordx4 v[174:175], off
	v_lshl_add_u64 v[174:175], v[222:223], 0, s[48:49]
	s_mov_b32 m0, s10
	s_nop 0
	global_load_lds_dwordx4 v[174:175], off
	v_lshl_add_u64 v[174:175], v[224:225], 0, s[48:49]
	s_mov_b32 m0, s11
	s_nop 0
	global_load_lds_dwordx4 v[174:175], off
	s_waitcnt vmcnt(8)
	s_waitcnt lgkmcnt(0)
	s_barrier
	s_setprio 1
	s_waitcnt lgkmcnt(0)
	v_mfma_f32_16x16x32_bf16 v[60:63], v[128:131], v[166:169], v[60:63]
	v_mfma_f32_16x16x32_bf16 v[56:59], v[142:145], v[166:169], v[56:59]
	v_mfma_f32_16x16x32_bf16 v[44:47], v[128:131], v[184:187], v[44:47]
	v_mfma_f32_16x16x32_bf16 v[40:43], v[142:145], v[184:187], v[40:43]
	v_mfma_f32_16x16x32_bf16 v[28:31], v[128:131], v[192:195], v[28:31]
	v_mfma_f32_16x16x32_bf16 v[24:27], v[142:145], v[192:195], v[24:27]
	v_mfma_f32_16x16x32_bf16 v[12:15], v[128:131], v[214:217], v[12:15]
	v_mfma_f32_16x16x32_bf16 v[8:11], v[142:145], v[214:217], v[8:11]
	v_mfma_f32_16x16x32_bf16 v[60:63], v[138:141], v[180:183], v[60:63]
	v_mfma_f32_16x16x32_bf16 v[56:59], v[146:149], v[180:183], v[56:59]
	v_mfma_f32_16x16x32_bf16 v[44:47], v[138:141], v[188:191], v[44:47]
	v_mfma_f32_16x16x32_bf16 v[40:43], v[146:149], v[188:191], v[40:43]
	v_mfma_f32_16x16x32_bf16 v[28:31], v[138:141], v[210:213], v[28:31]
	v_mfma_f32_16x16x32_bf16 v[24:27], v[146:149], v[210:213], v[24:27]
	v_mfma_f32_16x16x32_bf16 v[12:15], v[138:141], v[218:221], v[12:15]
	v_mfma_f32_16x16x32_bf16 v[8:11], v[146:149], v[218:221], v[8:11]
	v_mfma_f32_16x16x32_bf16 v[52:55], v[150:153], v[166:169], v[52:55]
	v_mfma_f32_16x16x32_bf16 v[48:51], v[158:161], v[166:169], v[48:51]
	v_mfma_f32_16x16x32_bf16 v[36:39], v[150:153], v[184:187], v[36:39]
	v_mfma_f32_16x16x32_bf16 v[32:35], v[158:161], v[184:187], v[32:35]
	v_mfma_f32_16x16x32_bf16 v[20:23], v[150:153], v[192:195], v[20:23]
	v_mfma_f32_16x16x32_bf16 v[16:19], v[158:161], v[192:195], v[16:19]
	v_mfma_f32_16x16x32_bf16 v[4:7], v[150:153], v[214:217], v[4:7]
	v_mfma_f32_16x16x32_bf16 v[0:3], v[158:161], v[214:217], v[0:3]
	v_mfma_f32_16x16x32_bf16 v[52:55], v[154:157], v[180:183], v[52:55]
	v_mfma_f32_16x16x32_bf16 v[48:51], v[162:165], v[180:183], v[48:51]
	v_mfma_f32_16x16x32_bf16 v[36:39], v[154:157], v[188:191], v[36:39]
	v_mfma_f32_16x16x32_bf16 v[32:35], v[162:165], v[188:191], v[32:35]
	v_mfma_f32_16x16x32_bf16 v[20:23], v[154:157], v[210:213], v[20:23]
	v_mfma_f32_16x16x32_bf16 v[16:19], v[162:165], v[210:213], v[16:19]
	v_mfma_f32_16x16x32_bf16 v[4:7], v[154:157], v[218:221], v[4:7]
	v_mfma_f32_16x16x32_bf16 v[0:3], v[162:165], v[218:221], v[0:3]
	s_setprio 0
	s_barrier
	s_movk_i32 s4, 0x100
	s_andn2_b64 vcc, exec, s[88:89]
	s_mov_b64 s[90:91], -1
	s_mov_b64 s[88:89], 0
	s_cbranch_vccz .LBB0_329
	s_and_b64 vcc, exec, s[62:63]
	s_cbranch_vccz .LBB0_332
	s_barrier

; #define PG8_STAGE(bufoff, gbase, voff) do { _Pragma("unroll") for (int _i = 0; _i < 2; ++_i) \
;         __builtin_amdgcn_global_load_lds((const unsigned*)((const char*)(gbase) + (voff)[_i]), (LAS unsigned*)(lds + (bufoff) + ldsw + _i * 8192), 16, 0, 0); } while (0)
; #define PG8_LDA(dst, b, h) do { _Pragma("unroll") for (int m = 0; m < 4; ++m) _Pragma("unroll") for (int k = 0; k < 2; ++k) dst[m][k] = *(const LAS bf16x8*)(lds + PG8_SA(b, h) + aoff + m * 2048 + k * 1024); } while (0)
; #define PG8_MMA(ai, bj, At, Bt) do { __builtin_amdgcn_s_setprio(1); _Pragma("unroll") for (int m = 0; m < 4; ++m) _Pragma("unroll") for (int n = 0; n < 2; ++n) _Pragma("unroll") for (int k = 0; k < 2; ++k) \
;         acc[ai][bj][m][n] = __builtin_amdgcn_mfma_f32_16x16x32_bf16(Bt[n][k], At[m][k], acc[ai][bj][m][n], 0, 0, 0); __builtin_amdgcn_s_setprio(0); } while (0)
; #define PG8_WAIT_V(n) asm volatile("s_waitcnt vmcnt(" #n ")" ::: "memory")
; #define PG8_WAIT_L(n) asm volatile("s_waitcnt lgkmcnt(" #n ")" ::: "memory")
; #define PG8_BAR __builtin_amdgcn_s_barrier()
; #define PG8_SCHED __builtin_amdgcn_sched_barrier(0)
; template <class Epi>
; __device__ __forceinline__ void gemm_phase(LAS unsigned char* lds, const GemmD g, const Epi& E, int G, int c) {
;     ...
;             PG8_WAIT_V(8); PG8_WAIT_L(0); PG8_BAR; PG8_MMA(0, 0, At, B0); PG8_MMA(0, 1, At, B1); PG8_BAR; PG8_SCHED;
;             PG8_LDA(At, 0, 1); PG8_STAGE(PG8_SB(0, 0), b2, voffB); PG8_STAGE(PG8_SB(0, 1), b2 + hstepB, voffB); PG8_STAGE(PG8_SA(0, 0), a2, voffA);
;             PG8_WAIT_V(8); PG8_WAIT_L(0); PG8_BAR; PG8_MMA(1, 0, At, B0); PG8_MMA(1, 1, At, B1); PG8_BAR; PG8_SCHED;
.Lrw_In_0_d:
	s_waitcnt lgkmcnt(0)
	s_barrier
	s_setprio 1
	s_waitcnt lgkmcnt(0)
	v_mfma_f32_16x16x32_bf16 v[124:127], v[128:131], v[184:187], v[124:127]
	v_mfma_f32_16x16x32_bf16 v[120:123], v[136:139], v[184:187], v[120:123]
	v_mfma_f32_16x16x32_bf16 v[108:111], v[128:131], v[210:213], v[108:111]
	v_mfma_f32_16x16x32_bf16 v[104:107], v[136:139], v[210:213], v[104:107]
	v_mfma_f32_16x16x32_bf16 v[92:95], v[128:131], v[218:221], v[92:95]
	v_mfma_f32_16x16x32_bf16 v[88:91], v[136:139], v[218:221], v[88:91]
	v_mfma_f32_16x16x32_bf16 v[76:79], v[128:131], v[226:229], v[76:79]
	v_mfma_f32_16x16x32_bf16 v[72:75], v[136:139], v[226:229], v[72:75]
	v_mfma_f32_16x16x32_bf16 v[124:127], v[132:135], v[188:191], v[124:127]
	v_mfma_f32_16x16x32_bf16 v[120:123], v[140:143], v[188:191], v[120:123]
	v_mfma_f32_16x16x32_bf16 v[108:111], v[132:135], v[214:217], v[108:111]
	v_mfma_f32_16x16x32_bf16 v[104:107], v[140:143], v[214:217], v[104:107]
	v_mfma_f32_16x16x32_bf16 v[92:95], v[132:135], v[222:225], v[92:95]
	v_mfma_f32_16x16x32_bf16 v[88:91], v[140:143], v[222:225], v[88:91]
	v_mfma_f32_16x16x32_bf16 v[76:79], v[132:135], v[230:233], v[76:79]
	v_mfma_f32_16x16x32_bf16 v[72:75], v[140:143], v[230:233], v[72:75]
	v_mfma_f32_16x16x32_bf16 v[116:119], v[162:165], v[184:187], v[116:119]
	v_mfma_f32_16x16x32_bf16 v[112:115], v[170:173], v[184:187], v[112:115]
	v_mfma_f32_16x16x32_bf16 v[100:103], v[162:165], v[210:213], v[100:103]
	v_mfma_f32_16x16x32_bf16 v[96:99], v[170:173], v[210:213], v[96:99]
	v_mfma_f32_16x16x32_bf16 v[84:87], v[162:165], v[218:221], v[84:87]
	v_mfma_f32_16x16x32_bf16 v[80:83], v[170:173], v[218:221], v[80:83]
	v_mfma_f32_16x16x32_bf16 v[68:71], v[162:165], v[226:229], v[68:71]
	v_mfma_f32_16x16x32_bf16 v[64:67], v[170:173], v[226:229], v[64:67]
	v_mfma_f32_16x16x32_bf16 v[116:119], v[166:169], v[188:191], v[116:119]
	v_mfma_f32_16x16x32_bf16 v[112:115], v[180:183], v[188:191], v[112:115]
	v_mfma_f32_16x16x32_bf16 v[100:103], v[166:169], v[214:217], v[100:103]
	v_mfma_f32_16x16x32_bf16 v[96:99], v[180:183], v[214:217], v[96:99]
	v_mfma_f32_16x16x32_bf16 v[84:87], v[166:169], v[222:225], v[84:87]
	v_mfma_f32_16x16x32_bf16 v[80:83], v[180:183], v[222:225], v[80:83]
	v_mfma_f32_16x16x32_bf16 v[68:71], v[166:169], v[230:233], v[68:71]
	v_mfma_f32_16x16x32_bf16 v[64:67], v[180:183], v[230:233], v[64:67]
	s_setprio 0
	s_barrier
	s_add_i32 s28, s28, s16
	v_lshl_add_u64 v[174:175], s[80:81], 0, v[148:149]
	s_mov_b32 m0, s28
	ds_read_b128 v[184:187], v196 offset:16384
	ds_read_b128 v[188:191], v196 offset:17408
	ds_read_b128 v[210:213], v196 offset:18432
	ds_read_b128 v[214:217], v196 offset:19456
	ds_read_b128 v[218:221], v196 offset:20480
	ds_read_b128 v[222:225], v196 offset:21504
	ds_read_b128 v[226:229], v196 offset:22528
	ds_read_b128 v[230:233], v196 offset:23552
	global_load_lds_dwordx4 v[174:175], off
	s_add_i32 m0, s28, 0x2000
	s_add_u32 s28, s80, 0x80000
	v_lshl_add_u64 v[192:193], s[80:81], 0, v[144:145]
	s_addc_u32 s29, s81, 0
	s_add_i32 s31, s31, s16
	global_load_lds_dwordx4 v[192:193], off
	v_lshl_add_u64 v[198:199], s[28:29], 0, v[148:149]
	s_mov_b32 m0, s31
	v_lshl_add_u64 v[234:235], s[4:5], 0, v[146:147]
	global_load_lds_dwordx4 v[198:199], off
	v_lshl_add_u64 v[198:199], s[28:29], 0, v[144:145]
	s_add_i32 m0, s31, 0x2000
	s_nop 0
	global_load_lds_dwordx4 v[198:199], off
	v_lshl_add_u64 v[198:199], s[4:5], 0, v[150:151]
	s_mov_b32 m0, s23
	s_nop 0
	global_load_lds_dwordx4 v[198:199], off
	s_mov_b32 m0, s26
	s_nop 0
	global_load_lds_dwordx4 v[234:235], off
	s_cmp_lg_u32 s99, 0
	s_cbranch_scc1 .Lrw_In_1_r
	s_waitcnt vmcnt(8)
	s_branch .Lrw_In_1_d

; #define PG8_STAGE(bufoff, gbase, voff) do { _Pragma("unroll") for (int _i = 0; _i < 2; ++_i) \
;         __builtin_amdgcn_global_load_lds((const unsigned*)((const char*)(gbase) + (voff)[_i]), (LAS unsigned*)(lds + (bufoff) + ldsw + _i * 8192), 16, 0, 0); } while (0)
; #define PG8_LDA(dst, b, h) do { _Pragma("unroll") for (int m = 0; m < 4; ++m) _Pragma("unroll") for (int k = 0; k < 2; ++k) dst[m][k] = *(const LAS bf16x8*)(lds + PG8_SA(b, h) + aoff + m * 2048 + k * 1024); } while (0)
; #define PG8_LDB(dst, b, h) do { _Pragma("unroll") for (int n = 0; n < 2; ++n) _Pragma("unroll") for (int k = 0; k < 2; ++k) dst[n][k] = *(const LAS bf16x8*)(lds + PG8_SB(b, h) + boff + n * 2048 + k * 1024); } while (0)
; #define PG8_MMA(ai, bj, At, Bt) do { __builtin_amdgcn_s_setprio(1); _Pragma("unroll") for (int m = 0; m < 4; ++m) _Pragma("unroll") for (int n = 0; n < 2; ++n) _Pragma("unroll") for (int k = 0; k < 2; ++k) \
;         acc[ai][bj][m][n] = __builtin_amdgcn_mfma_f32_16x16x32_bf16(Bt[n][k], At[m][k], acc[ai][bj][m][n], 0, 0, 0); __builtin_amdgcn_s_setprio(0); } while (0)
; #define PG8_WAIT_V(n) asm volatile("s_waitcnt vmcnt(" #n ")" ::: "memory")
; #define PG8_WAIT_L(n) asm volatile("s_waitcnt lgkmcnt(" #n ")" ::: "memory")
; #define PG8_BAR __builtin_amdgcn_s_barrier()
; #define PG8_SCHED __builtin_amdgcn_sched_barrier(0)
; template <class Epi>
; __device__ __forceinline__ void gemm_phase(LAS unsigned char* lds, const GemmD g, const Epi& E, int G, int c) {
;     ...
;             PG8_WAIT_V(8); PG8_WAIT_L(0); PG8_BAR; PG8_MMA(1, 0, At, B0); PG8_MMA(1, 1, At, B1); PG8_BAR; PG8_SCHED;
;             PG8_LDB(B0, 1, 0); PG8_LDB(B1, 1, 1); PG8_SCHED; PG8_LDA(At, 1, 0); PG8_STAGE(PG8_SA(0, 1), a2 + hstepA, voffA);
;             PG8_WAIT_V(8); PG8_WAIT_L(0); PG8_BAR; PG8_MMA(0, 0, At, B0); PG8_MMA(0, 1, At, B1); PG8_BAR; PG8_SCHED;
.Lrw_In_1_d:
	s_waitcnt lgkmcnt(0)
	s_barrier
	s_setprio 1
	s_waitcnt lgkmcnt(0)
	v_mfma_f32_16x16x32_bf16 v[60:63], v[128:131], v[184:187], v[60:63]
	v_mfma_f32_16x16x32_bf16 v[56:59], v[136:139], v[184:187], v[56:59]
	v_mfma_f32_16x16x32_bf16 v[44:47], v[128:131], v[210:213], v[44:47]
	v_mfma_f32_16x16x32_bf16 v[40:43], v[136:139], v[210:213], v[40:43]
	v_mfma_f32_16x16x32_bf16 v[28:31], v[128:131], v[218:221], v[28:31]
	v_mfma_f32_16x16x32_bf16 v[24:27], v[136:139], v[218:221], v[24:27]
	v_mfma_f32_16x16x32_bf16 v[12:15], v[128:131], v[226:229], v[12:15]
	v_mfma_f32_16x16x32_bf16 v[8:11], v[136:139], v[226:229], v[8:11]
	v_mfma_f32_16x16x32_bf16 v[60:63], v[132:135], v[188:191], v[60:63]
	v_mfma_f32_16x16x32_bf16 v[56:59], v[140:143], v[188:191], v[56:59]
	v_mfma_f32_16x16x32_bf16 v[44:47], v[132:135], v[214:217], v[44:47]
	v_mfma_f32_16x16x32_bf16 v[40:43], v[140:143], v[214:217], v[40:43]
	v_mfma_f32_16x16x32_bf16 v[28:31], v[132:135], v[222:225], v[28:31]
	v_mfma_f32_16x16x32_bf16 v[24:27], v[140:143], v[222:225], v[24:27]
	v_mfma_f32_16x16x32_bf16 v[12:15], v[132:135], v[230:233], v[12:15]
	v_mfma_f32_16x16x32_bf16 v[8:11], v[140:143], v[230:233], v[8:11]
	v_mfma_f32_16x16x32_bf16 v[52:55], v[162:165], v[184:187], v[52:55]
	v_mfma_f32_16x16x32_bf16 v[48:51], v[170:173], v[184:187], v[48:51]
	v_mfma_f32_16x16x32_bf16 v[36:39], v[162:165], v[210:213], v[36:39]
	v_mfma_f32_16x16x32_bf16 v[32:35], v[170:173], v[210:213], v[32:35]
	v_mfma_f32_16x16x32_bf16 v[20:23], v[162:165], v[218:221], v[20:23]
	v_mfma_f32_16x16x32_bf16 v[16:19], v[170:173], v[218:221], v[16:19]
	v_mfma_f32_16x16x32_bf16 v[4:7], v[162:165], v[226:229], v[4:7]
	v_mfma_f32_16x16x32_bf16 v[0:3], v[170:173], v[226:229], v[0:3]
	v_mfma_f32_16x16x32_bf16 v[52:55], v[166:169], v[188:191], v[52:55]
	v_mfma_f32_16x16x32_bf16 v[48:51], v[180:183], v[188:191], v[48:51]
	v_mfma_f32_16x16x32_bf16 v[36:39], v[166:169], v[214:217], v[36:39]
	v_mfma_f32_16x16x32_bf16 v[32:35], v[180:183], v[214:217], v[32:35]
	v_mfma_f32_16x16x32_bf16 v[20:23], v[166:169], v[222:225], v[20:23]
	v_mfma_f32_16x16x32_bf16 v[16:19], v[180:183], v[222:225], v[16:19]
	v_mfma_f32_16x16x32_bf16 v[4:7], v[166:169], v[230:233], v[4:7]
	v_mfma_f32_16x16x32_bf16 v[0:3], v[180:183], v[230:233], v[0:3]
	s_setprio 0
	s_barrier
	s_add_i32 s28, 0, 0x18000
	s_add_i32 s29, 0, 0x1c000
	v_add_u32_e32 v140, s28, v194
	v_add_u32_e32 v178, s29, v194
	ds_read_b128 v[128:131], v140
	ds_read_b128 v[132:135], v140 offset:1024
	ds_read_b128 v[136:139], v140 offset:2048
	ds_read_b128 v[140:143], v140 offset:3072
	ds_read_b128 v[162:165], v178
	ds_read_b128 v[166:169], v178 offset:1024
	ds_read_b128 v[170:173], v178 offset:2048
	ds_read_b128 v[180:183], v178 offset:3072
	s_add_u32 s4, s4, 0x80000
	s_addc_u32 s5, s5, 0
	s_mov_b32 m0, s30
	v_lshl_add_u64 v[236:237], s[4:5], 0, v[150:151]
	ds_read_b128 v[184:187], v196 offset:32768
	ds_read_b128 v[188:191], v196 offset:33792
	ds_read_b128 v[210:213], v196 offset:34816
	ds_read_b128 v[214:217], v196 offset:35840
	ds_read_b128 v[218:221], v196 offset:36864
	ds_read_b128 v[222:225], v196 offset:37888
	ds_read_b128 v[226:229], v196 offset:38912
	ds_read_b128 v[230:233], v196 offset:39936
	global_load_lds_dwordx4 v[236:237], off
	v_lshl_add_u64 v[236:237], s[4:5], 0, v[146:147]
	s_mov_b32 m0, s35
	s_nop 0
	global_load_lds_dwordx4 v[236:237], off
	s_waitcnt vmcnt(8)
	s_waitcnt lgkmcnt(0)
	s_barrier
	s_setprio 1
	s_waitcnt lgkmcnt(0)
	v_mfma_f32_16x16x32_bf16 v[124:127], v[128:131], v[184:187], v[124:127]
	v_mfma_f32_16x16x32_bf16 v[120:123], v[136:139], v[184:187], v[120:123]
	v_mfma_f32_16x16x32_bf16 v[108:111], v[128:131], v[210:213], v[108:111]
	v_mfma_f32_16x16x32_bf16 v[104:107], v[136:139], v[210:213], v[104:107]
	v_mfma_f32_16x16x32_bf16 v[92:95], v[128:131], v[218:221], v[92:95]
	v_mfma_f32_16x16x32_bf16 v[88:91], v[136:139], v[218:221], v[88:91]
	v_mfma_f32_16x16x32_bf16 v[76:79], v[128:131], v[226:229], v[76:79]
	v_mfma_f32_16x16x32_bf16 v[72:75], v[136:139], v[226:229], v[72:75]
	v_mfma_f32_16x16x32_bf16 v[124:127], v[132:135], v[188:191], v[124:127]
	v_mfma_f32_16x16x32_bf16 v[120:123], v[140:143], v[188:191], v[120:123]
	v_mfma_f32_16x16x32_bf16 v[108:111], v[132:135], v[214:217], v[108:111]
	v_mfma_f32_16x16x32_bf16 v[104:107], v[140:143], v[214:217], v[104:107]
	v_mfma_f32_16x16x32_bf16 v[92:95], v[132:135], v[222:225], v[92:95]
	v_mfma_f32_16x16x32_bf16 v[88:91], v[140:143], v[222:225], v[88:91]
	v_mfma_f32_16x16x32_bf16 v[76:79], v[132:135], v[230:233], v[76:79]
	v_mfma_f32_16x16x32_bf16 v[72:75], v[140:143], v[230:233], v[72:75]
	v_mfma_f32_16x16x32_bf16 v[116:119], v[162:165], v[184:187], v[116:119]
	v_mfma_f32_16x16x32_bf16 v[112:115], v[170:173], v[184:187], v[112:115]
	v_mfma_f32_16x16x32_bf16 v[100:103], v[162:165], v[210:213], v[100:103]
	v_mfma_f32_16x16x32_bf16 v[96:99], v[170:173], v[210:213], v[96:99]
	v_mfma_f32_16x16x32_bf16 v[84:87], v[162:165], v[218:221], v[84:87]
	v_mfma_f32_16x16x32_bf16 v[80:83], v[170:173], v[218:221], v[80:83]
	v_mfma_f32_16x16x32_bf16 v[68:71], v[162:165], v[226:229], v[68:71]
	v_mfma_f32_16x16x32_bf16 v[64:67], v[170:173], v[226:229], v[64:67]
	v_mfma_f32_16x16x32_bf16 v[116:119], v[166:169], v[188:191], v[116:119]
	v_mfma_f32_16x16x32_bf16 v[112:115], v[180:183], v[188:191], v[112:115]
	v_mfma_f32_16x16x32_bf16 v[100:103], v[166:169], v[214:217], v[100:103]
	v_mfma_f32_16x16x32_bf16 v[96:99], v[180:183], v[214:217], v[96:99]
	v_mfma_f32_16x16x32_bf16 v[84:87], v[166:169], v[222:225], v[84:87]
	v_mfma_f32_16x16x32_bf16 v[80:83], v[180:183], v[222:225], v[80:83]
	v_mfma_f32_16x16x32_bf16 v[68:71], v[166:169], v[230:233], v[68:71]
	v_mfma_f32_16x16x32_bf16 v[64:67], v[180:183], v[230:233], v[64:67]
	s_setprio 0
	s_barrier
; #define PG8_STAGE(bufoff, gbase, voff) do { _Pragma("unroll") for (int _i = 0; _i < 2; ++_i) \
;         __builtin_amdgcn_global_load_lds((const unsigned*)((const char*)(gbase) + (voff)[_i]), (LAS unsigned*)(lds + (bufoff) + ldsw + _i * 8192), 16, 0, 0); } while (0)
; #define PG8_LDA(dst, b, h) do { _Pragma("unroll") for (int m = 0; m < 4; ++m) _Pragma("unroll") for (int k = 0; k < 2; ++k) dst[m][k] = *(const LAS bf16x8*)(lds + PG8_SA(b, h) + aoff + m * 2048 + k * 1024); } while (0)
; #define PG8_MMA(ai, bj, At, Bt) do { __builtin_amdgcn_s_setprio(1); _Pragma("unroll") for (int m = 0; m < 4; ++m) _Pragma("unroll") for (int n = 0; n < 2; ++n) _Pragma("unroll") for (int k = 0; k < 2; ++k) \
;         acc[ai][bj][m][n] = __builtin_amdgcn_mfma_f32_16x16x32_bf16(Bt[n][k], At[m][k], acc[ai][bj][m][n], 0, 0, 0); __builtin_amdgcn_s_setprio(0); } while (0)
; #define PG8_WAIT_V(n) asm volatile("s_waitcnt vmcnt(" #n ")" ::: "memory")
; #define PG8_WAIT_L(n) asm volatile("s_waitcnt lgkmcnt(" #n ")" ::: "memory")
; #define PG8_BAR __builtin_amdgcn_s_barrier()
; #define PG8_SCHED __builtin_amdgcn_sched_barrier(0)
; template <class Epi>
; __device__ __forceinline__ void gemm_phase(LAS unsigned char* lds, const GemmD g, const Epi& E, int G, int c) {
;     ...
;             PG8_LDA(At, 1, 1); PG8_STAGE(PG8_SB(1, 0), b3, voffB); PG8_STAGE(PG8_SB(1, 1), b3 + hstepB, voffB); PG8_STAGE(PG8_SA(1, 0), a3, voffA);
;             PG8_WAIT_V(8); PG8_WAIT_L(0); PG8_BAR; PG8_MMA(1, 0, At, B0); PG8_MMA(1, 1, At, B1); PG8_BAR; PG8_SCHED;
;         }
;         if (wr == 0) PG8_BAR;
	s_add_i32 s4, s28, s16
	v_lshl_add_u64 v[174:175], v[174:175], 0, s[48:49]
	s_mov_b32 m0, s4
	ds_read_b128 v[184:187], v196 offset:49152
	ds_read_b128 v[188:191], v196 offset:50176
	ds_read_b128 v[210:213], v196 offset:51200
	ds_read_b128 v[214:217], v196 offset:52224
	ds_read_b128 v[218:221], v196 offset:53248
	ds_read_b128 v[222:225], v196 offset:54272
	ds_read_b128 v[226:229], v196 offset:55296
	ds_read_b128 v[230:233], v196 offset:56320
	global_load_lds_dwordx4 v[174:175], off
	s_add_i32 m0, s4, 0x2000
	s_add_u32 s4, s80, 0x80080
	v_lshl_add_u64 v[174:175], v[192:193], 0, s[48:49]
	s_addc_u32 s5, s81, 0
	s_add_i32 s28, s29, s16
	global_load_lds_dwordx4 v[174:175], off
	v_lshl_add_u64 v[174:175], s[4:5], 0, v[148:149]
	s_mov_b32 m0, s28
	s_nop 0
	global_load_lds_dwordx4 v[174:175], off
	v_lshl_add_u64 v[174:175], s[4:5], 0, v[144:145]
	s_add_i32 m0, s28, 0x2000
	s_nop 0
	global_load_lds_dwordx4 v[174:175], off
	v_lshl_add_u64 v[174:175], v[198:199], 0, s[48:49]
	s_mov_b32 m0, s36
	s_nop 0
	global_load_lds_dwordx4 v[174:175], off
	v_lshl_add_u64 v[174:175], v[234:235], 0, s[48:49]
	s_mov_b32 m0, s82
	s_nop 0
	global_load_lds_dwordx4 v[174:175], off
	s_waitcnt vmcnt(8)
	s_waitcnt lgkmcnt(0)
	s_barrier
	s_setprio 1
	s_waitcnt lgkmcnt(0)
	v_mfma_f32_16x16x32_bf16 v[60:63], v[128:131], v[184:187], v[60:63]
	v_mfma_f32_16x16x32_bf16 v[56:59], v[136:139], v[184:187], v[56:59]
	v_mfma_f32_16x16x32_bf16 v[44:47], v[128:131], v[210:213], v[44:47]
	v_mfma_f32_16x16x32_bf16 v[40:43], v[136:139], v[210:213], v[40:43]
	v_mfma_f32_16x16x32_bf16 v[28:31], v[128:131], v[218:221], v[28:31]
	v_mfma_f32_16x16x32_bf16 v[24:27], v[136:139], v[218:221], v[24:27]
	v_mfma_f32_16x16x32_bf16 v[12:15], v[128:131], v[226:229], v[12:15]
	v_mfma_f32_16x16x32_bf16 v[8:11], v[136:139], v[226:229], v[8:11]
	v_mfma_f32_16x16x32_bf16 v[60:63], v[132:135], v[188:191], v[60:63]
	v_mfma_f32_16x16x32_bf16 v[56:59], v[140:143], v[188:191], v[56:59]
	v_mfma_f32_16x16x32_bf16 v[44:47], v[132:135], v[214:217], v[44:47]
	v_mfma_f32_16x16x32_bf16 v[40:43], v[140:143], v[214:217], v[40:43]
	v_mfma_f32_16x16x32_bf16 v[28:31], v[132:135], v[222:225], v[28:31]
	v_mfma_f32_16x16x32_bf16 v[24:27], v[140:143], v[222:225], v[24:27]
	v_mfma_f32_16x16x32_bf16 v[12:15], v[132:135], v[230:233], v[12:15]
	v_mfma_f32_16x16x32_bf16 v[8:11], v[140:143], v[230:233], v[8:11]
	v_mfma_f32_16x16x32_bf16 v[52:55], v[162:165], v[184:187], v[52:55]
	v_mfma_f32_16x16x32_bf16 v[48:51], v[170:173], v[184:187], v[48:51]
	v_mfma_f32_16x16x32_bf16 v[36:39], v[162:165], v[210:213], v[36:39]
	v_mfma_f32_16x16x32_bf16 v[32:35], v[170:173], v[210:213], v[32:35]
	v_mfma_f32_16x16x32_bf16 v[20:23], v[162:165], v[218:221], v[20:23]
	v_mfma_f32_16x16x32_bf16 v[16:19], v[170:173], v[218:221], v[16:19]
	v_mfma_f32_16x16x32_bf16 v[4:7], v[162:165], v[226:229], v[4:7]
	v_mfma_f32_16x16x32_bf16 v[0:3], v[170:173], v[226:229], v[0:3]
	v_mfma_f32_16x16x32_bf16 v[52:55], v[166:169], v[188:191], v[52:55]
	v_mfma_f32_16x16x32_bf16 v[48:51], v[180:183], v[188:191], v[48:51]
	v_mfma_f32_16x16x32_bf16 v[36:39], v[166:169], v[214:217], v[36:39]
	v_mfma_f32_16x16x32_bf16 v[32:35], v[180:183], v[214:217], v[32:35]
	v_mfma_f32_16x16x32_bf16 v[20:23], v[166:169], v[222:225], v[20:23]
	v_mfma_f32_16x16x32_bf16 v[16:19], v[180:183], v[222:225], v[16:19]
	v_mfma_f32_16x16x32_bf16 v[4:7], v[166:169], v[230:233], v[4:7]
	v_mfma_f32_16x16x32_bf16 v[0:3], v[180:183], v[230:233], v[0:3]
	s_setprio 0
	s_barrier
	s_add_i32 s27, s27, 2
	s_add_u32 s42, s42, 0x100
	s_addc_u32 s43, s43, 0
	s_add_u32 s19, s19, 0x100
	s_addc_u32 s22, s22, 0
	s_cmp_gt_u32 s27, 29
	s_cbranch_scc0 .LBB0_394
	s_and_b64 vcc, exec, s[46:47]
	s_cbranch_vccz .LBB0_397
	s_barrier

; #define PG8_STAGE(bufoff, gbase, voff) do { _Pragma("unroll") for (int _i = 0; _i < 2; ++_i) \
;         __builtin_amdgcn_global_load_lds((const unsigned*)((const char*)(gbase) + (voff)[_i]), (LAS unsigned*)(lds + (bufoff) + ldsw + _i * 8192), 16, 0, 0); } while (0)
; #define PG8_LDA(dst, b, h) do { _Pragma("unroll") for (int m = 0; m < 4; ++m) _Pragma("unroll") for (int k = 0; k < 2; ++k) dst[m][k] = *(const LAS bf16x8*)(lds + PG8_SA(b, h) + aoff + m * 2048 + k * 1024); } while (0)
; #define PG8_MMA(ai, bj, At, Bt) do { __builtin_amdgcn_s_setprio(1); _Pragma("unroll") for (int m = 0; m < 4; ++m) _Pragma("unroll") for (int n = 0; n < 2; ++n) _Pragma("unroll") for (int k = 0; k < 2; ++k) \
;         acc[ai][bj][m][n] = __builtin_amdgcn_mfma_f32_16x16x32_bf16(Bt[n][k], At[m][k], acc[ai][bj][m][n], 0, 0, 0); __builtin_amdgcn_s_setprio(0); } while (0)
; #define PG8_WAIT_V(n) asm volatile("s_waitcnt vmcnt(" #n ")" ::: "memory")
; #define PG8_WAIT_L(n) asm volatile("s_waitcnt lgkmcnt(" #n ")" ::: "memory")
; #define PG8_BAR __builtin_amdgcn_s_barrier()
; #define PG8_SCHED __builtin_amdgcn_sched_barrier(0)
; template <class Epi>
; __device__ __forceinline__ void gemm_phase(LAS unsigned char* lds, const GemmD g, const Epi& E, int G, int c) {
;     ...
;             PG8_WAIT_V(8); PG8_WAIT_L(0); PG8_BAR; PG8_MMA(0, 0, At, B0); PG8_MMA(0, 1, At, B1); PG8_BAR; PG8_SCHED;
;             PG8_LDA(At, 0, 1); PG8_STAGE(PG8_SB(0, 0), b2, voffB); PG8_STAGE(PG8_SB(0, 1), b2 + hstepB, voffB); PG8_STAGE(PG8_SA(0, 0), a2, voffA);
;             PG8_WAIT_V(8); PG8_WAIT_L(0); PG8_BAR; PG8_MMA(1, 0, At, B0); PG8_MMA(1, 1, At, B1); PG8_BAR; PG8_SCHED;
.Lrw_Bf16_0_d:
	s_waitcnt lgkmcnt(0)
	s_barrier
	s_setprio 1
	s_waitcnt lgkmcnt(0)
	v_mfma_f32_16x16x32_bf16 v[124:127], v[128:131], v[180:183], v[124:127]
	v_mfma_f32_16x16x32_bf16 v[120:123], v[146:149], v[180:183], v[120:123]
	v_mfma_f32_16x16x32_bf16 v[112:115], v[128:131], v[188:191], v[112:115]
	v_mfma_f32_16x16x32_bf16 v[108:111], v[146:149], v[188:191], v[108:111]
	v_mfma_f32_16x16x32_bf16 v[100:103], v[128:131], v[210:213], v[100:103]
	v_mfma_f32_16x16x32_bf16 v[92:95], v[146:149], v[210:213], v[92:95]
	v_mfma_f32_16x16x32_bf16 v[84:87], v[128:131], v[218:221], v[84:87]
	v_mfma_f32_16x16x32_bf16 v[76:79], v[146:149], v[218:221], v[76:79]
	v_mfma_f32_16x16x32_bf16 v[124:127], v[132:135], v[184:187], v[124:127]
	v_mfma_f32_16x16x32_bf16 v[120:123], v[150:153], v[184:187], v[120:123]
	v_mfma_f32_16x16x32_bf16 v[112:115], v[132:135], v[192:195], v[112:115]
	v_mfma_f32_16x16x32_bf16 v[108:111], v[150:153], v[192:195], v[108:111]
	v_mfma_f32_16x16x32_bf16 v[100:103], v[132:135], v[214:217], v[100:103]
	v_mfma_f32_16x16x32_bf16 v[92:95], v[150:153], v[214:217], v[92:95]
	v_mfma_f32_16x16x32_bf16 v[84:87], v[132:135], v[222:225], v[84:87]
	v_mfma_f32_16x16x32_bf16 v[76:79], v[150:153], v[222:225], v[76:79]
	v_mfma_f32_16x16x32_bf16 v[116:119], v[154:157], v[180:183], v[116:119]
	v_mfma_f32_16x16x32_bf16 v[104:107], v[166:169], v[180:183], v[104:107]
	v_mfma_f32_16x16x32_bf16 v[96:99], v[154:157], v[188:191], v[96:99]
	v_mfma_f32_16x16x32_bf16 v[88:91], v[166:169], v[188:191], v[88:91]
	v_mfma_f32_16x16x32_bf16 v[80:83], v[154:157], v[210:213], v[80:83]
	v_mfma_f32_16x16x32_bf16 v[72:75], v[166:169], v[210:213], v[72:75]
	v_mfma_f32_16x16x32_bf16 v[68:71], v[154:157], v[218:221], v[68:71]
	v_mfma_f32_16x16x32_bf16 v[64:67], v[166:169], v[218:221], v[64:67]
	v_mfma_f32_16x16x32_bf16 v[116:119], v[162:165], v[184:187], v[116:119]
	v_mfma_f32_16x16x32_bf16 v[104:107], v[170:173], v[184:187], v[104:107]
	v_mfma_f32_16x16x32_bf16 v[96:99], v[162:165], v[192:195], v[96:99]
	v_mfma_f32_16x16x32_bf16 v[88:91], v[170:173], v[192:195], v[88:91]
	v_mfma_f32_16x16x32_bf16 v[80:83], v[162:165], v[214:217], v[80:83]
	v_mfma_f32_16x16x32_bf16 v[72:75], v[170:173], v[214:217], v[72:75]
	v_mfma_f32_16x16x32_bf16 v[68:71], v[162:165], v[222:225], v[68:71]
	v_mfma_f32_16x16x32_bf16 v[64:67], v[170:173], v[222:225], v[64:67]
	s_setprio 0
	s_barrier
	s_add_i32 s38, s38, s9
	v_lshl_add_u64 v[174:175], s[76:77], 0, v[178:179]
	s_mov_b32 m0, s38
	ds_read_b128 v[180:183], v161 offset:16384
	ds_read_b128 v[184:187], v161 offset:17408
	ds_read_b128 v[188:191], v161 offset:18432
	ds_read_b128 v[192:195], v161 offset:19456
	ds_read_b128 v[210:213], v161 offset:20480
	ds_read_b128 v[214:217], v161 offset:21504
	ds_read_b128 v[218:221], v161 offset:22528
	ds_read_b128 v[222:225], v161 offset:23552
	global_load_lds_dwordx4 v[174:175], off
	s_add_i32 m0, s38, 0x2000
	s_add_u32 s38, s76, 0x80000
	v_lshl_add_u64 v[198:199], s[76:77], 0, v[136:137]
	s_addc_u32 s39, s77, 0
	s_add_i32 s50, s50, s9
	global_load_lds_dwordx4 v[198:199], off
	v_lshl_add_u64 v[226:227], s[38:39], 0, v[178:179]
	s_mov_b32 m0, s50
	v_lshl_add_u64 v[228:229], s[4:5], 0, v[138:139]
	global_load_lds_dwordx4 v[226:227], off
	v_lshl_add_u64 v[226:227], s[38:39], 0, v[136:137]
	s_add_i32 m0, s50, 0x2000
	s_nop 0
	global_load_lds_dwordx4 v[226:227], off
	v_lshl_add_u64 v[226:227], s[4:5], 0, v[140:141]
	s_mov_b32 m0, s10
	s_nop 0
	global_load_lds_dwordx4 v[226:227], off
	s_mov_b32 m0, s11
	s_nop 0
	global_load_lds_dwordx4 v[228:229], off
	s_cmp_lg_u32 s99, 0
	s_cbranch_scc1 .Lrw_Bf16_1_r
	s_waitcnt vmcnt(8)
	s_branch .Lrw_Bf16_1_d

; #define PG8_STAGE(bufoff, gbase, voff) do { _Pragma("unroll") for (int _i = 0; _i < 2; ++_i) \
;         __builtin_amdgcn_global_load_lds((const unsigned*)((const char*)(gbase) + (voff)[_i]), (LAS unsigned*)(lds + (bufoff) + ldsw + _i * 8192), 16, 0, 0); } while (0)
; #define PG8_LDA(dst, b, h) do { _Pragma("unroll") for (int m = 0; m < 4; ++m) _Pragma("unroll") for (int k = 0; k < 2; ++k) dst[m][k] = *(const LAS bf16x8*)(lds + PG8_SA(b, h) + aoff + m * 2048 + k * 1024); } while (0)
; #define PG8_LDB(dst, b, h) do { _Pragma("unroll") for (int n = 0; n < 2; ++n) _Pragma("unroll") for (int k = 0; k < 2; ++k) dst[n][k] = *(const LAS bf16x8*)(lds + PG8_SB(b, h) + boff + n * 2048 + k * 1024); } while (0)
; #define PG8_MMA(ai, bj, At, Bt) do { __builtin_amdgcn_s_setprio(1); _Pragma("unroll") for (int m = 0; m < 4; ++m) _Pragma("unroll") for (int n = 0; n < 2; ++n) _Pragma("unroll") for (int k = 0; k < 2; ++k) \
;         acc[ai][bj][m][n] = __builtin_amdgcn_mfma_f32_16x16x32_bf16(Bt[n][k], At[m][k], acc[ai][bj][m][n], 0, 0, 0); __builtin_amdgcn_s_setprio(0); } while (0)
; #define PG8_WAIT_V(n) asm volatile("s_waitcnt vmcnt(" #n ")" ::: "memory")
; #define PG8_WAIT_L(n) asm volatile("s_waitcnt lgkmcnt(" #n ")" ::: "memory")
; #define PG8_BAR __builtin_amdgcn_s_barrier()
; #define PG8_SCHED __builtin_amdgcn_sched_barrier(0)
; template <class Epi>
; __device__ __forceinline__ void gemm_phase(LAS unsigned char* lds, const GemmD g, const Epi& E, int G, int c) {
;     ...
;             PG8_WAIT_V(8); PG8_WAIT_L(0); PG8_BAR; PG8_MMA(1, 0, At, B0); PG8_MMA(1, 1, At, B1); PG8_BAR; PG8_SCHED;
;             PG8_LDB(B0, 1, 0); PG8_LDB(B1, 1, 1); PG8_SCHED; PG8_LDA(At, 1, 0); PG8_STAGE(PG8_SA(0, 1), a2 + hstepA, voffA);
;             PG8_WAIT_V(8); PG8_WAIT_L(0); PG8_BAR; PG8_MMA(0, 0, At, B0); PG8_MMA(0, 1, At, B1); PG8_BAR; PG8_SCHED;
.Lrw_Bf16_1_d:
	s_waitcnt lgkmcnt(0)
	s_barrier
	s_setprio 1
	s_waitcnt lgkmcnt(0)
	v_mfma_f32_16x16x32_bf16 v[60:63], v[128:131], v[180:183], v[60:63]
	v_mfma_f32_16x16x32_bf16 v[56:59], v[146:149], v[180:183], v[56:59]
	v_mfma_f32_16x16x32_bf16 v[52:55], v[128:131], v[188:191], v[52:55]
	v_mfma_f32_16x16x32_bf16 v[44:47], v[146:149], v[188:191], v[44:47]
	v_mfma_f32_16x16x32_bf16 v[36:39], v[128:131], v[210:213], v[36:39]
	v_mfma_f32_16x16x32_bf16 v[28:31], v[146:149], v[210:213], v[28:31]
	v_mfma_f32_16x16x32_bf16 v[20:23], v[128:131], v[218:221], v[20:23]
	v_mfma_f32_16x16x32_bf16 v[12:15], v[146:149], v[218:221], v[12:15]
	v_mfma_f32_16x16x32_bf16 v[60:63], v[132:135], v[184:187], v[60:63]
	v_mfma_f32_16x16x32_bf16 v[56:59], v[150:153], v[184:187], v[56:59]
	v_mfma_f32_16x16x32_bf16 v[52:55], v[132:135], v[192:195], v[52:55]
	v_mfma_f32_16x16x32_bf16 v[44:47], v[150:153], v[192:195], v[44:47]
	v_mfma_f32_16x16x32_bf16 v[36:39], v[132:135], v[214:217], v[36:39]
	v_mfma_f32_16x16x32_bf16 v[28:31], v[150:153], v[214:217], v[28:31]
	v_mfma_f32_16x16x32_bf16 v[20:23], v[132:135], v[222:225], v[20:23]
	v_mfma_f32_16x16x32_bf16 v[12:15], v[150:153], v[222:225], v[12:15]
	v_mfma_f32_16x16x32_bf16 v[48:51], v[154:157], v[180:183], v[48:51]
	v_mfma_f32_16x16x32_bf16 v[40:43], v[166:169], v[180:183], v[40:43]
	v_mfma_f32_16x16x32_bf16 v[32:35], v[154:157], v[188:191], v[32:35]
	v_mfma_f32_16x16x32_bf16 v[24:27], v[166:169], v[188:191], v[24:27]
	v_mfma_f32_16x16x32_bf16 v[16:19], v[154:157], v[210:213], v[16:19]
	v_mfma_f32_16x16x32_bf16 v[8:11], v[166:169], v[210:213], v[8:11]
	v_mfma_f32_16x16x32_bf16 v[4:7], v[154:157], v[218:221], v[4:7]
	v_mfma_f32_16x16x32_bf16 v[0:3], v[166:169], v[218:221], v[0:3]
	v_mfma_f32_16x16x32_bf16 v[48:51], v[162:165], v[184:187], v[48:51]
	v_mfma_f32_16x16x32_bf16 v[40:43], v[170:173], v[184:187], v[40:43]
	v_mfma_f32_16x16x32_bf16 v[32:35], v[162:165], v[192:195], v[32:35]
	v_mfma_f32_16x16x32_bf16 v[24:27], v[170:173], v[192:195], v[24:27]
	v_mfma_f32_16x16x32_bf16 v[16:19], v[162:165], v[214:217], v[16:19]
	v_mfma_f32_16x16x32_bf16 v[8:11], v[170:173], v[214:217], v[8:11]
	v_mfma_f32_16x16x32_bf16 v[4:7], v[162:165], v[222:225], v[4:7]
	v_mfma_f32_16x16x32_bf16 v[0:3], v[170:173], v[222:225], v[0:3]
	s_setprio 0
	s_barrier
	s_add_i32 s38, 0, 0x18000
	s_add_i32 s39, 0, 0x1c000
	v_add_u32_e32 v150, s38, v159
	v_add_u32_e32 v170, s39, v159
	ds_read_b128 v[128:131], v150
	ds_read_b128 v[132:135], v150 offset:1024
	ds_read_b128 v[146:149], v150 offset:2048
	ds_read_b128 v[150:153], v150 offset:3072
	ds_read_b128 v[154:157], v170
	ds_read_b128 v[162:165], v170 offset:1024
	ds_read_b128 v[166:169], v170 offset:2048
	ds_read_b128 v[170:173], v170 offset:3072
	s_add_u32 s4, s4, 0x80000
	s_addc_u32 s5, s5, 0
	s_mov_b32 m0, s16
	v_lshl_add_u64 v[230:231], s[4:5], 0, v[140:141]
	ds_read_b128 v[180:183], v161 offset:32768
	ds_read_b128 v[184:187], v161 offset:33792
	ds_read_b128 v[188:191], v161 offset:34816
	ds_read_b128 v[192:195], v161 offset:35840
	ds_read_b128 v[210:213], v161 offset:36864
	ds_read_b128 v[214:217], v161 offset:37888
	ds_read_b128 v[218:221], v161 offset:38912
	ds_read_b128 v[222:225], v161 offset:39936
	global_load_lds_dwordx4 v[230:231], off
	v_lshl_add_u64 v[230:231], s[4:5], 0, v[138:139]
	s_mov_b32 m0, s17
	s_nop 0
	global_load_lds_dwordx4 v[230:231], off
	s_waitcnt vmcnt(8)
	s_waitcnt lgkmcnt(0)
	s_barrier
	s_setprio 1
	s_waitcnt lgkmcnt(0)
	v_mfma_f32_16x16x32_bf16 v[124:127], v[128:131], v[180:183], v[124:127]
	v_mfma_f32_16x16x32_bf16 v[120:123], v[146:149], v[180:183], v[120:123]
	v_mfma_f32_16x16x32_bf16 v[112:115], v[128:131], v[188:191], v[112:115]
	v_mfma_f32_16x16x32_bf16 v[108:111], v[146:149], v[188:191], v[108:111]
	v_mfma_f32_16x16x32_bf16 v[100:103], v[128:131], v[210:213], v[100:103]
	v_mfma_f32_16x16x32_bf16 v[92:95], v[146:149], v[210:213], v[92:95]
	v_mfma_f32_16x16x32_bf16 v[84:87], v[128:131], v[218:221], v[84:87]
	v_mfma_f32_16x16x32_bf16 v[76:79], v[146:149], v[218:221], v[76:79]
	v_mfma_f32_16x16x32_bf16 v[124:127], v[132:135], v[184:187], v[124:127]
	v_mfma_f32_16x16x32_bf16 v[120:123], v[150:153], v[184:187], v[120:123]
	v_mfma_f32_16x16x32_bf16 v[112:115], v[132:135], v[192:195], v[112:115]
	v_mfma_f32_16x16x32_bf16 v[108:111], v[150:153], v[192:195], v[108:111]
	v_mfma_f32_16x16x32_bf16 v[100:103], v[132:135], v[214:217], v[100:103]
	v_mfma_f32_16x16x32_bf16 v[92:95], v[150:153], v[214:217], v[92:95]
	v_mfma_f32_16x16x32_bf16 v[84:87], v[132:135], v[222:225], v[84:87]
	v_mfma_f32_16x16x32_bf16 v[76:79], v[150:153], v[222:225], v[76:79]
	v_mfma_f32_16x16x32_bf16 v[116:119], v[154:157], v[180:183], v[116:119]
	v_mfma_f32_16x16x32_bf16 v[104:107], v[166:169], v[180:183], v[104:107]
	v_mfma_f32_16x16x32_bf16 v[96:99], v[154:157], v[188:191], v[96:99]
	v_mfma_f32_16x16x32_bf16 v[88:91], v[166:169], v[188:191], v[88:91]
	v_mfma_f32_16x16x32_bf16 v[80:83], v[154:157], v[210:213], v[80:83]
	v_mfma_f32_16x16x32_bf16 v[72:75], v[166:169], v[210:213], v[72:75]
	v_mfma_f32_16x16x32_bf16 v[68:71], v[154:157], v[218:221], v[68:71]
	v_mfma_f32_16x16x32_bf16 v[64:67], v[166:169], v[218:221], v[64:67]
	v_mfma_f32_16x16x32_bf16 v[116:119], v[162:165], v[184:187], v[116:119]
	v_mfma_f32_16x16x32_bf16 v[104:107], v[170:173], v[184:187], v[104:107]
	v_mfma_f32_16x16x32_bf16 v[96:99], v[162:165], v[192:195], v[96:99]
	v_mfma_f32_16x16x32_bf16 v[88:91], v[170:173], v[192:195], v[88:91]
	v_mfma_f32_16x16x32_bf16 v[80:83], v[162:165], v[214:217], v[80:83]
	v_mfma_f32_16x16x32_bf16 v[72:75], v[170:173], v[214:217], v[72:75]
	v_mfma_f32_16x16x32_bf16 v[68:71], v[162:165], v[222:225], v[68:71]
	v_mfma_f32_16x16x32_bf16 v[64:67], v[170:173], v[222:225], v[64:67]
	s_setprio 0
	s_barrier
; #define PG8_STAGE(bufoff, gbase, voff) do { _Pragma("unroll") for (int _i = 0; _i < 2; ++_i) \
;         __builtin_amdgcn_global_load_lds((const unsigned*)((const char*)(gbase) + (voff)[_i]), (LAS unsigned*)(lds + (bufoff) + ldsw + _i * 8192), 16, 0, 0); } while (0)
; #define PG8_LDA(dst, b, h) do { _Pragma("unroll") for (int m = 0; m < 4; ++m) _Pragma("unroll") for (int k = 0; k < 2; ++k) dst[m][k] = *(const LAS bf16x8*)(lds + PG8_SA(b, h) + aoff + m * 2048 + k * 1024); } while (0)
; #define PG8_MMA(ai, bj, At, Bt) do { __builtin_amdgcn_s_setprio(1); _Pragma("unroll") for (int m = 0; m < 4; ++m) _Pragma("unroll") for (int n = 0; n < 2; ++n) _Pragma("unroll") for (int k = 0; k < 2; ++k) \
;         acc[ai][bj][m][n] = __builtin_amdgcn_mfma_f32_16x16x32_bf16(Bt[n][k], At[m][k], acc[ai][bj][m][n], 0, 0, 0); __builtin_amdgcn_s_setprio(0); } while (0)
; #define PG8_WAIT_V(n) asm volatile("s_waitcnt vmcnt(" #n ")" ::: "memory")
; #define PG8_WAIT_L(n) asm volatile("s_waitcnt lgkmcnt(" #n ")" ::: "memory")
; #define PG8_BAR __builtin_amdgcn_s_barrier()
; #define PG8_SCHED __builtin_amdgcn_sched_barrier(0)
; template <class Epi>
; __device__ __forceinline__ void gemm_phase(LAS unsigned char* lds, const GemmD g, const Epi& E, int G, int c) {
;     ...
;             PG8_LDA(At, 1, 1); PG8_STAGE(PG8_SB(1, 0), b3, voffB); PG8_STAGE(PG8_SB(1, 1), b3 + hstepB, voffB); PG8_STAGE(PG8_SA(1, 0), a3, voffA);
;             PG8_WAIT_V(8); PG8_WAIT_L(0); PG8_BAR; PG8_MMA(1, 0, At, B0); PG8_MMA(1, 1, At, B1); PG8_BAR; PG8_SCHED;
;         }
;         if (wr == 0) PG8_BAR;
	s_add_i32 s4, s38, s9
	v_lshl_add_u64 v[174:175], v[174:175], 0, s[48:49]
	s_mov_b32 m0, s4
	ds_read_b128 v[180:183], v161 offset:49152
	ds_read_b128 v[184:187], v161 offset:50176
	ds_read_b128 v[188:191], v161 offset:51200
	ds_read_b128 v[192:195], v161 offset:52224
	ds_read_b128 v[210:213], v161 offset:53248
	ds_read_b128 v[214:217], v161 offset:54272
	ds_read_b128 v[218:221], v161 offset:55296
	ds_read_b128 v[222:225], v161 offset:56320
	global_load_lds_dwordx4 v[174:175], off
	s_add_i32 m0, s4, 0x2000
	s_add_u32 s4, s76, 0x80080
	v_lshl_add_u64 v[174:175], v[198:199], 0, s[48:49]
	s_addc_u32 s5, s77, 0
	s_add_i32 s38, s39, s9
	global_load_lds_dwordx4 v[174:175], off
	v_lshl_add_u64 v[174:175], s[4:5], 0, v[178:179]
	s_mov_b32 m0, s38
	s_nop 0
	global_load_lds_dwordx4 v[174:175], off
	v_lshl_add_u64 v[174:175], s[4:5], 0, v[136:137]
	s_add_i32 m0, s38, 0x2000
	s_nop 0
	global_load_lds_dwordx4 v[174:175], off
	v_lshl_add_u64 v[174:175], v[226:227], 0, s[48:49]
	s_mov_b32 m0, s19
	s_nop 0
	global_load_lds_dwordx4 v[174:175], off
	v_lshl_add_u64 v[174:175], v[228:229], 0, s[48:49]
	s_mov_b32 m0, s22
	s_nop 0
	global_load_lds_dwordx4 v[174:175], off
	s_waitcnt vmcnt(8)
	s_waitcnt lgkmcnt(0)
	s_barrier
	s_setprio 1
	s_waitcnt lgkmcnt(0)
	v_mfma_f32_16x16x32_bf16 v[60:63], v[128:131], v[180:183], v[60:63]
	v_mfma_f32_16x16x32_bf16 v[56:59], v[146:149], v[180:183], v[56:59]
	v_mfma_f32_16x16x32_bf16 v[52:55], v[128:131], v[188:191], v[52:55]
	v_mfma_f32_16x16x32_bf16 v[44:47], v[146:149], v[188:191], v[44:47]
	v_mfma_f32_16x16x32_bf16 v[36:39], v[128:131], v[210:213], v[36:39]
	v_mfma_f32_16x16x32_bf16 v[28:31], v[146:149], v[210:213], v[28:31]
	v_mfma_f32_16x16x32_bf16 v[20:23], v[128:131], v[218:221], v[20:23]
	v_mfma_f32_16x16x32_bf16 v[12:15], v[146:149], v[218:221], v[12:15]
	v_mfma_f32_16x16x32_bf16 v[60:63], v[132:135], v[184:187], v[60:63]
	v_mfma_f32_16x16x32_bf16 v[56:59], v[150:153], v[184:187], v[56:59]
	v_mfma_f32_16x16x32_bf16 v[52:55], v[132:135], v[192:195], v[52:55]
	v_mfma_f32_16x16x32_bf16 v[44:47], v[150:153], v[192:195], v[44:47]
	v_mfma_f32_16x16x32_bf16 v[36:39], v[132:135], v[214:217], v[36:39]
	v_mfma_f32_16x16x32_bf16 v[28:31], v[150:153], v[214:217], v[28:31]
	v_mfma_f32_16x16x32_bf16 v[20:23], v[132:135], v[222:225], v[20:23]
	v_mfma_f32_16x16x32_bf16 v[12:15], v[150:153], v[222:225], v[12:15]
	v_mfma_f32_16x16x32_bf16 v[48:51], v[154:157], v[180:183], v[48:51]
	v_mfma_f32_16x16x32_bf16 v[40:43], v[166:169], v[180:183], v[40:43]
	v_mfma_f32_16x16x32_bf16 v[32:35], v[154:157], v[188:191], v[32:35]
	v_mfma_f32_16x16x32_bf16 v[24:27], v[166:169], v[188:191], v[24:27]
	v_mfma_f32_16x16x32_bf16 v[16:19], v[154:157], v[210:213], v[16:19]
	v_mfma_f32_16x16x32_bf16 v[8:11], v[166:169], v[210:213], v[8:11]
	v_mfma_f32_16x16x32_bf16 v[4:7], v[154:157], v[218:221], v[4:7]
	v_mfma_f32_16x16x32_bf16 v[0:3], v[166:169], v[218:221], v[0:3]
	v_mfma_f32_16x16x32_bf16 v[48:51], v[162:165], v[184:187], v[48:51]
	v_mfma_f32_16x16x32_bf16 v[40:43], v[170:173], v[184:187], v[40:43]
	v_mfma_f32_16x16x32_bf16 v[32:35], v[162:165], v[192:195], v[32:35]
	v_mfma_f32_16x16x32_bf16 v[24:27], v[170:173], v[192:195], v[24:27]
	v_mfma_f32_16x16x32_bf16 v[16:19], v[162:165], v[214:217], v[16:19]
	v_mfma_f32_16x16x32_bf16 v[8:11], v[170:173], v[214:217], v[8:11]
	v_mfma_f32_16x16x32_bf16 v[4:7], v[162:165], v[222:225], v[4:7]
	v_mfma_f32_16x16x32_bf16 v[0:3], v[170:173], v[222:225], v[0:3]
	s_setprio 0
	s_barrier
	s_add_i32 s36, s36, 2
	s_add_u32 s42, s42, 0x100
	s_addc_u32 s43, s43, 0
	s_add_u32 s33, s33, 0x100
	s_addc_u32 s35, s35, 0
	s_cmp_gt_u32 s36, 29
	s_cbranch_scc0 .LBB0_486
	s_and_b64 vcc, exec, s[46:47]
	s_cbranch_vccz .LBB0_489
	s_barrier
